# mixer phase: sg u-loads hoisted/pipelined + conv pass loads software-pipelined (plus sg part1 batching, reversed N=1024 order, trimmed K-loop DMA)
# speedup vs baseline: 1.0080x; 1.0029x over previous
; __device__ __forceinline__ void sg_item(int l, int chunk, LAS unsigned char* lds, const bf16_t* UB, const bf16_t* V2T, bf16_t* YC1, const bf16_t* Wb,
;                                         const float* sg_ln_g, const float* sg_ln_b, const float* sg_b, int lane, int wave) {
;     ...
;         const int th = wave & 1, cq = wave >> 1, s = 64 * th + lane;
;         const bf16_t* src = V2T + ((size_t)b * BW + 64 * cq) * SEQ + pos0;
;         float v[64]; float sum = 0.f, sq = 0.f;
; #pragma unroll
;         for (int cb = 0; cb < 64; cb += 8) {
;             unsigned raw[8]; const void* pp[8];
; #pragma unroll
;             for (int j = 0; j < 8; ++j) pp[j] = src + (size_t)(cb + j) * SEQ;
;             ld_u16_s8(raw, (unsigned)s * 2u, pp);
; #pragma unroll
;             for (int j = 0; j < 8; ++j) v[cb + j] = __uint_as_float(raw[j] << 16);
;         }
.LBB0_79:
	s_and_b32 s12, s88, 0xf80
	s_and_b32 s1, s85, 0x7ffff
	s_and_b32 s0, s84, 0xffffff00
	s_add_u32 s0, s0, s15
	s_addc_u32 s1, s1, s46
	s_lshl_b64 s[0:1], s[0:1], 13
	s_add_u32 s0, s2, s0
	s_addc_u32 s1, s3, s1
	s_lshl_b32 s12, s12, 1
	s_add_u32 s0, s0, s12
	s_addc_u32 s1, s1, 0
	s_mov_b64 s[48:49], s[0:1]
	s_nop 4
	global_load_ushort v132, v149, s[48:49]
	s_add_u32 s48, s48, 0x2000
	s_addc_u32 s49, s49, 0
	global_load_ushort v133, v149, s[48:49]
	s_add_u32 s48, s48, 0x2000
	s_addc_u32 s49, s49, 0
	global_load_ushort v130, v149, s[48:49]
	s_add_u32 s48, s48, 0x2000
	s_addc_u32 s49, s49, 0
	global_load_ushort v128, v149, s[48:49]
	s_add_u32 s48, s48, 0x2000
	s_addc_u32 s49, s49, 0
	global_load_ushort v126, v149, s[48:49]
	s_add_u32 s48, s48, 0x2000
	s_addc_u32 s49, s49, 0
	global_load_ushort v124, v149, s[48:49]
	s_add_u32 s48, s48, 0x2000
	s_addc_u32 s49, s49, 0
	global_load_ushort v120, v149, s[48:49]
	s_add_u32 s48, s48, 0x2000
	s_addc_u32 s49, s49, 0
	global_load_ushort v116, v149, s[48:49]
	s_add_u32 s48, s48, 0x2000
	s_addc_u32 s49, s49, 0
	global_load_ushort v122, v149, s[48:49]
	s_add_u32 s48, s48, 0x2000
	s_addc_u32 s49, s49, 0
	global_load_ushort v118, v149, s[48:49]
	s_add_u32 s48, s48, 0x2000
	s_addc_u32 s49, s49, 0
	global_load_ushort v114, v149, s[48:49]
	s_add_u32 s48, s48, 0x2000
	s_addc_u32 s49, s49, 0
	global_load_ushort v112, v149, s[48:49]
	s_add_u32 s48, s48, 0x2000
	s_addc_u32 s49, s49, 0
	global_load_ushort v110, v149, s[48:49]
	s_add_u32 s48, s48, 0x2000
	s_addc_u32 s49, s49, 0
	global_load_ushort v108, v149, s[48:49]
	s_add_u32 s48, s48, 0x2000
	s_addc_u32 s49, s49, 0
	global_load_ushort v104, v149, s[48:49]
	s_add_u32 s48, s48, 0x2000
	s_addc_u32 s49, s49, 0
	global_load_ushort v100, v149, s[48:49]
	s_add_u32 s48, s48, 0x2000
	s_addc_u32 s49, s49, 0
	global_load_ushort v106, v149, s[48:49]
	s_add_u32 s48, s48, 0x2000
	s_addc_u32 s49, s49, 0
	global_load_ushort v102, v149, s[48:49]
	s_add_u32 s48, s48, 0x2000
	s_addc_u32 s49, s49, 0
	global_load_ushort v98, v149, s[48:49]
	s_add_u32 s48, s48, 0x2000
	s_addc_u32 s49, s49, 0
	global_load_ushort v96, v149, s[48:49]
	s_add_u32 s48, s48, 0x2000
	s_addc_u32 s49, s49, 0
	global_load_ushort v94, v149, s[48:49]
	s_add_u32 s48, s48, 0x2000
	s_addc_u32 s49, s49, 0
	global_load_ushort v92, v149, s[48:49]
	s_add_u32 s48, s48, 0x2000
	s_addc_u32 s49, s49, 0
	global_load_ushort v88, v149, s[48:49]
	s_add_u32 s48, s48, 0x2000
	s_addc_u32 s49, s49, 0
	global_load_ushort v84, v149, s[48:49]
	s_add_u32 s48, s48, 0x2000
	s_addc_u32 s49, s49, 0
	global_load_ushort v90, v149, s[48:49]
	s_add_u32 s48, s48, 0x2000
	s_addc_u32 s49, s49, 0
	global_load_ushort v86, v149, s[48:49]
	s_add_u32 s48, s48, 0x2000
	s_addc_u32 s49, s49, 0
	global_load_ushort v82, v149, s[48:49]
	s_add_u32 s48, s48, 0x2000
	s_addc_u32 s49, s49, 0
	global_load_ushort v80, v149, s[48:49]
	s_add_u32 s48, s48, 0x2000
	s_addc_u32 s49, s49, 0
	global_load_ushort v78, v149, s[48:49]
	s_add_u32 s48, s48, 0x2000
	s_addc_u32 s49, s49, 0
	global_load_ushort v76, v149, s[48:49]
	s_add_u32 s48, s48, 0x2000
	s_addc_u32 s49, s49, 0
	global_load_ushort v72, v149, s[48:49]
	s_add_u32 s48, s48, 0x2000
	s_addc_u32 s49, s49, 0
	global_load_ushort v60, v149, s[48:49]
	s_add_u32 s48, s48, 0x2000
	s_addc_u32 s49, s49, 0
	global_load_ushort v74, v149, s[48:49]
	s_add_u32 s48, s48, 0x2000
	s_addc_u32 s49, s49, 0
	global_load_ushort v62, v149, s[48:49]
	s_add_u32 s48, s48, 0x2000
	s_addc_u32 s49, s49, 0
	global_load_ushort v58, v149, s[48:49]
	s_add_u32 s48, s48, 0x2000
	s_addc_u32 s49, s49, 0
	global_load_ushort v56, v149, s[48:49]
	s_add_u32 s48, s48, 0x2000
	s_addc_u32 s49, s49, 0
	global_load_ushort v54, v149, s[48:49]
	s_add_u32 s48, s48, 0x2000
	s_addc_u32 s49, s49, 0
	global_load_ushort v52, v149, s[48:49]
	s_add_u32 s48, s48, 0x2000
	s_addc_u32 s49, s49, 0
	global_load_ushort v48, v149, s[48:49]
	s_add_u32 s48, s48, 0x2000
	s_addc_u32 s49, s49, 0
	global_load_ushort v44, v149, s[48:49]
	s_add_u32 s48, s48, 0x2000
	s_addc_u32 s49, s49, 0
	global_load_ushort v50, v149, s[48:49]
	s_add_u32 s48, s48, 0x2000
	s_addc_u32 s49, s49, 0
	global_load_ushort v46, v149, s[48:49]
	s_add_u32 s48, s48, 0x2000
	s_addc_u32 s49, s49, 0
	global_load_ushort v42, v149, s[48:49]
	s_add_u32 s48, s48, 0x2000
	s_addc_u32 s49, s49, 0
	global_load_ushort v40, v149, s[48:49]
	s_add_u32 s48, s48, 0x2000
	s_addc_u32 s49, s49, 0
	global_load_ushort v38, v149, s[48:49]
	s_add_u32 s48, s48, 0x2000
	s_addc_u32 s49, s49, 0
	global_load_ushort v36, v149, s[48:49]
	s_add_u32 s48, s48, 0x2000
	s_addc_u32 s49, s49, 0
	global_load_ushort v32, v149, s[48:49]
	s_add_u32 s48, s48, 0x2000
	s_addc_u32 s49, s49, 0
	global_load_ushort v28, v149, s[48:49]
	s_add_u32 s48, s48, 0x2000
	s_addc_u32 s49, s49, 0
	global_load_ushort v34, v149, s[48:49]
	s_add_u32 s48, s48, 0x2000
	s_addc_u32 s49, s49, 0
	global_load_ushort v30, v149, s[48:49]
	s_add_u32 s48, s48, 0x2000
	s_addc_u32 s49, s49, 0
	global_load_ushort v26, v149, s[48:49]
	s_add_u32 s48, s48, 0x2000
	s_addc_u32 s49, s49, 0
	global_load_ushort v24, v149, s[48:49]
	s_add_u32 s48, s48, 0x2000
	s_addc_u32 s49, s49, 0
	global_load_ushort v22, v149, s[48:49]
	s_add_u32 s48, s48, 0x2000
	s_addc_u32 s49, s49, 0
	global_load_ushort v20, v149, s[48:49]
	s_add_u32 s48, s48, 0x2000
	s_addc_u32 s49, s49, 0
	global_load_ushort v16, v149, s[48:49]
	s_add_u32 s48, s48, 0x2000
	s_addc_u32 s49, s49, 0
	global_load_ushort v12, v149, s[48:49]
	s_add_u32 s48, s48, 0x2000
	s_addc_u32 s49, s49, 0
	global_load_ushort v18, v149, s[48:49]
	s_add_u32 s48, s48, 0x2000
	s_addc_u32 s49, s49, 0
	global_load_ushort v14, v149, s[48:49]
	s_add_u32 s48, s48, 0x2000
	s_addc_u32 s49, s49, 0
	global_load_ushort v10, v149, s[48:49]
	s_add_u32 s48, s48, 0x2000
	s_addc_u32 s49, s49, 0
	global_load_ushort v8, v149, s[48:49]
	s_add_u32 s48, s48, 0x2000
	s_addc_u32 s49, s49, 0
	global_load_ushort v6, v149, s[48:49]
	s_add_u32 s48, s48, 0x2000
	s_addc_u32 s49, s49, 0
	global_load_ushort v4, v149, s[48:49]
	s_add_u32 s48, s48, 0x2000
	s_addc_u32 s49, s49, 0
	global_load_ushort v2, v149, s[48:49]
	s_add_u32 s48, s48, 0x2000
	s_addc_u32 s49, s49, 0
	global_load_ushort v0, v149, s[48:49]
	s_waitcnt vmcnt(0)
; __device__ __forceinline__ void sg_item(int l, int chunk, LAS unsigned char* lds, const bf16_t* UB, const bf16_t* V2T, bf16_t* YC1, const bf16_t* Wb,
;                                         const float* sg_ln_g, const float* sg_ln_b, const float* sg_b, int lane, int wave) {
;     ...
;             for (int j = 0; j < 8; ++j) v[cb + j] = __uint_as_float(raw[j] << 16);
;         }
; #pragma unroll
;         for (int c = 0; c < 64; ++c) { sum += v[c]; sq += v[c] * v[c]; }
	v_lshlrev_b32_e32 v132, 16, v132
	v_lshlrev_b32_e32 v133, 16, v133
	v_lshlrev_b32_e32 v130, 16, v130
	v_lshlrev_b32_e32 v128, 16, v128
	v_lshlrev_b32_e32 v126, 16, v126
	v_lshlrev_b32_e32 v124, 16, v124
	v_lshlrev_b32_e32 v120, 16, v120
	v_lshlrev_b32_e32 v116, 16, v116
	v_lshlrev_b32_e32 v122, 16, v122
	v_lshlrev_b32_e32 v118, 16, v118
	v_lshlrev_b32_e32 v114, 16, v114
	v_lshlrev_b32_e32 v112, 16, v112
	v_lshlrev_b32_e32 v110, 16, v110
	v_lshlrev_b32_e32 v108, 16, v108
	v_lshlrev_b32_e32 v104, 16, v104
	v_lshlrev_b32_e32 v100, 16, v100
	v_lshlrev_b32_e32 v106, 16, v106
	v_lshlrev_b32_e32 v102, 16, v102
	v_lshlrev_b32_e32 v98, 16, v98
	v_lshlrev_b32_e32 v96, 16, v96
	v_lshlrev_b32_e32 v94, 16, v94
	v_lshlrev_b32_e32 v92, 16, v92
	v_lshlrev_b32_e32 v88, 16, v88
	v_lshlrev_b32_e32 v84, 16, v84
	v_lshlrev_b32_e32 v90, 16, v90
	v_lshlrev_b32_e32 v86, 16, v86
	v_lshlrev_b32_e32 v82, 16, v82
	v_lshlrev_b32_e32 v80, 16, v80
	v_lshlrev_b32_e32 v78, 16, v78
	v_lshlrev_b32_e32 v76, 16, v76
	v_lshlrev_b32_e32 v72, 16, v72
	v_lshlrev_b32_e32 v60, 16, v60
	v_lshlrev_b32_e32 v74, 16, v74
	v_lshlrev_b32_e32 v62, 16, v62
	v_lshlrev_b32_e32 v58, 16, v58
	v_lshlrev_b32_e32 v56, 16, v56
	v_lshlrev_b32_e32 v54, 16, v54
	v_lshlrev_b32_e32 v52, 16, v52
	v_lshlrev_b32_e32 v48, 16, v48
	v_lshlrev_b32_e32 v44, 16, v44
	v_lshlrev_b32_e32 v50, 16, v50
	v_lshlrev_b32_e32 v46, 16, v46
	v_lshlrev_b32_e32 v42, 16, v42
	v_lshlrev_b32_e32 v40, 16, v40
	v_lshlrev_b32_e32 v38, 16, v38
	v_lshlrev_b32_e32 v36, 16, v36
	v_lshlrev_b32_e32 v32, 16, v32
	v_lshlrev_b32_e32 v28, 16, v28
	v_lshlrev_b32_e32 v34, 16, v34
	v_lshlrev_b32_e32 v30, 16, v30
	v_lshlrev_b32_e32 v26, 16, v26
	v_lshlrev_b32_e32 v24, 16, v24
	v_lshlrev_b32_e32 v22, 16, v22
	v_lshlrev_b32_e32 v20, 16, v20
	v_lshlrev_b32_e32 v16, 16, v16
	v_lshlrev_b32_e32 v12, 16, v12
	v_lshlrev_b32_e32 v18, 16, v18
	v_lshlrev_b32_e32 v14, 16, v14
	v_lshlrev_b32_e32 v10, 16, v10
	v_lshlrev_b32_e32 v8, 16, v8
	v_lshlrev_b32_e32 v6, 16, v6
	v_lshlrev_b32_e32 v4, 16, v4
	v_lshlrev_b32_e32 v2, 16, v2
	v_lshlrev_b32_e32 v0, 16, v0
	v_mul_f32_e32 v221, v132, v132
	v_fmac_f32_e32 v221, v133, v133
	v_add_f32_e32 v220, v132, v133
	v_mul_f32_e32 v131, v130, v130
	v_pk_add_f32 v[220:221], v[220:221], v[130:131]
	v_mul_f32_e32 v129, v128, v128
	v_pk_add_f32 v[220:221], v[220:221], v[128:129]
	v_mul_f32_e32 v127, v126, v126
	v_pk_add_f32 v[220:221], v[220:221], v[126:127]
	v_mul_f32_e32 v125, v124, v124
	v_pk_add_f32 v[220:221], v[220:221], v[124:125]
	v_mul_f32_e32 v121, v120, v120
	v_pk_add_f32 v[220:221], v[220:221], v[120:121]
	v_mul_f32_e32 v117, v116, v116
	v_pk_add_f32 v[220:221], v[220:221], v[116:117]
	v_mul_f32_e32 v123, v122, v122
	v_pk_add_f32 v[220:221], v[220:221], v[122:123]
	v_mul_f32_e32 v119, v118, v118
	v_pk_add_f32 v[220:221], v[220:221], v[118:119]
	v_mul_f32_e32 v115, v114, v114
	v_pk_add_f32 v[220:221], v[220:221], v[114:115]
	v_mul_f32_e32 v113, v112, v112
	v_pk_add_f32 v[220:221], v[220:221], v[112:113]
	v_mul_f32_e32 v111, v110, v110
	v_pk_add_f32 v[220:221], v[220:221], v[110:111]
	v_mul_f32_e32 v109, v108, v108
	v_pk_add_f32 v[220:221], v[220:221], v[108:109]
	v_mul_f32_e32 v105, v104, v104
	v_pk_add_f32 v[220:221], v[220:221], v[104:105]
	v_mul_f32_e32 v101, v100, v100
	v_pk_add_f32 v[220:221], v[220:221], v[100:101]
	v_mul_f32_e32 v107, v106, v106
	v_pk_add_f32 v[220:221], v[220:221], v[106:107]
	v_mul_f32_e32 v103, v102, v102
	v_pk_add_f32 v[220:221], v[220:221], v[102:103]
	v_mul_f32_e32 v99, v98, v98
	v_pk_add_f32 v[220:221], v[220:221], v[98:99]
	v_mul_f32_e32 v97, v96, v96
	v_pk_add_f32 v[220:221], v[220:221], v[96:97]
	v_mul_f32_e32 v95, v94, v94
	v_pk_add_f32 v[220:221], v[220:221], v[94:95]
	v_mul_f32_e32 v93, v92, v92
	v_pk_add_f32 v[220:221], v[220:221], v[92:93]
	v_mul_f32_e32 v89, v88, v88
	v_pk_add_f32 v[220:221], v[220:221], v[88:89]
	v_mul_f32_e32 v85, v84, v84
	v_pk_add_f32 v[220:221], v[220:221], v[84:85]
	v_mul_f32_e32 v91, v90, v90
	v_pk_add_f32 v[220:221], v[220:221], v[90:91]
	v_mul_f32_e32 v87, v86, v86
	v_pk_add_f32 v[220:221], v[220:221], v[86:87]
	v_mul_f32_e32 v83, v82, v82
	v_pk_add_f32 v[220:221], v[220:221], v[82:83]
	v_mul_f32_e32 v81, v80, v80
	v_pk_add_f32 v[220:221], v[220:221], v[80:81]
	v_mul_f32_e32 v79, v78, v78
	v_pk_add_f32 v[220:221], v[220:221], v[78:79]
	v_mul_f32_e32 v77, v76, v76
	v_pk_add_f32 v[220:221], v[220:221], v[76:77]
	v_mul_f32_e32 v73, v72, v72
	v_pk_add_f32 v[220:221], v[220:221], v[72:73]
	v_mul_f32_e32 v61, v60, v60
	v_pk_add_f32 v[220:221], v[220:221], v[60:61]
	v_mul_f32_e32 v75, v74, v74
	v_pk_add_f32 v[220:221], v[220:221], v[74:75]
	v_mul_f32_e32 v63, v62, v62
	v_pk_add_f32 v[220:221], v[220:221], v[62:63]
	v_mul_f32_e32 v59, v58, v58
	v_pk_add_f32 v[220:221], v[220:221], v[58:59]
	v_mul_f32_e32 v57, v56, v56
	v_pk_add_f32 v[220:221], v[220:221], v[56:57]
	v_mul_f32_e32 v55, v54, v54
	v_pk_add_f32 v[220:221], v[220:221], v[54:55]
	v_mul_f32_e32 v53, v52, v52
	v_pk_add_f32 v[220:221], v[220:221], v[52:53]
	v_mul_f32_e32 v49, v48, v48
	v_pk_add_f32 v[220:221], v[220:221], v[48:49]
	v_mul_f32_e32 v45, v44, v44
	v_pk_add_f32 v[220:221], v[220:221], v[44:45]
	v_mul_f32_e32 v51, v50, v50
	v_pk_add_f32 v[220:221], v[220:221], v[50:51]
	v_mul_f32_e32 v47, v46, v46
	v_pk_add_f32 v[220:221], v[220:221], v[46:47]
	v_mul_f32_e32 v43, v42, v42
	v_pk_add_f32 v[220:221], v[220:221], v[42:43]
	v_mul_f32_e32 v41, v40, v40
	v_pk_add_f32 v[220:221], v[220:221], v[40:41]
	v_mul_f32_e32 v39, v38, v38
	v_pk_add_f32 v[220:221], v[220:221], v[38:39]
	v_mul_f32_e32 v37, v36, v36
	v_pk_add_f32 v[220:221], v[220:221], v[36:37]
	v_mul_f32_e32 v33, v32, v32
; __device__ __forceinline__ bf16_t f2bf(float f) { return (bf16_t)(cvt_pk_bf16(f, f) & 0xffffu); }
; __device__ __forceinline__ float ln_eps_s() { float e = LN_EPS; asm volatile("" : "+s"(e)); return e; }
; __device__ __forceinline__ void sg_item(int l, int chunk, LAS unsigned char* lds, const bf16_t* UB, const bf16_t* V2T, bf16_t* YC1, const bf16_t* Wb,
;                                         const float* sg_ln_g, const float* sg_ln_b, const float* sg_b, int lane, int wave) {
;     ...
;         for (int c = 0; c < 64; ++c) { sum += v[c]; sq += v[c] * v[c]; }
;         part[(cq * 128 + s) * 2] = sum; part[(cq * 128 + s) * 2 + 1] = sq;
;         const float gl = sg_ln_g[l * BW + 64 * cq + lane], bl = sg_ln_b[l * BW + 64 * cq + lane];
;         __syncthreads();
;         float ts = 0.f, tq = 0.f;
; #pragma unroll
;         for (int k = 0; k < 4; ++k) { ts += part[(k * 128 + s) * 2]; tq += part[(k * 128 + s) * 2 + 1]; }
;         const float mean = ts * (1.f / BW), var = fmaxf(tq * (1.f / BW) - mean * mean, 0.f), rstd = __builtin_amdgcn_rsqf(var + ln_eps_s());
; #pragma unroll
;         for (int c = 0; c < 64; ++c) {
;             const float gc = __uint_as_float(__builtin_amdgcn_readlane(__float_as_uint(gl), c)), bc = __uint_as_float(__builtin_amdgcn_readlane(__float_as_uint(bl), c));
;             vT[(64 * cq + c) * VS + s] = f2bf((v[c] - mean) * rstd * gc + bc);
	v_pk_add_f32 v[220:221], v[220:221], v[32:33]
	v_mul_f32_e32 v29, v28, v28
	v_pk_add_f32 v[220:221], v[220:221], v[28:29]
	v_mul_f32_e32 v35, v34, v34
	v_pk_add_f32 v[220:221], v[220:221], v[34:35]
	v_mul_f32_e32 v31, v30, v30
	v_pk_add_f32 v[220:221], v[220:221], v[30:31]
	v_mul_f32_e32 v27, v26, v26
	v_pk_add_f32 v[220:221], v[220:221], v[26:27]
	v_mul_f32_e32 v25, v24, v24
	v_pk_add_f32 v[220:221], v[220:221], v[24:25]
	v_mul_f32_e32 v23, v22, v22
	v_pk_add_f32 v[220:221], v[220:221], v[22:23]
	v_mul_f32_e32 v21, v20, v20
	v_pk_add_f32 v[220:221], v[220:221], v[20:21]
	v_mul_f32_e32 v17, v16, v16
	v_pk_add_f32 v[220:221], v[220:221], v[16:17]
	v_mul_f32_e32 v13, v12, v12
	v_pk_add_f32 v[220:221], v[220:221], v[12:13]
	v_mul_f32_e32 v19, v18, v18
	v_pk_add_f32 v[220:221], v[220:221], v[18:19]
	v_mul_f32_e32 v15, v14, v14
	v_pk_add_f32 v[220:221], v[220:221], v[14:15]
	v_mul_f32_e32 v11, v10, v10
	v_pk_add_f32 v[220:221], v[220:221], v[10:11]
	v_mul_f32_e32 v9, v8, v8
	v_pk_add_f32 v[220:221], v[220:221], v[8:9]
	v_mul_f32_e32 v7, v6, v6
	v_pk_add_f32 v[220:221], v[220:221], v[6:7]
	v_mul_f32_e32 v5, v4, v4
	v_pk_add_f32 v[220:221], v[220:221], v[4:5]
	v_mul_f32_e32 v3, v2, v2
	v_pk_add_f32 v[220:221], v[220:221], v[2:3]
	v_mul_f32_e32 v1, v0, v0
	v_pk_add_f32 v[220:221], v[220:221], v[0:1]
	s_mov_b32 s0, 0x3b800000
	ds_write_b64 v150, v[220:221]
	global_load_dword v1, v[64:65], off
	global_load_dword v3, v[66:67], off
	s_waitcnt lgkmcnt(0)
	s_barrier
	ds_read2st64_b64 v[220:223], v151 offset1:2
	s_add_u32 s48, s4, s80
	s_addc_u32 s49, s5, s81
	s_mov_b32 s12, 0xb400000
	s_waitcnt lgkmcnt(0)
	v_add_f32_e32 v5, 0, v220
	v_add_f32_e32 v7, 0, v221
	v_add_f32_e32 v5, v5, v222
	v_add_f32_e32 v7, v7, v223
	ds_read2st64_b64 v[220:223], v151 offset0:4 offset1:6
	s_waitcnt lgkmcnt(0)
	v_add_f32_e32 v5, v5, v220
	v_add_f32_e32 v5, v5, v222
	v_add_f32_e32 v7, v7, v221
	v_mul_f32_e32 v9, 0x3b800000, v5
	v_add_f32_e32 v7, v7, v223
	v_mul_f32_e32 v9, v9, v9
	v_fma_f32 v7, v7, s0, -v9
	v_max_f32_e32 v7, 0, v7
	s_mov_b32 s0, 0x3727c5ac
	v_fmac_f32_e32 v132, 0xbb800000, v5
	v_add_f32_e32 v7, s0, v7
	v_rsq_f32_e32 v7, v7
	v_fmac_f32_e32 v133, 0xbb800000, v5
	v_fmac_f32_e32 v130, 0xbb800000, v5
	v_fmac_f32_e32 v128, 0xbb800000, v5
	v_mul_f32_e32 v9, v132, v7
	v_fmac_f32_e32 v126, 0xbb800000, v5
	v_fmac_f32_e32 v124, 0xbb800000, v5
	v_fmac_f32_e32 v120, 0xbb800000, v5
	v_fmac_f32_e32 v116, 0xbb800000, v5
	v_fmac_f32_e32 v122, 0xbb800000, v5
	v_fmac_f32_e32 v118, 0xbb800000, v5
	v_fmac_f32_e32 v114, 0xbb800000, v5
	v_fmac_f32_e32 v112, 0xbb800000, v5
	v_fmac_f32_e32 v110, 0xbb800000, v5
	v_fmac_f32_e32 v108, 0xbb800000, v5
	v_fmac_f32_e32 v104, 0xbb800000, v5
	v_fmac_f32_e32 v100, 0xbb800000, v5
	v_fmac_f32_e32 v106, 0xbb800000, v5
	v_fmac_f32_e32 v102, 0xbb800000, v5
	v_fmac_f32_e32 v98, 0xbb800000, v5
	v_fmac_f32_e32 v96, 0xbb800000, v5
	v_fmac_f32_e32 v94, 0xbb800000, v5
	v_fmac_f32_e32 v92, 0xbb800000, v5
	v_fmac_f32_e32 v88, 0xbb800000, v5
	v_fmac_f32_e32 v84, 0xbb800000, v5
	v_fmac_f32_e32 v90, 0xbb800000, v5
	v_fmac_f32_e32 v86, 0xbb800000, v5
	v_fmac_f32_e32 v82, 0xbb800000, v5
	v_fmac_f32_e32 v80, 0xbb800000, v5
	v_fmac_f32_e32 v78, 0xbb800000, v5
	v_fmac_f32_e32 v76, 0xbb800000, v5
	v_fmac_f32_e32 v72, 0xbb800000, v5
	v_fmac_f32_e32 v60, 0xbb800000, v5
	v_fmac_f32_e32 v74, 0xbb800000, v5
	v_fmac_f32_e32 v62, 0xbb800000, v5
	v_fmac_f32_e32 v58, 0xbb800000, v5
	v_fmac_f32_e32 v56, 0xbb800000, v5
	v_fmac_f32_e32 v54, 0xbb800000, v5
	v_fmac_f32_e32 v52, 0xbb800000, v5
	v_fmac_f32_e32 v48, 0xbb800000, v5
	v_fmac_f32_e32 v44, 0xbb800000, v5
	v_fmac_f32_e32 v50, 0xbb800000, v5
	v_fmac_f32_e32 v46, 0xbb800000, v5
	v_fmac_f32_e32 v42, 0xbb800000, v5
	v_fmac_f32_e32 v40, 0xbb800000, v5
	v_fmac_f32_e32 v38, 0xbb800000, v5
	v_fmac_f32_e32 v36, 0xbb800000, v5
	v_fmac_f32_e32 v32, 0xbb800000, v5
	v_fmac_f32_e32 v28, 0xbb800000, v5
	s_waitcnt vmcnt(1)
	v_readlane_b32 s0, v1, 0
	s_waitcnt vmcnt(0)
	v_readlane_b32 s1, v3, 0
	v_fmac_f32_e32 v34, 0xbb800000, v5
	v_fmac_f32_e32 v30, 0xbb800000, v5
	v_mov_b32_e32 v11, s1
	v_fmac_f32_e32 v11, s0, v9
	v_cvt_pk_bf16_f32 v9, v11, v11
	v_readlane_b32 s1, v3, 1
	ds_write_b16 v202, v9
	v_readlane_b32 s0, v1, 1
	v_mul_f32_e32 v9, v133, v7
	v_mov_b32_e32 v11, s1
	v_fmac_f32_e32 v11, s0, v9
	v_cvt_pk_bf16_f32 v9, v11, v11
	v_readlane_b32 s1, v3, 2
	ds_write_b16 v202, v9 offset:272
	v_readlane_b32 s0, v1, 2
	v_mul_f32_e32 v9, v130, v7
	v_mov_b32_e32 v11, s1
	v_fmac_f32_e32 v11, s0, v9
	v_cvt_pk_bf16_f32 v9, v11, v11
	v_readlane_b32 s1, v3, 3
	ds_write_b16 v202, v9 offset:544
	v_readlane_b32 s0, v1, 3
	v_mul_f32_e32 v9, v128, v7
	v_mov_b32_e32 v11, s1
	v_fmac_f32_e32 v11, s0, v9
	v_cvt_pk_bf16_f32 v9, v11, v11
	v_readlane_b32 s1, v3, 4
	ds_write_b16 v202, v9 offset:816
	v_readlane_b32 s0, v1, 4
	v_mul_f32_e32 v9, v126, v7
	v_mov_b32_e32 v11, s1
	v_fmac_f32_e32 v11, s0, v9
	v_cvt_pk_bf16_f32 v9, v11, v11
	v_readlane_b32 s1, v3, 5
	ds_write_b16 v202, v9 offset:1088
	v_readlane_b32 s0, v1, 5
	v_mul_f32_e32 v9, v124, v7
	v_mov_b32_e32 v11, s1
	v_fmac_f32_e32 v11, s0, v9
	v_cvt_pk_bf16_f32 v9, v11, v11
	v_readlane_b32 s1, v3, 6
	ds_write_b16 v202, v9 offset:1360
	v_readlane_b32 s0, v1, 6
	v_mul_f32_e32 v9, v120, v7
	v_mov_b32_e32 v11, s1
	v_fmac_f32_e32 v11, s0, v9
	v_cvt_pk_bf16_f32 v9, v11, v11
	v_readlane_b32 s1, v3, 7
	ds_write_b16 v202, v9 offset:1632
	v_readlane_b32 s0, v1, 7
	v_mul_f32_e32 v9, v116, v7
	v_mov_b32_e32 v11, s1
	v_fmac_f32_e32 v11, s0, v9
	v_cvt_pk_bf16_f32 v9, v11, v11
	v_readlane_b32 s1, v3, 8
	ds_write_b16 v202, v9 offset:1904
	v_readlane_b32 s0, v1, 8
	v_mul_f32_e32 v9, v122, v7
	v_mov_b32_e32 v11, s1
; __device__ __forceinline__ bf16_t f2bf(float f) { return (bf16_t)(cvt_pk_bf16(f, f) & 0xffffu); }
; __device__ __forceinline__ void sg_item(int l, int chunk, LAS unsigned char* lds, const bf16_t* UB, const bf16_t* V2T, bf16_t* YC1, const bf16_t* Wb,
;                                         const float* sg_ln_g, const float* sg_ln_b, const float* sg_b, int lane, int wave) {
;     ...
; #pragma unroll
;         for (int c = 0; c < 64; ++c) {
;             const float gc = __uint_as_float(__builtin_amdgcn_readlane(__float_as_uint(gl), c)), bc = __uint_as_float(__builtin_amdgcn_readlane(__float_as_uint(bl), c));
;             vT[(64 * cq + c) * VS + s] = f2bf((v[c] - mean) * rstd * gc + bc);
	v_fmac_f32_e32 v11, s0, v9
	v_cvt_pk_bf16_f32 v9, v11, v11
	v_readlane_b32 s1, v3, 9
	ds_write_b16 v202, v9 offset:2176
	v_readlane_b32 s0, v1, 9
	v_mul_f32_e32 v9, v118, v7
	v_mov_b32_e32 v11, s1
	v_fmac_f32_e32 v11, s0, v9
	v_cvt_pk_bf16_f32 v9, v11, v11
	v_readlane_b32 s1, v3, 10
	ds_write_b16 v202, v9 offset:2448
	v_readlane_b32 s0, v1, 10
	v_mul_f32_e32 v9, v114, v7
	v_mov_b32_e32 v11, s1
	v_fmac_f32_e32 v11, s0, v9
	v_cvt_pk_bf16_f32 v9, v11, v11
	v_readlane_b32 s1, v3, 11
	ds_write_b16 v202, v9 offset:2720
	v_readlane_b32 s0, v1, 11
	v_mul_f32_e32 v9, v112, v7
	v_mov_b32_e32 v11, s1
	v_fmac_f32_e32 v11, s0, v9
	v_cvt_pk_bf16_f32 v9, v11, v11
	v_readlane_b32 s1, v3, 12
	ds_write_b16 v202, v9 offset:2992
	v_readlane_b32 s0, v1, 12
	v_mul_f32_e32 v9, v110, v7
	v_mov_b32_e32 v11, s1
	v_fmac_f32_e32 v11, s0, v9
	v_cvt_pk_bf16_f32 v9, v11, v11
	v_readlane_b32 s1, v3, 13
	ds_write_b16 v202, v9 offset:3264
	v_readlane_b32 s0, v1, 13
	v_mul_f32_e32 v9, v108, v7
	v_mov_b32_e32 v11, s1
	v_fmac_f32_e32 v11, s0, v9
	v_cvt_pk_bf16_f32 v9, v11, v11
	v_readlane_b32 s1, v3, 14
	ds_write_b16 v202, v9 offset:3536
	v_readlane_b32 s0, v1, 14
	v_mul_f32_e32 v9, v104, v7
	v_mov_b32_e32 v11, s1
	v_fmac_f32_e32 v11, s0, v9
	v_cvt_pk_bf16_f32 v9, v11, v11
	v_readlane_b32 s1, v3, 15
	ds_write_b16 v202, v9 offset:3808
	v_readlane_b32 s0, v1, 15
	v_mul_f32_e32 v9, v100, v7
	v_mov_b32_e32 v11, s1
	v_fmac_f32_e32 v11, s0, v9
	v_cvt_pk_bf16_f32 v9, v11, v11
	v_readlane_b32 s1, v3, 16
	ds_write_b16 v202, v9 offset:4080
	v_readlane_b32 s0, v1, 16
	v_mul_f32_e32 v9, v106, v7
	v_mov_b32_e32 v11, s1
	v_fmac_f32_e32 v11, s0, v9
	v_cvt_pk_bf16_f32 v9, v11, v11
	v_readlane_b32 s1, v3, 17
	ds_write_b16 v202, v9 offset:4352
	v_readlane_b32 s0, v1, 17
	v_mul_f32_e32 v9, v102, v7
	v_mov_b32_e32 v11, s1
	v_fmac_f32_e32 v11, s0, v9
	v_cvt_pk_bf16_f32 v9, v11, v11
	v_readlane_b32 s1, v3, 18
	ds_write_b16 v202, v9 offset:4624
	v_readlane_b32 s0, v1, 18
	v_mul_f32_e32 v9, v98, v7
	v_mov_b32_e32 v11, s1
	v_fmac_f32_e32 v11, s0, v9
	v_cvt_pk_bf16_f32 v9, v11, v11
	v_readlane_b32 s1, v3, 19
	ds_write_b16 v202, v9 offset:4896
	v_readlane_b32 s0, v1, 19
	v_mul_f32_e32 v9, v96, v7
	v_mov_b32_e32 v11, s1
	v_fmac_f32_e32 v11, s0, v9
	v_cvt_pk_bf16_f32 v9, v11, v11
	v_readlane_b32 s1, v3, 20
	ds_write_b16 v202, v9 offset:5168
	v_readlane_b32 s0, v1, 20
	v_mul_f32_e32 v9, v94, v7
	v_mov_b32_e32 v11, s1
	v_fmac_f32_e32 v11, s0, v9
	v_cvt_pk_bf16_f32 v9, v11, v11
	v_readlane_b32 s1, v3, 21
	ds_write_b16 v202, v9 offset:5440
	v_readlane_b32 s0, v1, 21
	v_mul_f32_e32 v9, v92, v7
	v_mov_b32_e32 v11, s1
	v_fmac_f32_e32 v11, s0, v9
	v_cvt_pk_bf16_f32 v9, v11, v11
	v_readlane_b32 s1, v3, 22
	ds_write_b16 v202, v9 offset:5712
	v_readlane_b32 s0, v1, 22
	v_mul_f32_e32 v9, v88, v7
	v_mov_b32_e32 v11, s1
	v_fmac_f32_e32 v11, s0, v9
	v_cvt_pk_bf16_f32 v9, v11, v11
	v_readlane_b32 s1, v3, 23
	ds_write_b16 v202, v9 offset:5984
	v_readlane_b32 s0, v1, 23
	v_mul_f32_e32 v9, v84, v7
	v_mov_b32_e32 v11, s1
	v_fmac_f32_e32 v11, s0, v9
	v_cvt_pk_bf16_f32 v9, v11, v11
	v_readlane_b32 s1, v3, 24
	ds_write_b16 v202, v9 offset:6256
	v_readlane_b32 s0, v1, 24
	v_mul_f32_e32 v9, v90, v7
	v_mov_b32_e32 v11, s1
	v_fmac_f32_e32 v11, s0, v9
	v_cvt_pk_bf16_f32 v9, v11, v11
	v_readlane_b32 s1, v3, 25
	ds_write_b16 v202, v9 offset:6528
	v_readlane_b32 s0, v1, 25
	v_mul_f32_e32 v9, v86, v7
	v_mov_b32_e32 v11, s1
	v_fmac_f32_e32 v11, s0, v9
	v_cvt_pk_bf16_f32 v9, v11, v11
	v_readlane_b32 s1, v3, 26
	ds_write_b16 v202, v9 offset:6800
	v_readlane_b32 s0, v1, 26
	v_mul_f32_e32 v9, v82, v7
	v_mov_b32_e32 v11, s1
	v_fmac_f32_e32 v11, s0, v9
	v_cvt_pk_bf16_f32 v9, v11, v11
	v_readlane_b32 s1, v3, 27
	ds_write_b16 v202, v9 offset:7072
	v_readlane_b32 s0, v1, 27
	v_mul_f32_e32 v9, v80, v7
	v_mov_b32_e32 v11, s1
	v_fmac_f32_e32 v11, s0, v9
	v_cvt_pk_bf16_f32 v9, v11, v11
	v_readlane_b32 s1, v3, 28
	ds_write_b16 v202, v9 offset:7344
	v_readlane_b32 s0, v1, 28
	v_mul_f32_e32 v9, v78, v7
	v_mov_b32_e32 v11, s1
	v_fmac_f32_e32 v11, s0, v9
	v_cvt_pk_bf16_f32 v9, v11, v11
	v_readlane_b32 s1, v3, 29
	ds_write_b16 v202, v9 offset:7616
	v_readlane_b32 s0, v1, 29
	v_mul_f32_e32 v9, v76, v7
	v_mov_b32_e32 v11, s1
	v_fmac_f32_e32 v11, s0, v9
	v_cvt_pk_bf16_f32 v9, v11, v11
	v_readlane_b32 s1, v3, 30
	ds_write_b16 v202, v9 offset:7888
	v_readlane_b32 s0, v1, 30
	v_mul_f32_e32 v9, v72, v7
	v_mov_b32_e32 v11, s1
	v_fmac_f32_e32 v11, s0, v9
	v_cvt_pk_bf16_f32 v9, v11, v11
	v_readlane_b32 s1, v3, 31
	ds_write_b16 v202, v9 offset:8160
	v_readlane_b32 s0, v1, 31
	v_mul_f32_e32 v9, v60, v7
	v_mov_b32_e32 v11, s1
	v_fmac_f32_e32 v11, s0, v9
	v_cvt_pk_bf16_f32 v9, v11, v11
	v_readlane_b32 s1, v3, 32
	ds_write_b16 v202, v9 offset:8432
	v_readlane_b32 s0, v1, 32
	v_mul_f32_e32 v9, v74, v7
	v_mov_b32_e32 v11, s1
	v_fmac_f32_e32 v11, s0, v9
	v_cvt_pk_bf16_f32 v9, v11, v11
	v_readlane_b32 s1, v3, 33
	ds_write_b16 v202, v9 offset:8704
	v_readlane_b32 s0, v1, 33
	v_mul_f32_e32 v9, v62, v7
	v_mov_b32_e32 v11, s1
	v_fmac_f32_e32 v11, s0, v9
	v_cvt_pk_bf16_f32 v9, v11, v11
	v_readlane_b32 s1, v3, 34
	ds_write_b16 v202, v9 offset:8976
	v_readlane_b32 s0, v1, 34
	v_mul_f32_e32 v9, v58, v7
	v_mov_b32_e32 v11, s1
	v_fmac_f32_e32 v11, s0, v9
	v_cvt_pk_bf16_f32 v9, v11, v11
	v_readlane_b32 s1, v3, 35
	ds_write_b16 v202, v9 offset:9248
	v_readlane_b32 s0, v1, 35
	v_mul_f32_e32 v9, v56, v7
	v_mov_b32_e32 v11, s1
	v_fmac_f32_e32 v11, s0, v9
	v_cvt_pk_bf16_f32 v9, v11, v11
	v_readlane_b32 s1, v3, 36
	ds_write_b16 v202, v9 offset:9520
	v_readlane_b32 s0, v1, 36
	v_mul_f32_e32 v9, v54, v7
	v_mov_b32_e32 v11, s1
	v_fmac_f32_e32 v11, s0, v9
	v_cvt_pk_bf16_f32 v9, v11, v11
; __device__ __forceinline__ bf16_t f2bf(float f) { return (bf16_t)(cvt_pk_bf16(f, f) & 0xffffu); }
; __device__ __forceinline__ void sg_item(int l, int chunk, LAS unsigned char* lds, const bf16_t* UB, const bf16_t* V2T, bf16_t* YC1, const bf16_t* Wb,
;                                         const float* sg_ln_g, const float* sg_ln_b, const float* sg_b, int lane, int wave) {
;     ...
; #pragma unroll
;         for (int c = 0; c < 64; ++c) {
;             const float gc = __uint_as_float(__builtin_amdgcn_readlane(__float_as_uint(gl), c)), bc = __uint_as_float(__builtin_amdgcn_readlane(__float_as_uint(bl), c));
;             vT[(64 * cq + c) * VS + s] = f2bf((v[c] - mean) * rstd * gc + bc);
;         }
;     }
;     __syncthreads();
	v_readlane_b32 s1, v3, 37
	ds_write_b16 v202, v9 offset:9792
	v_readlane_b32 s0, v1, 37
	v_mul_f32_e32 v9, v52, v7
	v_mov_b32_e32 v11, s1
	v_fmac_f32_e32 v11, s0, v9
	v_cvt_pk_bf16_f32 v9, v11, v11
	v_readlane_b32 s1, v3, 38
	ds_write_b16 v202, v9 offset:10064
	v_readlane_b32 s0, v1, 38
	v_mul_f32_e32 v9, v48, v7
	v_mov_b32_e32 v11, s1
	v_fmac_f32_e32 v11, s0, v9
	v_cvt_pk_bf16_f32 v9, v11, v11
	v_readlane_b32 s1, v3, 39
	ds_write_b16 v202, v9 offset:10336
	v_readlane_b32 s0, v1, 39
	v_mul_f32_e32 v9, v44, v7
	v_mov_b32_e32 v11, s1
	v_fmac_f32_e32 v11, s0, v9
	v_cvt_pk_bf16_f32 v9, v11, v11
	v_readlane_b32 s1, v3, 40
	ds_write_b16 v202, v9 offset:10608
	v_readlane_b32 s0, v1, 40
	v_mul_f32_e32 v9, v50, v7
	v_mov_b32_e32 v11, s1
	v_fmac_f32_e32 v11, s0, v9
	v_cvt_pk_bf16_f32 v9, v11, v11
	v_readlane_b32 s1, v3, 41
	ds_write_b16 v202, v9 offset:10880
	v_readlane_b32 s0, v1, 41
	v_mul_f32_e32 v9, v46, v7
	v_mov_b32_e32 v11, s1
	v_fmac_f32_e32 v11, s0, v9
	v_cvt_pk_bf16_f32 v9, v11, v11
	v_readlane_b32 s1, v3, 42
	ds_write_b16 v202, v9 offset:11152
	v_readlane_b32 s0, v1, 42
	v_mul_f32_e32 v9, v42, v7
	v_mov_b32_e32 v11, s1
	v_fmac_f32_e32 v11, s0, v9
	v_cvt_pk_bf16_f32 v9, v11, v11
	v_readlane_b32 s1, v3, 43
	ds_write_b16 v202, v9 offset:11424
	v_readlane_b32 s0, v1, 43
	v_mul_f32_e32 v9, v40, v7
	v_mov_b32_e32 v11, s1
	v_fmac_f32_e32 v11, s0, v9
	v_cvt_pk_bf16_f32 v9, v11, v11
	v_readlane_b32 s1, v3, 44
	ds_write_b16 v202, v9 offset:11696
	v_readlane_b32 s0, v1, 44
	v_mul_f32_e32 v9, v38, v7
	v_mov_b32_e32 v11, s1
	v_fmac_f32_e32 v11, s0, v9
	v_cvt_pk_bf16_f32 v9, v11, v11
	v_readlane_b32 s1, v3, 45
	ds_write_b16 v202, v9 offset:11968
	v_readlane_b32 s0, v1, 45
	v_mul_f32_e32 v9, v36, v7
	v_mov_b32_e32 v11, s1
	v_fmac_f32_e32 v11, s0, v9
	v_cvt_pk_bf16_f32 v9, v11, v11
	v_readlane_b32 s1, v3, 46
	ds_write_b16 v202, v9 offset:12240
	v_readlane_b32 s0, v1, 46
	v_mul_f32_e32 v9, v32, v7
	v_mov_b32_e32 v11, s1
	v_fmac_f32_e32 v11, s0, v9
	v_cvt_pk_bf16_f32 v9, v11, v11
	v_readlane_b32 s1, v3, 47
	ds_write_b16 v202, v9 offset:12512
	v_readlane_b32 s0, v1, 47
	v_mul_f32_e32 v9, v28, v7
	v_mov_b32_e32 v11, s1
	v_fmac_f32_e32 v11, s0, v9
	v_cvt_pk_bf16_f32 v9, v11, v11
	v_readlane_b32 s1, v3, 48
	ds_write_b16 v202, v9 offset:12784
	v_readlane_b32 s0, v1, 48
	v_mul_f32_e32 v9, v34, v7
	v_mov_b32_e32 v11, s1
	v_fmac_f32_e32 v11, s0, v9
	v_cvt_pk_bf16_f32 v9, v11, v11
	v_readlane_b32 s1, v3, 49
	ds_write_b16 v202, v9 offset:13056
	v_readlane_b32 s0, v1, 49
	v_mul_f32_e32 v9, v30, v7
	v_mov_b32_e32 v11, s1
	v_fmac_f32_e32 v11, s0, v9
	v_cvt_pk_bf16_f32 v9, v11, v11
	v_readlane_b32 s1, v3, 50
	v_fmac_f32_e32 v26, 0xbb800000, v5
	ds_write_b16 v202, v9 offset:13328
	v_readlane_b32 s0, v1, 50
	v_mul_f32_e32 v9, v26, v7
	v_mov_b32_e32 v11, s1
	v_fmac_f32_e32 v11, s0, v9
	v_cvt_pk_bf16_f32 v9, v11, v11
	v_readlane_b32 s1, v3, 51
	v_fmac_f32_e32 v24, 0xbb800000, v5
	ds_write_b16 v202, v9 offset:13600
	v_readlane_b32 s0, v1, 51
	v_mul_f32_e32 v9, v24, v7
	v_mov_b32_e32 v11, s1
	v_fmac_f32_e32 v11, s0, v9
	v_cvt_pk_bf16_f32 v9, v11, v11
	v_readlane_b32 s1, v3, 52
	v_fmac_f32_e32 v22, 0xbb800000, v5
	ds_write_b16 v202, v9 offset:13872
	v_readlane_b32 s0, v1, 52
	v_mul_f32_e32 v9, v22, v7
	v_mov_b32_e32 v11, s1
	v_fmac_f32_e32 v11, s0, v9
	v_cvt_pk_bf16_f32 v9, v11, v11
	v_readlane_b32 s1, v3, 53
	v_fmac_f32_e32 v20, 0xbb800000, v5
	ds_write_b16 v202, v9 offset:14144
	v_readlane_b32 s0, v1, 53
	v_mul_f32_e32 v9, v20, v7
	v_mov_b32_e32 v11, s1
	v_fmac_f32_e32 v11, s0, v9
	v_cvt_pk_bf16_f32 v9, v11, v11
	v_readlane_b32 s1, v3, 54
	v_fmac_f32_e32 v16, 0xbb800000, v5
	ds_write_b16 v202, v9 offset:14416
	v_readlane_b32 s0, v1, 54
	v_mul_f32_e32 v9, v16, v7
	v_mov_b32_e32 v11, s1
	v_fmac_f32_e32 v11, s0, v9
	v_cvt_pk_bf16_f32 v9, v11, v11
	v_readlane_b32 s1, v3, 55
	v_fmac_f32_e32 v12, 0xbb800000, v5
	ds_write_b16 v202, v9 offset:14688
	v_readlane_b32 s0, v1, 55
	v_mul_f32_e32 v9, v12, v7
	v_mov_b32_e32 v11, s1
	v_fmac_f32_e32 v11, s0, v9
	v_cvt_pk_bf16_f32 v9, v11, v11
	v_readlane_b32 s1, v3, 56
	v_fmac_f32_e32 v18, 0xbb800000, v5
	ds_write_b16 v202, v9 offset:14960
	v_readlane_b32 s0, v1, 56
	v_mul_f32_e32 v9, v18, v7
	v_mov_b32_e32 v11, s1
	v_fmac_f32_e32 v11, s0, v9
	v_cvt_pk_bf16_f32 v9, v11, v11
	v_readlane_b32 s1, v3, 57
	v_fmac_f32_e32 v14, 0xbb800000, v5
	ds_write_b16 v202, v9 offset:15232
	v_readlane_b32 s0, v1, 57
	v_mul_f32_e32 v9, v14, v7
	v_mov_b32_e32 v11, s1
	v_fmac_f32_e32 v11, s0, v9
	v_cvt_pk_bf16_f32 v9, v11, v11
	v_readlane_b32 s1, v3, 58
	v_fmac_f32_e32 v10, 0xbb800000, v5
	ds_write_b16 v202, v9 offset:15504
	v_readlane_b32 s0, v1, 58
	v_mul_f32_e32 v9, v10, v7
	v_mov_b32_e32 v10, s1
	v_fmac_f32_e32 v10, s0, v9
	v_cvt_pk_bf16_f32 v9, v10, v10
	v_readlane_b32 s1, v3, 59
	v_fmac_f32_e32 v8, 0xbb800000, v5
	ds_write_b16 v202, v9 offset:15776
	v_readlane_b32 s0, v1, 59
	v_mul_f32_e32 v8, v8, v7
	v_mov_b32_e32 v9, s1
	v_fmac_f32_e32 v9, s0, v8
	v_cvt_pk_bf16_f32 v8, v9, v9
	v_readlane_b32 s1, v3, 60
	v_fmac_f32_e32 v6, 0xbb800000, v5
	ds_write_b16 v202, v8 offset:16048
	v_readlane_b32 s0, v1, 60
	v_mul_f32_e32 v6, v6, v7
	v_mov_b32_e32 v8, s1
	v_fmac_f32_e32 v8, s0, v6
	v_cvt_pk_bf16_f32 v6, v8, v8
	v_readlane_b32 s1, v3, 61
	v_fmac_f32_e32 v4, 0xbb800000, v5
	ds_write_b16 v202, v6 offset:16320
	v_readlane_b32 s0, v1, 61
	v_mul_f32_e32 v4, v4, v7
	v_mov_b32_e32 v6, s1
	v_fmac_f32_e32 v6, s0, v4
	v_cvt_pk_bf16_f32 v4, v6, v6
	v_readlane_b32 s1, v3, 62
	v_fmac_f32_e32 v2, 0xbb800000, v5
	ds_write_b16 v202, v4 offset:16592
	v_readlane_b32 s0, v1, 62
	v_mul_f32_e32 v2, v2, v7
	v_mov_b32_e32 v4, s1
	v_readlane_b32 s1, v3, 63
	v_fmac_f32_e32 v0, 0xbb800000, v5
	v_fmac_f32_e32 v4, s0, v2
	v_readlane_b32 s0, v1, 63
	v_mul_f32_e32 v0, v0, v7
	v_mov_b32_e32 v1, s1
	v_cvt_pk_bf16_f32 v2, v4, v4
	ds_write_b16 v202, v2 offset:16864
	v_fmac_f32_e32 v1, s0, v0
	v_cvt_pk_bf16_f32 v0, v1, v1
	ds_write_b16 v202, v0 offset:17136
	s_waitcnt lgkmcnt(0)
	s_barrier
; #define LAS __attribute__((address_space(3)))
; __device__ __forceinline__ int crow(int r, int hi) { return (r & 3) + 8 * (r >> 2) + 4 * hi; }
; __device__ __forceinline__ void sg_item(int l, int chunk, LAS unsigned char* lds, const bf16_t* UB, const bf16_t* V2T, bf16_t* YC1, const bf16_t* Wb,
;                                         const float* sg_ln_g, const float* sg_ln_b, const float* sg_b, int lane, int wave) {
;     ...
;         bf16x8 Bf[8];
; #pragma unroll
;         for (int ks = 0; ks < 8; ++ks) Bf[ks] = *(const LAS bf16x8*)(vT + c * VS + 16 * ks + 8 * hi);
; #pragma unroll
;         for (int i = 0; i < 4; ++i) {
; #pragma unroll
;             for (int kb = 0; kb < 2 * i + 2; kb += 4) {
;                 u32x4 af[4]; const void* pp[4];
; #pragma unroll
;                 for (int j = 0; j < 4; ++j) pp[j] = Wg + (size_t)(32 * i) * 128 + 16 * ((kb + j) < 2 * i + 2 ? (kb + j) : 0);
;                 ld_b128_s4(af, avoff, pp);
; #pragma unroll
;                 for (int j = 0; j < 4; ++j) if (kb + j < 2 * i + 2) acc[i] = __builtin_amdgcn_mfma_f32_32x32x16_bf16(__builtin_bit_cast(bf16x8, af[j]), Bf[kb + j], acc[i], 0, 0, 0);
;             }
;         }
;         const float sb_lo = sg_b[(l * 4 + g) * 128 + lane], sb_hi = sg_b[(l * 4 + g) * 128 + 64 + lane];
;         const unsigned uvoff = (unsigned)(4 * hi * BW + c) * 2u;
; #pragma unroll
;         for (int i = 0; i < 4; ++i) {
;             unsigned uu[16];
; #pragma unroll
;             for (int rb = 0; rb < 16; rb += 8) {
;                 unsigned raw[8]; const void* pp[8];
; #pragma unroll
;                 for (int j = 0; j < 8; ++j) pp[j] = UB + (r0 + 32 * i + crow(rb + j, 0)) * BW;
;                 ld_u16_s8(raw, uvoff, pp);
	ds_read_b128 v[0:3], v201
	ds_read_b128 v[72:75], v201 offset:32
	ds_read_b128 v[76:79], v201 offset:64
	ds_read_b128 v[80:83], v201 offset:96
	ds_read_b128 v[84:87], v201 offset:128
	ds_read_b128 v[88:91], v201 offset:160
	ds_read_b128 v[92:95], v201 offset:192
	ds_read_b128 v[96:99], v201 offset:224
	s_add_u32 s98, s92, s80
	s_addc_u32 s99, s93, s81
	global_load_ushort v112, v152, s[48:49]
	s_add_u32 s98, s98, 0x200
	s_addc_u32 s99, s99, 0
	global_load_ushort v113, v152, s[98:99]
	s_add_u32 s98, s98, 0x200
	s_addc_u32 s99, s99, 0
	global_load_ushort v114, v152, s[98:99]
	s_add_u32 s98, s98, 0x200
	s_addc_u32 s99, s99, 0
	global_load_ushort v115, v152, s[98:99]
	s_add_u32 s98, s98, 0xa00
	s_addc_u32 s99, s99, 0
	global_load_ushort v116, v152, s[98:99]
	s_add_u32 s98, s98, 0x200
	s_addc_u32 s99, s99, 0
	global_load_ushort v117, v152, s[98:99]
	s_add_u32 s98, s98, 0x200
	s_addc_u32 s99, s99, 0
	global_load_ushort v118, v152, s[98:99]
	s_add_u32 s98, s98, 0x200
	s_addc_u32 s99, s99, 0
	global_load_ushort v119, v152, s[98:99]
	s_add_u32 s98, s98, 0xa00
	s_addc_u32 s99, s99, 0
	global_load_ushort v120, v152, s[98:99]
	s_add_u32 s98, s98, 0x200
	s_addc_u32 s99, s99, 0
	global_load_ushort v121, v152, s[98:99]
	s_add_u32 s98, s98, 0x200
	s_addc_u32 s99, s99, 0
	global_load_ushort v122, v152, s[98:99]
	s_add_u32 s98, s98, 0x200
	s_addc_u32 s99, s99, 0
	global_load_ushort v123, v152, s[98:99]
	s_add_u32 s98, s98, 0xa00
	s_addc_u32 s99, s99, 0
	global_load_ushort v124, v152, s[98:99]
	s_add_u32 s98, s98, 0x200
	s_addc_u32 s99, s99, 0
	global_load_ushort v125, v152, s[98:99]
	s_add_u32 s98, s98, 0x200
	s_addc_u32 s99, s99, 0
	global_load_ushort v126, v152, s[98:99]
	s_add_u32 s98, s98, 0x200
	s_addc_u32 s99, s99, 0
	global_load_ushort v127, v152, s[98:99]
	s_add_u32 s98, s98, 0xa00
	s_addc_u32 s99, s99, 0
	global_load_ushort v128, v152, s[98:99]
	s_add_u32 s98, s98, 0x200
	s_addc_u32 s99, s99, 0
	global_load_ushort v129, v152, s[98:99]
	s_add_u32 s98, s98, 0x200
	s_addc_u32 s99, s99, 0
	global_load_ushort v130, v152, s[98:99]
	s_add_u32 s98, s98, 0x200
	s_addc_u32 s99, s99, 0
	global_load_ushort v131, v152, s[98:99]
	s_add_u32 s98, s98, 0xa00
	s_addc_u32 s99, s99, 0
	global_load_ushort v132, v152, s[98:99]
	s_add_u32 s98, s98, 0x200
	s_addc_u32 s99, s99, 0
	global_load_ushort v133, v152, s[98:99]
	s_add_u32 s98, s98, 0x200
	s_addc_u32 s99, s99, 0
	global_load_ushort v220, v152, s[98:99]
	s_add_u32 s98, s98, 0x200
	s_addc_u32 s99, s99, 0
	global_load_ushort v221, v152, s[98:99]
	s_add_u32 s98, s98, 0xa00
	s_addc_u32 s99, s99, 0
	global_load_ushort v222, v152, s[98:99]
	s_add_u32 s98, s98, 0x200
	s_addc_u32 s99, s99, 0
	global_load_ushort v223, v152, s[98:99]
	s_add_u32 s98, s98, 0x200
	s_addc_u32 s99, s99, 0
	global_load_ushort v224, v152, s[98:99]
	s_add_u32 s98, s98, 0x200
	s_addc_u32 s99, s99, 0
	global_load_ushort v225, v152, s[98:99]
	s_add_u32 s98, s98, 0xa00
	s_addc_u32 s99, s99, 0
	global_load_ushort v226, v152, s[98:99]
	s_add_u32 s98, s98, 0x200
	s_addc_u32 s99, s99, 0
	global_load_ushort v227, v152, s[98:99]
	s_add_u32 s98, s98, 0x200
	s_addc_u32 s99, s99, 0
	global_load_ushort v228, v152, s[98:99]
	s_add_u32 s98, s98, 0x200
	s_addc_u32 s99, s99, 0
	global_load_ushort v229, v152, s[98:99]
	s_nop 4
	global_load_dwordx4 v[4:7], v203, s[6:7]
	global_load_dwordx4 v[8:11], v203, s[8:9]
	global_load_dwordx4 v[12:15], v203, s[6:7]
	global_load_dwordx4 v[16:19], v203, s[6:7]
	s_waitcnt vmcnt(0)
	s_add_u32 s0, s92, s80
	s_waitcnt lgkmcnt(7)
	v_mfma_f32_32x32x16_bf16 v[48:63], v[4:7], v[0:3], 0
	s_addc_u32 s1, s93, s81
	s_add_u32 s50, s0, 0x200
	s_addc_u32 s51, s1, 0
	s_add_u32 s52, s0, 0x400
	s_addc_u32 s53, s1, 0
	s_add_u32 s54, s0, 0x600
	s_addc_u32 s55, s1, 0
	s_waitcnt lgkmcnt(6)
	v_mfma_f32_32x32x16_bf16 v[48:63], v[8:11], v[72:75], v[48:63]
	s_nop 4
	global_load_dwordx4 v[4:7], v203, s[10:11]
	global_load_dwordx4 v[8:11], v203, s[16:17]
	global_load_dwordx4 v[12:15], v203, s[18:19]
	global_load_dwordx4 v[16:19], v203, s[20:21]
	s_waitcnt vmcnt(0)
	s_add_u32 s56, s0, 0x1000
	s_addc_u32 s57, s1, 0
	s_add_u32 s58, s0, 0x1200
	s_addc_u32 s59, s1, 0
	s_add_u32 s60, s0, 0x1400
	s_addc_u32 s61, s1, 0
	v_mfma_f32_32x32x16_bf16 v[32:47], v[4:7], v[0:3], 0
	s_add_u32 s62, s0, 0x1600
	s_addc_u32 s63, s1, 0
	v_mfma_f32_32x32x16_bf16 v[32:47], v[8:11], v[72:75], v[32:47]
	s_waitcnt lgkmcnt(5)
	v_mfma_f32_32x32x16_bf16 v[32:47], v[12:15], v[76:79], v[32:47]
	s_nop 4
	global_load_dwordx4 v[4:7], v203, s[22:23]
	global_load_dwordx4 v[8:11], v203, s[24:25]
	global_load_dwordx4 v[12:15], v203, s[26:27]
	global_load_dwordx4 v[100:103], v203, s[28:29]
	s_waitcnt vmcnt(0)
	s_waitcnt lgkmcnt(4)
	v_mfma_f32_32x32x16_bf16 v[32:47], v[16:19], v[80:83], v[32:47]
	v_mfma_f32_32x32x16_bf16 v[16:31], v[4:7], v[0:3], 0
	v_mfma_f32_32x32x16_bf16 v[16:31], v[8:11], v[72:75], v[16:31]
	v_mfma_f32_32x32x16_bf16 v[16:31], v[12:15], v[76:79], v[16:31]
	v_mfma_f32_32x32x16_bf16 v[16:31], v[100:103], v[80:83], v[16:31]
	s_nop 4
	global_load_dwordx4 v[4:7], v203, s[30:31]
	global_load_dwordx4 v[8:11], v203, s[34:35]
	global_load_dwordx4 v[12:15], v203, s[22:23]
	global_load_dwordx4 v[100:103], v203, s[22:23]
	s_waitcnt vmcnt(0)
	s_waitcnt lgkmcnt(3)
	v_mfma_f32_32x32x16_bf16 v[16:31], v[4:7], v[84:87], v[16:31]
	s_nop 4
	global_load_dwordx4 v[4:7], v203, s[36:37]
	global_load_dwordx4 v[100:103], v203, s[38:39]
	global_load_dwordx4 v[104:107], v203, s[68:69]
	global_load_dwordx4 v[108:111], v203, s[70:71]
	s_waitcnt vmcnt(0)
	s_waitcnt lgkmcnt(2)
; __device__ __forceinline__ bf16_t f2bf(float f) { return (bf16_t)(cvt_pk_bf16(f, f) & 0xffffu); }
; __device__ __forceinline__ int crow(int r, int hi) { return (r & 3) + 8 * (r >> 2) + 4 * hi; }
; __device__ __forceinline__ void sg_item(int l, int chunk, LAS unsigned char* lds, const bf16_t* UB, const bf16_t* V2T, bf16_t* YC1, const bf16_t* Wb,
;                                         const float* sg_ln_g, const float* sg_ln_b, const float* sg_b, int lane, int wave) {
;     ...
; #pragma unroll
;         for (int i = 0; i < 4; ++i) {
; #pragma unroll
;             for (int kb = 0; kb < 2 * i + 2; kb += 4) {
;                 u32x4 af[4]; const void* pp[4];
; #pragma unroll
;                 for (int j = 0; j < 4; ++j) pp[j] = Wg + (size_t)(32 * i) * 128 + 16 * ((kb + j) < 2 * i + 2 ? (kb + j) : 0);
;                 ld_b128_s4(af, avoff, pp);
; #pragma unroll
;                 for (int j = 0; j < 4; ++j) if (kb + j < 2 * i + 2) acc[i] = __builtin_amdgcn_mfma_f32_32x32x16_bf16(__builtin_bit_cast(bf16x8, af[j]), Bf[kb + j], acc[i], 0, 0, 0);
;             }
;         }
;         const float sb_lo = sg_b[(l * 4 + g) * 128 + lane], sb_hi = sg_b[(l * 4 + g) * 128 + 64 + lane];
;         const unsigned uvoff = (unsigned)(4 * hi * BW + c) * 2u;
; #pragma unroll
;         for (int i = 0; i < 4; ++i) {
;             unsigned uu[16];
; #pragma unroll
;             for (int rb = 0; rb < 16; rb += 8) {
;                 unsigned raw[8]; const void* pp[8];
; #pragma unroll
;                 for (int j = 0; j < 8; ++j) pp[j] = UB + (r0 + 32 * i + crow(rb + j, 0)) * BW;
;                 ld_u16_s8(raw, uvoff, pp);
; #pragma unroll
;                 for (int j = 0; j < 8; ++j) uu[rb + j] = raw[j];
;             }
; #pragma unroll
;             for (int r = 0; r < 16; ++r) {
;                 const int t = 32 * i + crow(r, hi);
;                 const float sbv = __int_as_float(__builtin_amdgcn_ds_bpermute((t & 63) << 2, __float_as_int(i < 2 ? sb_lo : sb_hi)));
;                 YC1[(r0 + t) * BW + c] = f2bf(__uint_as_float(uu[r] << 16) * (acc[i][r] + sbv));
	v_mfma_f32_32x32x16_bf16 v[16:31], v[8:11], v[88:91], v[16:31]
	v_mfma_f32_32x32x16_bf16 v[0:15], v[4:7], v[0:3], 0
	v_mfma_f32_32x32x16_bf16 v[0:15], v[100:103], v[72:75], v[0:15]
	v_mfma_f32_32x32x16_bf16 v[0:15], v[104:107], v[76:79], v[0:15]
	v_mfma_f32_32x32x16_bf16 v[0:15], v[108:111], v[80:83], v[0:15]
	s_nop 4
	global_load_dwordx4 v[72:75], v203, s[72:73]
	global_load_dwordx4 v[76:79], v203, s[74:75]
	global_load_dwordx4 v[80:83], v203, s[76:77]
	global_load_dwordx4 v[100:103], v203, s[78:79]
	s_waitcnt vmcnt(0)
	s_nop 0
	v_mfma_f32_32x32x16_bf16 v[0:15], v[72:75], v[84:87], v[0:15]
	global_load_dword v75, v[68:69], off
	global_load_dword v74, v[68:69], off offset:256
	s_waitcnt vmcnt(1)
	ds_bpermute_b32 v73, v200, v75
	v_mfma_f32_32x32x16_bf16 v[0:15], v[76:79], v[88:91], v[0:15]
	s_waitcnt lgkmcnt(0)
	v_add_f32_e32 v48, v48, v73
	v_mfma_f32_32x32x16_bf16 v[0:15], v[80:83], v[92:95], v[0:15]
	s_waitcnt vmcnt(0)
	v_mov_b32_e32 v72, v112
	v_mov_b32_e32 v90, v113
	v_mov_b32_e32 v89, v114
	v_mov_b32_e32 v88, v115
	v_mov_b32_e32 v87, v116
	v_mov_b32_e32 v86, v117
	v_mov_b32_e32 v84, v118
	v_mov_b32_e32 v83, v119
	s_add_u32 s48, s0, 0x2000
	s_addc_u32 s49, s1, 0
	s_add_u32 s50, s0, 0x2200
	s_addc_u32 s51, s1, 0
	s_add_u32 s52, s0, 0x2400
	s_addc_u32 s53, s1, 0
	s_add_u32 s54, s0, 0x2600
	s_addc_u32 s55, s1, 0
	s_add_u32 s56, s0, 0x3000
	s_addc_u32 s57, s1, 0
	s_add_u32 s58, s0, 0x3200
	v_lshlrev_b32_e32 v72, 16, v72
	s_addc_u32 s59, s1, 0
	v_mul_f32_e32 v48, v48, v72
	v_lshl_add_u64 v[72:73], v[70:71], 0, s[80:81]
	s_add_u32 s60, s0, 0x3400
	v_add_co_u32_e32 v92, vcc, s12, v72
	s_addc_u32 s61, s1, 0
	s_nop 0
	v_addc_co_u32_e32 v93, vcc, 0, v73, vcc
	s_mov_b32 s12, 0xb401000
	s_add_u32 s62, s0, 0x3600
	v_add_co_u32_e32 v94, vcc, s12, v72
	s_addc_u32 s63, s1, 0
	s_waitcnt vmcnt(0)
	v_mov_b32_e32 v85, v120
	v_mov_b32_e32 v82, v121
	v_mov_b32_e32 v81, v122
	v_mov_b32_e32 v80, v123
	v_mov_b32_e32 v79, v124
	v_mov_b32_e32 v78, v125
	v_mov_b32_e32 v77, v126
	v_mov_b32_e32 v76, v127
	s_add_u32 s98, s98, 0xa00
	s_addc_u32 s99, s99, 0
	global_load_ushort v112, v152, s[98:99]
	s_add_u32 s98, s98, 0x200
	s_addc_u32 s99, s99, 0
	global_load_ushort v113, v152, s[98:99]
	s_add_u32 s98, s98, 0x200
	s_addc_u32 s99, s99, 0
	global_load_ushort v114, v152, s[98:99]
	s_add_u32 s98, s98, 0x200
	s_addc_u32 s99, s99, 0
	global_load_ushort v115, v152, s[98:99]
	s_add_u32 s98, s98, 0xa00
	s_addc_u32 s99, s99, 0
	global_load_ushort v116, v152, s[98:99]
	s_add_u32 s98, s98, 0x200
	s_addc_u32 s99, s99, 0
	global_load_ushort v117, v152, s[98:99]
	s_add_u32 s98, s98, 0x200
	s_addc_u32 s99, s99, 0
	global_load_ushort v118, v152, s[98:99]
	s_add_u32 s98, s98, 0x200
	s_addc_u32 s99, s99, 0
	global_load_ushort v119, v152, s[98:99]
	s_add_u32 s98, s98, 0xa00
	s_addc_u32 s99, s99, 0
	global_load_ushort v120, v152, s[98:99]
	s_add_u32 s98, s98, 0x200
	s_addc_u32 s99, s99, 0
	global_load_ushort v121, v152, s[98:99]
	s_add_u32 s98, s98, 0x200
	s_addc_u32 s99, s99, 0
	global_load_ushort v122, v152, s[98:99]
	s_add_u32 s98, s98, 0x200
	s_addc_u32 s99, s99, 0
	global_load_ushort v123, v152, s[98:99]
	s_add_u32 s98, s98, 0xa00
	s_addc_u32 s99, s99, 0
	global_load_ushort v124, v152, s[98:99]
	s_add_u32 s98, s98, 0x200
	s_addc_u32 s99, s99, 0
	global_load_ushort v125, v152, s[98:99]
	s_add_u32 s98, s98, 0x200
	s_addc_u32 s99, s99, 0
	global_load_ushort v126, v152, s[98:99]
	s_add_u32 s98, s98, 0x200
	s_addc_u32 s99, s99, 0
	global_load_ushort v127, v152, s[98:99]
	v_cvt_pk_bf16_f32 v48, v48, v48
	s_nop 0
	v_addc_co_u32_e32 v95, vcc, 0, v73, vcc
	global_store_short v[94:95], v48, off offset:-4096
	ds_bpermute_b32 v48, v204, v75
	v_lshlrev_b32_e32 v90, 16, v90
	s_mov_b32 s12, 0xb402000
	s_add_u32 s48, s0, 0x4000
	s_addc_u32 s49, s1, 0
	s_waitcnt lgkmcnt(0)
	v_add_f32_e32 v48, v49, v48
	v_mul_f32_e32 v48, v48, v90
	v_cvt_pk_bf16_f32 v48, v48, v48
	global_store_short v[92:93], v48, off offset:512
	ds_bpermute_b32 v48, v205, v75
	v_lshlrev_b32_e32 v49, 16, v89
	s_add_u32 s50, s0, 0x4200
	s_addc_u32 s51, s1, 0
	s_add_u32 s52, s0, 0x4400
	s_waitcnt lgkmcnt(0)
	v_add_f32_e32 v48, v50, v48
	v_mul_f32_e32 v48, v48, v49
	v_cvt_pk_bf16_f32 v48, v48, v48
	global_store_short v[92:93], v48, off offset:1024
	ds_bpermute_b32 v48, v206, v75
	v_lshlrev_b32_e32 v49, 16, v88
	s_addc_u32 s53, s1, 0
	s_add_u32 s54, s0, 0x4600
	s_addc_u32 s55, s1, 0
	s_waitcnt lgkmcnt(0)
	v_add_f32_e32 v48, v51, v48
	v_mul_f32_e32 v48, v48, v49
	v_cvt_pk_bf16_f32 v48, v48, v48
	global_store_short v[92:93], v48, off offset:1536
	ds_bpermute_b32 v48, v207, v75
	v_lshlrev_b32_e32 v49, 16, v87
	s_add_u32 s56, s0, 0x5000
	s_addc_u32 s57, s1, 0
	s_add_u32 s58, s0, 0x5200
	s_waitcnt lgkmcnt(0)
	v_add_f32_e32 v48, v52, v48
	v_mul_f32_e32 v48, v48, v49
	v_cvt_pk_bf16_f32 v48, v48, v48
	global_store_short v[94:95], v48, off
	ds_bpermute_b32 v48, v208, v75
	v_lshlrev_b32_e32 v49, 16, v86
	s_addc_u32 s59, s1, 0
	s_add_u32 s60, s0, 0x5400
	s_addc_u32 s61, s1, 0
	s_waitcnt lgkmcnt(0)
	v_add_f32_e32 v48, v53, v48
	v_mul_f32_e32 v48, v48, v49
	v_cvt_pk_bf16_f32 v48, v48, v48
	global_store_short v[94:95], v48, off offset:512
	ds_bpermute_b32 v48, v209, v75
	v_lshlrev_b32_e32 v49, 16, v84
	v_lshlrev_b32_e32 v53, 16, v82
	s_add_u32 s62, s0, 0x5600
	s_addc_u32 s63, s1, 0
	s_waitcnt lgkmcnt(0)
	v_add_f32_e32 v48, v54, v48
	v_mul_f32_e32 v48, v48, v49
	v_cvt_pk_bf16_f32 v48, v48, v48
	global_store_short v[94:95], v48, off offset:1024
	ds_bpermute_b32 v48, v210, v75
	v_lshlrev_b32_e32 v49, 16, v83
	v_mfma_f32_32x32x16_bf16 v[0:15], v[100:103], v[96:99], v[0:15]
	v_lshl_add_u64 v[70:71], v[70:71], 0, s[82:83]
	s_waitcnt lgkmcnt(0)
; __device__ __forceinline__ bf16_t f2bf(float f) { return (bf16_t)(cvt_pk_bf16(f, f) & 0xffffu); }
; __device__ __forceinline__ int crow(int r, int hi) { return (r & 3) + 8 * (r >> 2) + 4 * hi; }
; __device__ __forceinline__ void sg_item(int l, int chunk, LAS unsigned char* lds, const bf16_t* UB, const bf16_t* V2T, bf16_t* YC1, const bf16_t* Wb,
;                                         const float* sg_ln_g, const float* sg_ln_b, const float* sg_b, int lane, int wave) {
;     ...
; #pragma unroll
;         for (int i = 0; i < 4; ++i) {
;             unsigned uu[16];
; #pragma unroll
;             for (int rb = 0; rb < 16; rb += 8) {
;                 unsigned raw[8]; const void* pp[8];
; #pragma unroll
;                 for (int j = 0; j < 8; ++j) pp[j] = UB + (r0 + 32 * i + crow(rb + j, 0)) * BW;
;                 ld_u16_s8(raw, uvoff, pp);
; #pragma unroll
;                 for (int j = 0; j < 8; ++j) uu[rb + j] = raw[j];
;             }
; #pragma unroll
;             for (int r = 0; r < 16; ++r) {
;                 const int t = 32 * i + crow(r, hi);
;                 const float sbv = __int_as_float(__builtin_amdgcn_ds_bpermute((t & 63) << 2, __float_as_int(i < 2 ? sb_lo : sb_hi)));
;                 YC1[(r0 + t) * BW + c] = f2bf(__uint_as_float(uu[r] << 16) * (acc[i][r] + sbv));
	v_add_f32_e32 v48, v55, v48
	v_mul_f32_e32 v48, v48, v49
	v_cvt_pk_bf16_f32 v48, v48, v48
	global_store_short v[94:95], v48, off offset:1536
	ds_bpermute_b32 v48, v211, v75
	v_lshlrev_b32_e32 v49, 16, v85
	s_waitcnt lgkmcnt(0)
	v_add_f32_e32 v48, v56, v48
	v_mul_f32_e32 v48, v48, v49
	v_cvt_pk_bf16_f32 v52, v48, v48
	v_add_co_u32_e32 v48, vcc, s12, v72
	s_mov_b32 s12, 0xb403000
	s_nop 0
	v_addc_co_u32_e32 v49, vcc, 0, v73, vcc
	v_add_co_u32_e32 v50, vcc, s12, v72
	s_mov_b32 s12, 0xb404000
	s_nop 0
	v_addc_co_u32_e32 v51, vcc, 0, v73, vcc
	global_store_short v[50:51], v52, off offset:-4096
	ds_bpermute_b32 v52, v212, v75
	s_waitcnt lgkmcnt(0)
	v_add_f32_e32 v52, v57, v52
	v_mul_f32_e32 v52, v52, v53
	v_cvt_pk_bf16_f32 v52, v52, v52
	global_store_short v[48:49], v52, off offset:512
	ds_bpermute_b32 v52, v213, v75
	v_lshlrev_b32_e32 v53, 16, v81
	s_waitcnt lgkmcnt(0)
	v_add_f32_e32 v52, v58, v52
	v_mul_f32_e32 v52, v52, v53
	v_cvt_pk_bf16_f32 v52, v52, v52
	global_store_short v[48:49], v52, off offset:1024
	ds_bpermute_b32 v52, v214, v75
	v_lshlrev_b32_e32 v53, 16, v80
	s_waitcnt lgkmcnt(0)
	v_add_f32_e32 v52, v59, v52
	v_mul_f32_e32 v52, v52, v53
	v_cvt_pk_bf16_f32 v52, v52, v52
	global_store_short v[48:49], v52, off offset:1536
	ds_bpermute_b32 v48, v215, v75
	v_lshlrev_b32_e32 v49, 16, v79
	s_waitcnt lgkmcnt(0)
	v_add_f32_e32 v48, v60, v48
	v_mul_f32_e32 v48, v48, v49
	v_cvt_pk_bf16_f32 v48, v48, v48
	global_store_short v[50:51], v48, off
	ds_bpermute_b32 v48, v216, v75
	v_lshlrev_b32_e32 v49, 16, v78
	s_waitcnt lgkmcnt(0)
	v_add_f32_e32 v48, v61, v48
	v_mul_f32_e32 v48, v48, v49
	v_cvt_pk_bf16_f32 v48, v48, v48
	global_store_short v[50:51], v48, off offset:512
	ds_bpermute_b32 v48, v217, v75
	v_lshlrev_b32_e32 v49, 16, v77
	s_waitcnt lgkmcnt(0)
	v_add_f32_e32 v48, v62, v48
	v_mul_f32_e32 v48, v48, v49
	v_cvt_pk_bf16_f32 v48, v48, v48
	global_store_short v[50:51], v48, off offset:1024
	ds_bpermute_b32 v48, v218, v75
	v_lshlrev_b32_e32 v49, 16, v76
	ds_bpermute_b32 v76, v153, v75
	s_waitcnt lgkmcnt(1)
	v_add_f32_e32 v48, v63, v48
	v_mul_f32_e32 v48, v48, v49
	v_cvt_pk_bf16_f32 v48, v48, v48
	global_store_short v[50:51], v48, off offset:1536
	s_waitcnt vmcnt(63)
	v_mov_b32_e32 v63, v128
	v_mov_b32_e32 v62, v129
	v_mov_b32_e32 v61, v130
	v_mov_b32_e32 v60, v131
	v_mov_b32_e32 v59, v132
	v_mov_b32_e32 v58, v133
	v_mov_b32_e32 v56, v220
	v_mov_b32_e32 v55, v221
	s_add_u32 s48, s0, 0x6000
	s_addc_u32 s49, s1, 0
	s_add_u32 s50, s0, 0x6200
	s_addc_u32 s51, s1, 0
	s_add_u32 s52, s0, 0x6400
	s_addc_u32 s53, s1, 0
	s_add_u32 s54, s0, 0x6600
	s_addc_u32 s55, s1, 0
	s_add_u32 s56, s0, 0x7000
	s_addc_u32 s57, s1, 0
	s_add_u32 s58, s0, 0x7200
	s_addc_u32 s59, s1, 0
	s_add_u32 s60, s0, 0x7400
	s_waitcnt lgkmcnt(0)
	v_add_f32_e32 v32, v32, v76
	v_add_co_u32_e32 v76, vcc, s12, v72
	s_addc_u32 s61, s1, 0
	v_lshlrev_b32_e32 v63, 16, v63
	v_addc_co_u32_e32 v77, vcc, 0, v73, vcc
	s_mov_b32 s12, 0xb405000
	s_add_u32 s62, s0, 0x7600
	v_mul_f32_e32 v32, v32, v63
	v_add_co_u32_e32 v78, vcc, s12, v72
	s_addc_u32 s63, s1, 0
	s_waitcnt vmcnt(58)
	v_mov_b32_e32 v57, v222
	v_mov_b32_e32 v54, v223
	v_mov_b32_e32 v53, v224
	v_mov_b32_e32 v52, v225
	v_mov_b32_e32 v51, v226
	v_mov_b32_e32 v50, v227
	v_mov_b32_e32 v49, v228
	v_mov_b32_e32 v48, v229
	s_add_u32 s98, s98, 0xa00
	s_addc_u32 s99, s99, 0
	global_load_ushort v128, v152, s[98:99]
	s_add_u32 s98, s98, 0x200
	s_addc_u32 s99, s99, 0
	global_load_ushort v129, v152, s[98:99]
	s_add_u32 s98, s98, 0x200
	s_addc_u32 s99, s99, 0
	global_load_ushort v130, v152, s[98:99]
	s_add_u32 s98, s98, 0x200
	s_addc_u32 s99, s99, 0
	global_load_ushort v131, v152, s[98:99]
	s_add_u32 s98, s98, 0xa00
	s_addc_u32 s99, s99, 0
	global_load_ushort v132, v152, s[98:99]
	s_add_u32 s98, s98, 0x200
	s_addc_u32 s99, s99, 0
	global_load_ushort v133, v152, s[98:99]
	s_add_u32 s98, s98, 0x200
	s_addc_u32 s99, s99, 0
	global_load_ushort v220, v152, s[98:99]
	s_add_u32 s98, s98, 0x200
	s_addc_u32 s99, s99, 0
	global_load_ushort v221, v152, s[98:99]
	s_add_u32 s98, s98, 0xa00
	s_addc_u32 s99, s99, 0
	global_load_ushort v222, v152, s[98:99]
	s_add_u32 s98, s98, 0x200
	s_addc_u32 s99, s99, 0
	global_load_ushort v223, v152, s[98:99]
	s_add_u32 s98, s98, 0x200
	s_addc_u32 s99, s99, 0
	global_load_ushort v224, v152, s[98:99]
	s_add_u32 s98, s98, 0x200
	s_addc_u32 s99, s99, 0
	global_load_ushort v225, v152, s[98:99]
	s_add_u32 s98, s98, 0xa00
	s_addc_u32 s99, s99, 0
	global_load_ushort v226, v152, s[98:99]
	s_add_u32 s98, s98, 0x200
	s_addc_u32 s99, s99, 0
	global_load_ushort v227, v152, s[98:99]
	s_add_u32 s98, s98, 0x200
	s_addc_u32 s99, s99, 0
	global_load_ushort v228, v152, s[98:99]
	s_add_u32 s98, s98, 0x200
	s_addc_u32 s99, s99, 0
	global_load_ushort v229, v152, s[98:99]
	v_cvt_pk_bf16_f32 v32, v32, v32
	s_nop 0
	v_addc_co_u32_e32 v79, vcc, 0, v73, vcc
	global_store_short v[78:79], v32, off offset:-4096
	ds_bpermute_b32 v32, v154, v75
	v_lshlrev_b32_e32 v62, 16, v62
	s_mov_b32 s12, 0xb406000
	s_add_u32 s48, s0, 0x8000
	s_addc_u32 s49, s1, 0
	s_waitcnt lgkmcnt(0)
	v_add_f32_e32 v32, v33, v32
	v_mul_f32_e32 v32, v32, v62
	v_cvt_pk_bf16_f32 v32, v32, v32
	global_store_short v[76:77], v32, off offset:512
	ds_bpermute_b32 v32, v155, v75
	v_lshlrev_b32_e32 v33, 16, v61
	s_add_u32 s50, s0, 0x8200
	s_addc_u32 s51, s1, 0
	s_add_u32 s52, s0, 0x8400
	s_waitcnt lgkmcnt(0)
	v_add_f32_e32 v32, v34, v32
	v_mul_f32_e32 v32, v32, v33
	v_cvt_pk_bf16_f32 v32, v32, v32
	global_store_short v[76:77], v32, off offset:1024
	ds_bpermute_b32 v32, v157, v75
	v_lshlrev_b32_e32 v33, 16, v60
	s_addc_u32 s53, s1, 0
	s_add_u32 s54, s0, 0x8600
	s_addc_u32 s55, s1, 0
	s_waitcnt lgkmcnt(0)
; __device__ __forceinline__ bf16_t f2bf(float f) { return (bf16_t)(cvt_pk_bf16(f, f) & 0xffffu); }
; __device__ __forceinline__ int crow(int r, int hi) { return (r & 3) + 8 * (r >> 2) + 4 * hi; }
; __device__ __forceinline__ void sg_item(int l, int chunk, LAS unsigned char* lds, const bf16_t* UB, const bf16_t* V2T, bf16_t* YC1, const bf16_t* Wb,
;                                         const float* sg_ln_g, const float* sg_ln_b, const float* sg_b, int lane, int wave) {
;     ...
; #pragma unroll
;         for (int i = 0; i < 4; ++i) {
;             unsigned uu[16];
; #pragma unroll
;             for (int rb = 0; rb < 16; rb += 8) {
;                 unsigned raw[8]; const void* pp[8];
; #pragma unroll
;                 for (int j = 0; j < 8; ++j) pp[j] = UB + (r0 + 32 * i + crow(rb + j, 0)) * BW;
;                 ld_u16_s8(raw, uvoff, pp);
; #pragma unroll
;                 for (int j = 0; j < 8; ++j) uu[rb + j] = raw[j];
;             }
; #pragma unroll
;             for (int r = 0; r < 16; ++r) {
;                 const int t = 32 * i + crow(r, hi);
;                 const float sbv = __int_as_float(__builtin_amdgcn_ds_bpermute((t & 63) << 2, __float_as_int(i < 2 ? sb_lo : sb_hi)));
;                 YC1[(r0 + t) * BW + c] = f2bf(__uint_as_float(uu[r] << 16) * (acc[i][r] + sbv));
	v_add_f32_e32 v32, v35, v32
	v_mul_f32_e32 v32, v32, v33
	v_cvt_pk_bf16_f32 v32, v32, v32
	global_store_short v[76:77], v32, off offset:1536
	ds_bpermute_b32 v32, v161, v75
	v_lshlrev_b32_e32 v33, 16, v59
	s_add_u32 s56, s0, 0x9000
	s_addc_u32 s57, s1, 0
	s_add_u32 s58, s0, 0x9200
	s_waitcnt lgkmcnt(0)
	v_add_f32_e32 v32, v36, v32
	v_mul_f32_e32 v32, v32, v33
	v_cvt_pk_bf16_f32 v32, v32, v32
	global_store_short v[78:79], v32, off
	ds_bpermute_b32 v32, v162, v75
	v_lshlrev_b32_e32 v33, 16, v58
	s_addc_u32 s59, s1, 0
	s_add_u32 s60, s0, 0x9400
	s_addc_u32 s61, s1, 0
	s_waitcnt lgkmcnt(0)
	v_add_f32_e32 v32, v37, v32
	v_mul_f32_e32 v32, v32, v33
	v_cvt_pk_bf16_f32 v32, v32, v32
	global_store_short v[78:79], v32, off offset:512
	ds_bpermute_b32 v32, v163, v75
	v_lshlrev_b32_e32 v33, 16, v56
	v_lshlrev_b32_e32 v37, 16, v54
	s_add_u32 s62, s0, 0x9600
	s_addc_u32 s63, s1, 0
	s_waitcnt lgkmcnt(0)
	v_add_f32_e32 v32, v38, v32
	v_mul_f32_e32 v32, v32, v33
	v_cvt_pk_bf16_f32 v32, v32, v32
	global_store_short v[78:79], v32, off offset:1024
	ds_bpermute_b32 v32, v164, v75
	v_lshlrev_b32_e32 v33, 16, v55
	s_waitcnt lgkmcnt(0)
	v_add_f32_e32 v32, v39, v32
	v_mul_f32_e32 v32, v32, v33
	v_cvt_pk_bf16_f32 v32, v32, v32
	global_store_short v[78:79], v32, off offset:1536
	ds_bpermute_b32 v32, v165, v75
	v_lshlrev_b32_e32 v33, 16, v57
	s_waitcnt lgkmcnt(0)
	v_add_f32_e32 v32, v40, v32
	v_mul_f32_e32 v32, v32, v33
	v_cvt_pk_bf16_f32 v36, v32, v32
	v_add_co_u32_e32 v32, vcc, s12, v72
	s_mov_b32 s12, 0xb407000
	s_nop 0
	v_addc_co_u32_e32 v33, vcc, 0, v73, vcc
	v_add_co_u32_e32 v34, vcc, s12, v72
	s_mov_b32 s12, 0xb408000
	s_nop 0
	v_addc_co_u32_e32 v35, vcc, 0, v73, vcc
	global_store_short v[34:35], v36, off offset:-4096
	ds_bpermute_b32 v36, v166, v75
	s_waitcnt lgkmcnt(0)
	v_add_f32_e32 v36, v41, v36
	v_mul_f32_e32 v36, v36, v37
	v_cvt_pk_bf16_f32 v36, v36, v36
	global_store_short v[32:33], v36, off offset:512
	ds_bpermute_b32 v36, v167, v75
	v_lshlrev_b32_e32 v37, 16, v53
	s_waitcnt lgkmcnt(0)
	v_add_f32_e32 v36, v42, v36
	v_mul_f32_e32 v36, v36, v37
	v_cvt_pk_bf16_f32 v36, v36, v36
	global_store_short v[32:33], v36, off offset:1024
	ds_bpermute_b32 v36, v168, v75
	v_lshlrev_b32_e32 v37, 16, v52
	s_waitcnt lgkmcnt(0)
	v_add_f32_e32 v36, v43, v36
	v_mul_f32_e32 v36, v36, v37
	v_cvt_pk_bf16_f32 v36, v36, v36
	global_store_short v[32:33], v36, off offset:1536
	ds_bpermute_b32 v32, v169, v75
	v_lshlrev_b32_e32 v33, 16, v51
	s_waitcnt lgkmcnt(0)
	v_add_f32_e32 v32, v44, v32
	v_mul_f32_e32 v32, v32, v33
	v_cvt_pk_bf16_f32 v32, v32, v32
	global_store_short v[34:35], v32, off
	ds_bpermute_b32 v32, v170, v75
	v_lshlrev_b32_e32 v33, 16, v50
	s_waitcnt lgkmcnt(0)
	v_add_f32_e32 v32, v45, v32
	v_mul_f32_e32 v32, v32, v33
	v_cvt_pk_bf16_f32 v32, v32, v32
	global_store_short v[34:35], v32, off offset:512
	ds_bpermute_b32 v32, v171, v75
	v_lshlrev_b32_e32 v33, 16, v49
	s_waitcnt lgkmcnt(0)
	v_add_f32_e32 v32, v46, v32
	v_mul_f32_e32 v32, v32, v33
	v_cvt_pk_bf16_f32 v32, v32, v32
	global_store_short v[34:35], v32, off offset:1024
	ds_bpermute_b32 v32, v172, v75
	v_lshlrev_b32_e32 v33, 16, v48
	s_waitcnt vmcnt(31)
	ds_bpermute_b32 v48, v200, v74
	s_waitcnt lgkmcnt(1)
	v_add_f32_e32 v32, v47, v32
	v_mul_f32_e32 v32, v32, v33
	v_cvt_pk_bf16_f32 v32, v32, v32
	global_store_short v[34:35], v32, off offset:1536
	s_waitcnt vmcnt(56)
	v_mov_b32_e32 v47, v112
	v_mov_b32_e32 v46, v113
	v_mov_b32_e32 v45, v114
	v_mov_b32_e32 v44, v115
	v_mov_b32_e32 v43, v116
	v_mov_b32_e32 v42, v117
	v_mov_b32_e32 v40, v118
	v_mov_b32_e32 v39, v119
	s_add_u32 s48, s0, 0xa000
	s_addc_u32 s49, s1, 0
	s_add_u32 s50, s0, 0xa200
	s_addc_u32 s51, s1, 0
	s_add_u32 s52, s0, 0xa400
	s_addc_u32 s53, s1, 0
	s_add_u32 s54, s0, 0xa600
	s_addc_u32 s55, s1, 0
	s_add_u32 s56, s0, 0xb000
	s_addc_u32 s57, s1, 0
	s_add_u32 s58, s0, 0xb200
	s_addc_u32 s59, s1, 0
	s_add_u32 s60, s0, 0xb400
	s_waitcnt lgkmcnt(0)
	v_add_f32_e32 v16, v16, v48
	v_add_co_u32_e32 v48, vcc, s12, v72
	s_addc_u32 s61, s1, 0
	v_lshlrev_b32_e32 v47, 16, v47
	v_addc_co_u32_e32 v49, vcc, 0, v73, vcc
	s_mov_b32 s12, 0xb409000
	s_add_u32 s62, s0, 0xb600
	v_mul_f32_e32 v16, v16, v47
	v_add_co_u32_e32 v50, vcc, s12, v72
	s_addc_u32 s63, s1, 0
	s_waitcnt vmcnt(48)
	v_mov_b32_e32 v41, v120
	v_mov_b32_e32 v38, v121
	v_mov_b32_e32 v37, v122
	v_mov_b32_e32 v36, v123
	v_mov_b32_e32 v35, v124
	v_mov_b32_e32 v34, v125
	v_mov_b32_e32 v33, v126
	v_mov_b32_e32 v32, v127
	v_cvt_pk_bf16_f32 v16, v16, v16
	s_nop 0
	v_addc_co_u32_e32 v51, vcc, 0, v73, vcc
	global_store_short v[50:51], v16, off offset:-4096
	ds_bpermute_b32 v16, v173, v74
	v_lshlrev_b32_e32 v46, 16, v46
	s_mov_b32 s12, 0xb40a000
	s_add_u32 s48, s0, 0xc000
	s_addc_u32 s49, s1, 0
	s_waitcnt lgkmcnt(0)
	v_add_f32_e32 v16, v17, v16
	v_mul_f32_e32 v16, v16, v46
	v_cvt_pk_bf16_f32 v16, v16, v16
	global_store_short v[48:49], v16, off offset:512
	ds_bpermute_b32 v16, v174, v74
	v_lshlrev_b32_e32 v17, 16, v45
	s_add_u32 s50, s0, 0xc200
	s_addc_u32 s51, s1, 0
	s_add_u32 s52, s0, 0xc400
	s_waitcnt lgkmcnt(0)
	v_add_f32_e32 v16, v18, v16
	v_mul_f32_e32 v16, v16, v17
	v_cvt_pk_bf16_f32 v16, v16, v16
	global_store_short v[48:49], v16, off offset:1024
	ds_bpermute_b32 v16, v175, v74
	v_lshlrev_b32_e32 v17, 16, v44
	s_addc_u32 s53, s1, 0
	s_add_u32 s54, s0, 0xc600
	s_addc_u32 s55, s1, 0
	s_waitcnt lgkmcnt(0)
	v_add_f32_e32 v16, v19, v16
	v_mul_f32_e32 v16, v16, v17
	v_cvt_pk_bf16_f32 v16, v16, v16
	global_store_short v[48:49], v16, off offset:1536
	ds_bpermute_b32 v16, v176, v74
	v_lshlrev_b32_e32 v17, 16, v43
	s_add_u32 s56, s0, 0xd000
	s_addc_u32 s57, s1, 0
	s_add_u32 s58, s0, 0xd200
	s_waitcnt lgkmcnt(0)
; __device__ __forceinline__ bf16_t f2bf(float f) { return (bf16_t)(cvt_pk_bf16(f, f) & 0xffffu); }
; __device__ __forceinline__ int crow(int r, int hi) { return (r & 3) + 8 * (r >> 2) + 4 * hi; }
; __device__ __forceinline__ void sg_item(int l, int chunk, LAS unsigned char* lds, const bf16_t* UB, const bf16_t* V2T, bf16_t* YC1, const bf16_t* Wb,
;                                         const float* sg_ln_g, const float* sg_ln_b, const float* sg_b, int lane, int wave) {
;     ...
;             for (int rb = 0; rb < 16; rb += 8) {
;                 unsigned raw[8]; const void* pp[8];
; #pragma unroll
;                 for (int j = 0; j < 8; ++j) pp[j] = UB + (r0 + 32 * i + crow(rb + j, 0)) * BW;
;                 ld_u16_s8(raw, uvoff, pp);
; #pragma unroll
;                 for (int j = 0; j < 8; ++j) uu[rb + j] = raw[j];
;             }
; #pragma unroll
;             for (int r = 0; r < 16; ++r) {
;                 const int t = 32 * i + crow(r, hi);
;                 const float sbv = __int_as_float(__builtin_amdgcn_ds_bpermute((t & 63) << 2, __float_as_int(i < 2 ? sb_lo : sb_hi)));
;                 YC1[(r0 + t) * BW + c] = f2bf(__uint_as_float(uu[r] << 16) * (acc[i][r] + sbv));
	v_add_f32_e32 v16, v20, v16
	v_mul_f32_e32 v16, v16, v17
	v_cvt_pk_bf16_f32 v16, v16, v16
	global_store_short v[50:51], v16, off
	ds_bpermute_b32 v16, v177, v74
	v_lshlrev_b32_e32 v17, 16, v42
	s_addc_u32 s59, s1, 0
	s_add_u32 s60, s0, 0xd400
	s_addc_u32 s61, s1, 0
	s_waitcnt lgkmcnt(0)
	v_add_f32_e32 v16, v21, v16
	v_mul_f32_e32 v16, v16, v17
	v_cvt_pk_bf16_f32 v16, v16, v16
	global_store_short v[50:51], v16, off offset:512
	ds_bpermute_b32 v16, v178, v74
	v_lshlrev_b32_e32 v17, 16, v40
	v_lshlrev_b32_e32 v21, 16, v38
	s_add_u32 s62, s0, 0xd600
	s_addc_u32 s63, s1, 0
	s_waitcnt lgkmcnt(0)
	v_add_f32_e32 v16, v22, v16
	v_mul_f32_e32 v16, v16, v17
	v_cvt_pk_bf16_f32 v16, v16, v16
	global_store_short v[50:51], v16, off offset:1024
	ds_bpermute_b32 v16, v179, v74
	v_lshlrev_b32_e32 v17, 16, v39
	s_waitcnt lgkmcnt(0)
	v_add_f32_e32 v16, v23, v16
	v_mul_f32_e32 v16, v16, v17
	v_cvt_pk_bf16_f32 v16, v16, v16
	global_store_short v[50:51], v16, off offset:1536
	ds_bpermute_b32 v16, v180, v74
	v_lshlrev_b32_e32 v17, 16, v41
	s_waitcnt lgkmcnt(0)
	v_add_f32_e32 v16, v24, v16
	v_mul_f32_e32 v16, v16, v17
	v_cvt_pk_bf16_f32 v20, v16, v16
	v_add_co_u32_e32 v16, vcc, s12, v72
	s_mov_b32 s12, 0xb40b000
	s_nop 0
	v_addc_co_u32_e32 v17, vcc, 0, v73, vcc
	v_add_co_u32_e32 v18, vcc, s12, v72
	s_nop 1
	v_addc_co_u32_e32 v19, vcc, 0, v73, vcc
	global_store_short v[18:19], v20, off offset:-4096
	ds_bpermute_b32 v20, v181, v74
	s_waitcnt lgkmcnt(0)
	v_add_f32_e32 v20, v25, v20
	v_mul_f32_e32 v20, v20, v21
	v_cvt_pk_bf16_f32 v20, v20, v20
	global_store_short v[16:17], v20, off offset:512
	ds_bpermute_b32 v20, v182, v74
	v_lshlrev_b32_e32 v21, 16, v37
	s_waitcnt lgkmcnt(0)
	v_add_f32_e32 v20, v26, v20
	v_mul_f32_e32 v20, v20, v21
	v_cvt_pk_bf16_f32 v20, v20, v20
	global_store_short v[16:17], v20, off offset:1024
	ds_bpermute_b32 v20, v183, v74
	v_lshlrev_b32_e32 v21, 16, v36
	s_waitcnt lgkmcnt(0)
	v_add_f32_e32 v20, v27, v20
	v_mul_f32_e32 v20, v20, v21
	v_cvt_pk_bf16_f32 v20, v20, v20
	global_store_short v[16:17], v20, off offset:1536
	ds_bpermute_b32 v16, v184, v74
	v_lshlrev_b32_e32 v17, 16, v35
	s_waitcnt lgkmcnt(0)
	v_add_f32_e32 v16, v28, v16
	v_mul_f32_e32 v16, v16, v17
	v_cvt_pk_bf16_f32 v16, v16, v16
	global_store_short v[18:19], v16, off
	ds_bpermute_b32 v16, v185, v74
	v_lshlrev_b32_e32 v17, 16, v34
	s_waitcnt lgkmcnt(0)
	v_add_f32_e32 v16, v29, v16
	v_mul_f32_e32 v16, v16, v17
	v_cvt_pk_bf16_f32 v16, v16, v16
	global_store_short v[18:19], v16, off offset:512
	ds_bpermute_b32 v16, v186, v74
	v_lshlrev_b32_e32 v17, 16, v33
	s_waitcnt lgkmcnt(0)
	v_add_f32_e32 v16, v30, v16
	v_mul_f32_e32 v16, v16, v17
	v_cvt_pk_bf16_f32 v16, v16, v16
	global_store_short v[18:19], v16, off offset:1024
	ds_bpermute_b32 v16, v187, v74
	v_lshlrev_b32_e32 v17, 16, v32
	ds_bpermute_b32 v32, v188, v74
	s_waitcnt lgkmcnt(1)
	v_add_f32_e32 v16, v31, v16
	v_mul_f32_e32 v16, v16, v17
	v_cvt_pk_bf16_f32 v16, v16, v16
	global_store_short v[18:19], v16, off offset:1536
	s_waitcnt vmcnt(40)
	v_mov_b32_e32 v31, v128
	v_mov_b32_e32 v30, v129
	v_mov_b32_e32 v29, v130
	v_mov_b32_e32 v28, v131
	v_mov_b32_e32 v27, v132
	v_mov_b32_e32 v26, v133
	v_mov_b32_e32 v24, v220
	v_mov_b32_e32 v23, v221
	s_add_u32 s48, s0, 0xe000
	s_addc_u32 s49, s1, 0
	s_add_u32 s50, s0, 0xe200
	s_addc_u32 s51, s1, 0
	s_add_u32 s52, s0, 0xe400
	s_addc_u32 s53, s1, 0
	s_add_u32 s54, s0, 0xe600
	s_addc_u32 s55, s1, 0
	s_add_u32 s56, s0, 0xf000
	s_addc_u32 s57, s1, 0
	s_add_u32 s58, s0, 0xf200
	s_addc_u32 s59, s1, 0
	s_add_u32 s60, s0, 0xf400
	s_addc_u32 s61, s1, 0
	s_add_u32 s0, s0, 0xf600
	s_addc_u32 s1, s1, 0
	s_waitcnt vmcnt(32)
	v_mov_b32_e32 v25, v222
	v_mov_b32_e32 v22, v223
	v_mov_b32_e32 v21, v224
	v_mov_b32_e32 v20, v225
	v_mov_b32_e32 v19, v226
	v_mov_b32_e32 v18, v227
	v_mov_b32_e32 v17, v228
	v_mov_b32_e32 v16, v229
	s_mov_b32 s0, 0xb40c000
	s_waitcnt lgkmcnt(0)
; __device__ __forceinline__ bf16_t f2bf(float f) { return (bf16_t)(cvt_pk_bf16(f, f) & 0xffffu); }
; __device__ __forceinline__ int crow(int r, int hi) { return (r & 3) + 8 * (r >> 2) + 4 * hi; }
; __device__ __forceinline__ void sg_item(int l, int chunk, LAS unsigned char* lds, const bf16_t* UB, const bf16_t* V2T, bf16_t* YC1, const bf16_t* Wb,
;                                         const float* sg_ln_g, const float* sg_ln_b, const float* sg_b, int lane, int wave) {
;     ...
;             for (int r = 0; r < 16; ++r) {
;                 const int t = 32 * i + crow(r, hi);
;                 const float sbv = __int_as_float(__builtin_amdgcn_ds_bpermute((t & 63) << 2, __float_as_int(i < 2 ? sb_lo : sb_hi)));
;                 YC1[(r0 + t) * BW + c] = f2bf(__uint_as_float(uu[r] << 16) * (acc[i][r] + sbv));
;             }
;         }
;     }
;     __syncthreads();
	v_add_f32_e32 v0, v0, v32
	v_add_co_u32_e32 v32, vcc, s0, v72
	v_lshlrev_b32_e32 v31, 16, v31
	s_nop 0
	v_addc_co_u32_e32 v33, vcc, 0, v73, vcc
	s_mov_b32 s0, 0xb40d000
	v_mul_f32_e32 v0, v0, v31
	v_add_co_u32_e32 v34, vcc, s0, v72
	v_cvt_pk_bf16_f32 v0, v0, v0
	v_lshlrev_b32_e32 v30, 16, v30
	s_nop 0
	v_addc_co_u32_e32 v35, vcc, 0, v73, vcc
	global_store_short v[34:35], v0, off offset:-4096
	ds_bpermute_b32 v0, v189, v74
	s_mov_b32 s0, 0xb40e000
	s_add_i32 s13, s13, s96
	s_add_u32 s92, s92, s82
	s_addc_u32 s93, s93, s83
	s_waitcnt lgkmcnt(0)
	v_add_f32_e32 v0, v1, v0
	v_mul_f32_e32 v0, v0, v30
	v_cvt_pk_bf16_f32 v0, v0, v0
	global_store_short v[32:33], v0, off offset:512
	ds_bpermute_b32 v0, v190, v74
	v_lshlrev_b32_e32 v1, 16, v29
	s_add_u32 s4, s4, s82
	s_addc_u32 s5, s5, s83
	s_add_u32 s84, s84, s86
	s_waitcnt lgkmcnt(0)
	v_add_f32_e32 v0, v2, v0
	v_mul_f32_e32 v0, v0, v1
	v_cvt_pk_bf16_f32 v0, v0, v0
	global_store_short v[32:33], v0, off offset:1024
	ds_bpermute_b32 v0, v157, v74
	v_lshlrev_b32_e32 v1, 16, v28
	s_addc_u32 s85, s85, s87
	s_add_u32 s88, s88, s90
	s_addc_u32 s89, s89, s91
	s_waitcnt lgkmcnt(0)
	v_add_f32_e32 v0, v3, v0
	v_mul_f32_e32 v0, v0, v1
	v_cvt_pk_bf16_f32 v0, v0, v0
	global_store_short v[32:33], v0, off offset:1536
	ds_bpermute_b32 v0, v191, v74
	v_lshlrev_b32_e32 v1, 16, v27
	v_lshlrev_b32_e32 v3, 16, v22
	s_cmpk_gt_i32 s13, 0xff
	s_waitcnt lgkmcnt(0)
	v_add_f32_e32 v0, v4, v0
	v_mul_f32_e32 v0, v0, v1
	v_cvt_pk_bf16_f32 v0, v0, v0
	global_store_short v[34:35], v0, off
	ds_bpermute_b32 v0, v192, v74
	v_lshlrev_b32_e32 v1, 16, v26
	s_waitcnt lgkmcnt(0)
	v_add_f32_e32 v0, v5, v0
	v_mul_f32_e32 v0, v0, v1
	v_cvt_pk_bf16_f32 v0, v0, v0
	global_store_short v[34:35], v0, off offset:512
	ds_bpermute_b32 v0, v193, v74
	v_lshlrev_b32_e32 v1, 16, v24
	s_waitcnt lgkmcnt(0)
	v_add_f32_e32 v0, v6, v0
	v_mul_f32_e32 v0, v0, v1
	v_cvt_pk_bf16_f32 v0, v0, v0
	global_store_short v[34:35], v0, off offset:1024
	ds_bpermute_b32 v0, v164, v74
	v_lshlrev_b32_e32 v1, 16, v23
	s_waitcnt lgkmcnt(0)
	v_add_f32_e32 v0, v7, v0
	v_mul_f32_e32 v0, v0, v1
	v_cvt_pk_bf16_f32 v0, v0, v0
	global_store_short v[34:35], v0, off offset:1536
	ds_bpermute_b32 v0, v194, v74
	v_lshlrev_b32_e32 v1, 16, v25
	s_waitcnt lgkmcnt(0)
	v_add_f32_e32 v0, v8, v0
	v_mul_f32_e32 v0, v0, v1
	v_cvt_pk_bf16_f32 v2, v0, v0
	v_add_co_u32_e32 v0, vcc, s0, v72
	s_mov_b32 s0, 0xb40f000
	s_nop 0
	v_addc_co_u32_e32 v1, vcc, 0, v73, vcc
	v_add_co_u32_e32 v4, vcc, s0, v72
	s_nop 1
	v_addc_co_u32_e32 v5, vcc, 0, v73, vcc
	global_store_short v[4:5], v2, off offset:-4096
	ds_bpermute_b32 v2, v195, v74
	s_waitcnt lgkmcnt(0)
	v_add_f32_e32 v2, v9, v2
	v_mul_f32_e32 v2, v2, v3
	v_cvt_pk_bf16_f32 v2, v2, v2
	global_store_short v[0:1], v2, off offset:512
	ds_bpermute_b32 v2, v196, v74
	v_lshlrev_b32_e32 v3, 16, v21
	s_waitcnt lgkmcnt(0)
	v_add_f32_e32 v2, v10, v2
	v_mul_f32_e32 v2, v2, v3
	v_cvt_pk_bf16_f32 v2, v2, v2
	global_store_short v[0:1], v2, off offset:1024
	ds_bpermute_b32 v2, v168, v74
	v_lshlrev_b32_e32 v3, 16, v20
	s_waitcnt lgkmcnt(0)
	v_add_f32_e32 v2, v11, v2
	v_mul_f32_e32 v2, v2, v3
	v_cvt_pk_bf16_f32 v2, v2, v2
	global_store_short v[0:1], v2, off offset:1536
	ds_bpermute_b32 v0, v197, v74
	v_lshlrev_b32_e32 v1, 16, v19
	s_waitcnt lgkmcnt(0)
	v_add_f32_e32 v0, v12, v0
	v_mul_f32_e32 v0, v0, v1
	v_cvt_pk_bf16_f32 v0, v0, v0
	global_store_short v[4:5], v0, off
	ds_bpermute_b32 v0, v198, v74
	v_lshlrev_b32_e32 v1, 16, v18
	s_waitcnt lgkmcnt(0)
	v_add_f32_e32 v0, v13, v0
	v_mul_f32_e32 v0, v0, v1
	v_cvt_pk_bf16_f32 v0, v0, v0
	global_store_short v[4:5], v0, off offset:512
	ds_bpermute_b32 v0, v199, v74
	v_lshlrev_b32_e32 v1, 16, v17
	s_waitcnt lgkmcnt(0)
	v_add_f32_e32 v0, v14, v0
	v_mul_f32_e32 v0, v0, v1
	v_cvt_pk_bf16_f32 v0, v0, v0
	global_store_short v[4:5], v0, off offset:1024
	ds_bpermute_b32 v0, v172, v74
	v_lshlrev_b32_e32 v1, 16, v16
	s_waitcnt lgkmcnt(0)
	v_add_f32_e32 v0, v15, v0
	v_mul_f32_e32 v0, v0, v1
	v_cvt_pk_bf16_f32 v0, v0, v0
	global_store_short v[4:5], v0, off offset:1536
	s_waitcnt vmcnt(63) expcnt(7) lgkmcnt(15)
	s_barrier
	s_cbranch_scc0 .LBB0_79

; __device__ __forceinline__ void conv_item(int l, int it, LAS unsigned char* lds, const bf16_t* CGB, bf16_t* YC, const float* conv_w, const float* conv_b,
;                                           const float* conv_ln_g, const float* conv_ln_b, int tid, int lane, int wave) {
;     ...
;             for (int ib = 0; ib < 48; ib += 12) {
;                 unsigned raw[12]; const void* pp[12];
; #pragma unroll
;                 for (int j = 0; j < 12; ++j) { const int off = tp - 30 + (ib + j < 46 ? ib + j : 45); pp[j] = CGB + (r0 + (pos0 + off >= 0 ? off : -pos0)) * BW; }
;                 ld_u16_s12(raw, (unsigned)c * 2u, pp);
; #pragma unroll
;                 for (int j = 0; j < 12; ++j) if (ib + j < 46) x[ib + j] = (pos0 + tp - 30 + ib + j >= 0) ? __uint_as_float(raw[j] << 16) : 0.f;
.LBB0_102:
	s_or_b32 s9, s8, s42
	s_sub_i32 s4, s9, 30
	s_max_i32 s4, s4, s7
	s_ashr_i32 s5, s4, 31
	s_add_u32 s4, s0, s4
	s_addc_u32 s5, s1, s5
	s_lshl_b64 s[4:5], s[4:5], 9
	s_add_u32 s4, s78, s4
	s_addc_u32 s5, s79, s5
	s_sub_i32 s10, s9, 29
	s_max_i32 s10, s10, s7
	s_ashr_i32 s11, s10, 31
	s_add_u32 s10, s0, s10
	s_addc_u32 s11, s1, s11
	s_lshl_b64 s[10:11], s[10:11], 9
	s_add_u32 s12, s78, s10
	s_addc_u32 s13, s79, s11
	s_sub_i32 s10, s9, 28
	s_max_i32 s10, s10, s7
	s_ashr_i32 s11, s10, 31
	s_add_u32 s10, s0, s10
	s_addc_u32 s11, s1, s11
	s_lshl_b64 s[10:11], s[10:11], 9
	s_add_u32 s16, s78, s10
	s_addc_u32 s17, s79, s11
	s_sub_i32 s10, s9, 27
	s_max_i32 s10, s10, s7
	s_ashr_i32 s11, s10, 31
	s_add_u32 s10, s0, s10
	s_addc_u32 s11, s1, s11
	s_lshl_b64 s[10:11], s[10:11], 9
	s_add_u32 s18, s78, s10
	s_addc_u32 s19, s79, s11
	s_sub_i32 s10, s9, 26
	s_max_i32 s10, s10, s7
	s_ashr_i32 s11, s10, 31
	s_add_u32 s10, s0, s10
	s_addc_u32 s11, s1, s11
	s_lshl_b64 s[10:11], s[10:11], 9
	s_add_u32 s20, s78, s10
	s_addc_u32 s21, s79, s11
	s_sub_i32 s10, s9, 25
	s_max_i32 s10, s10, s7
	s_ashr_i32 s11, s10, 31
	s_add_u32 s10, s0, s10
	s_addc_u32 s11, s1, s11
	s_lshl_b64 s[10:11], s[10:11], 9
	s_add_u32 s22, s78, s10
	s_addc_u32 s23, s79, s11
	s_sub_i32 s10, s9, 24
	s_max_i32 s10, s10, s7
	s_ashr_i32 s11, s10, 31
	s_add_u32 s10, s0, s10
	s_addc_u32 s11, s1, s11
	s_lshl_b64 s[10:11], s[10:11], 9
	s_add_u32 s24, s78, s10
	s_addc_u32 s25, s79, s11
	s_sub_i32 s10, s9, 23
	s_max_i32 s10, s10, s7
	s_ashr_i32 s11, s10, 31
	s_add_u32 s10, s0, s10
	s_addc_u32 s11, s1, s11
	s_lshl_b64 s[10:11], s[10:11], 9
	s_add_u32 s26, s78, s10
	s_addc_u32 s27, s79, s11
	s_sub_i32 s10, s9, 22
	s_max_i32 s10, s10, s7
	s_ashr_i32 s11, s10, 31
	s_add_u32 s10, s0, s10
	s_addc_u32 s11, s1, s11
	s_lshl_b64 s[10:11], s[10:11], 9
	s_add_u32 s28, s78, s10
	s_addc_u32 s29, s79, s11
	s_sub_i32 s10, s9, 21
	s_max_i32 s10, s10, s7
	s_ashr_i32 s11, s10, 31
	s_add_u32 s10, s0, s10
	s_addc_u32 s11, s1, s11
	s_lshl_b64 s[10:11], s[10:11], 9
	s_add_u32 s30, s78, s10
	s_addc_u32 s31, s79, s11
	s_sub_i32 s10, s9, 20
	s_max_i32 s10, s10, s7
	s_ashr_i32 s11, s10, 31
	s_add_u32 s10, s0, s10
	s_addc_u32 s11, s1, s11
	s_lshl_b64 s[10:11], s[10:11], 9
	s_add_u32 s34, s78, s10
	s_addc_u32 s35, s79, s11
	s_sub_i32 s10, s9, 19
	s_max_i32 s10, s10, s7
	s_ashr_i32 s11, s10, 31
	s_add_u32 s10, s0, s10
	s_addc_u32 s11, s1, s11
	s_lshl_b64 s[10:11], s[10:11], 9
	s_add_u32 s36, s78, s10
	s_addc_u32 s37, s79, s11
	s_add_i32 s10, s9, s6
	s_nop 4
	global_load_ushort v108, v33, s[4:5]
	global_load_ushort v109, v33, s[12:13]
	global_load_ushort v110, v33, s[16:17]
	global_load_ushort v111, v33, s[18:19]
	global_load_ushort v112, v33, s[20:21]
	global_load_ushort v113, v33, s[22:23]
	global_load_ushort v114, v33, s[24:25]
	global_load_ushort v115, v33, s[26:27]
	global_load_ushort v116, v33, s[28:29]
	global_load_ushort v117, v33, s[30:31]
	global_load_ushort v118, v33, s[34:35]
	global_load_ushort v119, v33, s[36:37]
	s_sub_i32 s98, s9, 30
	s_ashr_i32 s99, s98, 31
	s_add_u32 s98, s0, s98
	s_addc_u32 s99, s1, s99
	s_lshl_b64 s[98:99], s[98:99], 9
	s_add_u32 s98, s78, s98
	s_addc_u32 s99, s79, s99
	s_add_u32 s98, s98, 0x1800
	s_addc_u32 s99, s99, 0
	global_load_ushort v219, v33, s[98:99]
	s_add_u32 s98, s98, 0x200
	s_addc_u32 s99, s99, 0
	global_load_ushort v220, v33, s[98:99]
	s_add_u32 s98, s98, 0x200
	s_addc_u32 s99, s99, 0
	global_load_ushort v221, v33, s[98:99]
	s_add_u32 s98, s98, 0x200
	s_addc_u32 s99, s99, 0
	global_load_ushort v222, v33, s[98:99]
	s_add_u32 s98, s98, 0x200
	s_addc_u32 s99, s99, 0
	global_load_ushort v223, v33, s[98:99]
	s_add_u32 s98, s98, 0x200
	s_addc_u32 s99, s99, 0
	global_load_ushort v224, v33, s[98:99]
	s_add_u32 s98, s98, 0x200
	s_addc_u32 s99, s99, 0
	global_load_ushort v225, v33, s[98:99]
	s_add_u32 s98, s98, 0x200
	s_addc_u32 s99, s99, 0
	global_load_ushort v226, v33, s[98:99]
	s_add_u32 s98, s98, 0x200
	s_addc_u32 s99, s99, 0
	global_load_ushort v227, v33, s[98:99]
	s_add_u32 s98, s98, 0x200
	s_addc_u32 s99, s99, 0
	global_load_ushort v228, v33, s[98:99]
	s_add_u32 s98, s98, 0x200
	s_addc_u32 s99, s99, 0
	global_load_ushort v229, v33, s[98:99]
	s_add_u32 s98, s98, 0x200
	s_addc_u32 s99, s99, 0
	global_load_ushort v230, v33, s[98:99]
	s_waitcnt vmcnt(12)
	s_cmp_gt_i32 s10, 29
	v_lshlrev_b32_e32 v108, 16, v108
	s_cselect_b64 vcc, -1, 0
	s_cmp_gt_i32 s10, 28
	v_lshlrev_b32_e32 v109, 16, v109
	v_cndmask_b32_e32 v108, 0, v108, vcc
	s_cselect_b64 vcc, -1, 0
	s_cmp_gt_i32 s10, 27
	v_lshlrev_b32_e32 v110, 16, v110
	v_lshlrev_b32_e32 v120, 16, v116
	v_lshlrev_b32_e32 v116, 16, v117
	v_lshlrev_b32_e32 v117, 16, v118
	v_lshlrev_b32_e32 v118, 16, v119
	v_cndmask_b32_e32 v119, 0, v109, vcc
	s_cselect_b64 vcc, -1, 0
	s_cmp_gt_i32 s10, 26
	v_lshlrev_b32_e32 v111, 16, v111
	v_cndmask_b32_e32 v121, 0, v110, vcc
	s_cselect_b64 vcc, -1, 0
	s_cmp_gt_i32 s10, 25
	v_lshlrev_b32_e32 v112, 16, v112
	s_waitcnt vmcnt(0)
; __device__ __forceinline__ void conv_item(int l, int it, LAS unsigned char* lds, const bf16_t* CGB, bf16_t* YC, const float* conv_w, const float* conv_b,
;                                           const float* conv_ln_g, const float* conv_ln_b, int tid, int lane, int wave) {
;     ...
;             for (int ib = 0; ib < 48; ib += 12) {
;                 unsigned raw[12]; const void* pp[12];
; #pragma unroll
;                 for (int j = 0; j < 12; ++j) { const int off = tp - 30 + (ib + j < 46 ? ib + j : 45); pp[j] = CGB + (r0 + (pos0 + off >= 0 ? off : -pos0)) * BW; }
;                 ld_u16_s12(raw, (unsigned)c * 2u, pp);
; #pragma unroll
;                 for (int j = 0; j < 12; ++j) if (ib + j < 46) x[ib + j] = (pos0 + tp - 30 + ib + j >= 0) ? __uint_as_float(raw[j] << 16) : 0.f;
;             }
; #pragma unroll
;             for (int t = 0; t < 16; ++t) {
;                 float acc = bias;
; #pragma unroll
;                 for (int j = 0; j < 31; ++j) acc += wd[j] * x[t + j];
	v_fma_f32 v108, v0, v108, v106
	v_cndmask_b32_e32 v122, 0, v111, vcc
	s_cselect_b64 vcc, -1, 0
	s_cmp_gt_i32 s10, 24
	v_lshlrev_b32_e32 v113, 16, v113
	v_fma_f32 v109, v0, v119, v106
	v_fmac_f32_e32 v108, v1, v119
	v_cndmask_b32_e32 v119, 0, v112, vcc
	s_cselect_b64 vcc, -1, 0
	s_cmp_gt_i32 s10, 23
	v_lshlrev_b32_e32 v114, 16, v114
	v_fmac_f32_e32 v109, v1, v121
	v_fma_f32 v110, v0, v121, v106
	v_fmac_f32_e32 v108, v2, v121
	v_cndmask_b32_e32 v121, 0, v113, vcc
	s_cselect_b64 vcc, -1, 0
	s_cmp_gt_i32 s10, 22
	v_lshlrev_b32_e32 v115, 16, v115
	v_fmac_f32_e32 v109, v2, v122
	v_fmac_f32_e32 v110, v1, v122
	v_fma_f32 v111, v0, v122, v106
	v_fmac_f32_e32 v108, v3, v122
	v_cndmask_b32_e32 v122, 0, v114, vcc
	s_cselect_b64 vcc, -1, 0
	s_cmp_gt_i32 s10, 21
	v_fmac_f32_e32 v109, v3, v119
	v_fmac_f32_e32 v110, v2, v119
	v_fmac_f32_e32 v111, v1, v119
	v_fma_f32 v112, v0, v119, v106
	v_fmac_f32_e32 v108, v4, v119
	v_cndmask_b32_e32 v119, 0, v115, vcc
	s_cselect_b64 vcc, -1, 0
	s_cmp_gt_i32 s10, 20
	v_fmac_f32_e32 v109, v4, v121
	v_fmac_f32_e32 v110, v3, v121
	v_fmac_f32_e32 v111, v2, v121
	v_fmac_f32_e32 v112, v1, v121
	v_fma_f32 v113, v0, v121, v106
	v_fmac_f32_e32 v108, v5, v121
	v_cndmask_b32_e32 v120, 0, v120, vcc
	s_cselect_b64 vcc, -1, 0
	s_cmp_gt_i32 s10, 19
	v_fmac_f32_e32 v109, v5, v122
	v_fmac_f32_e32 v110, v4, v122
	v_fmac_f32_e32 v111, v3, v122
	v_fmac_f32_e32 v112, v2, v122
	v_fmac_f32_e32 v113, v1, v122
	v_fma_f32 v114, v0, v122, v106
	v_fmac_f32_e32 v108, v6, v122
	v_cndmask_b32_e32 v121, 0, v116, vcc
	s_cselect_b64 vcc, -1, 0
	s_cmp_gt_i32 s10, 18
	v_fmac_f32_e32 v109, v6, v119
	v_fmac_f32_e32 v110, v5, v119
	v_fmac_f32_e32 v111, v4, v119
	v_fmac_f32_e32 v112, v3, v119
	v_fmac_f32_e32 v113, v2, v119
	v_fmac_f32_e32 v114, v1, v119
	v_fma_f32 v115, v0, v119, v106
	v_fmac_f32_e32 v108, v7, v119
	v_cndmask_b32_e32 v119, 0, v117, vcc
	s_cselect_b64 vcc, -1, 0
	s_sub_i32 s4, s9, 18
	s_max_i32 s4, s4, s7
	s_ashr_i32 s5, s4, 31
	s_add_u32 s4, s0, s4
	s_addc_u32 s5, s1, s5
	s_lshl_b64 s[4:5], s[4:5], 9
	s_add_u32 s12, s78, s4
	s_addc_u32 s13, s79, s5
	s_sub_i32 s4, s9, 17
	s_max_i32 s4, s4, s7
	s_ashr_i32 s5, s4, 31
	s_add_u32 s4, s0, s4
	s_addc_u32 s5, s1, s5
	s_lshl_b64 s[4:5], s[4:5], 9
	s_add_u32 s16, s78, s4
	s_addc_u32 s17, s79, s5
	s_add_i32 s4, s9, -16
	s_max_i32 s4, s4, s7
	s_ashr_i32 s5, s4, 31
	s_add_u32 s4, s0, s4
	s_addc_u32 s5, s1, s5
	s_lshl_b64 s[4:5], s[4:5], 9
	s_add_u32 s18, s78, s4
	s_addc_u32 s19, s79, s5
	s_add_i32 s4, s9, -15
	s_max_i32 s4, s4, s7
	s_ashr_i32 s5, s4, 31
	s_add_u32 s4, s0, s4
	s_addc_u32 s5, s1, s5
	s_lshl_b64 s[4:5], s[4:5], 9
	s_add_u32 s20, s78, s4
	s_addc_u32 s21, s79, s5
	s_add_i32 s4, s9, -14
	s_max_i32 s4, s4, s7
	s_ashr_i32 s5, s4, 31
	s_add_u32 s4, s0, s4
	s_addc_u32 s5, s1, s5
	s_lshl_b64 s[4:5], s[4:5], 9
	s_add_u32 s22, s78, s4
	s_addc_u32 s23, s79, s5
	s_add_i32 s4, s9, -13
	s_max_i32 s4, s4, s7
	s_ashr_i32 s5, s4, 31
	s_add_u32 s4, s0, s4
	s_addc_u32 s5, s1, s5
	s_lshl_b64 s[4:5], s[4:5], 9
	s_add_u32 s24, s78, s4
	s_addc_u32 s25, s79, s5
	s_add_i32 s4, s9, -12
	s_max_i32 s4, s4, s7
	s_ashr_i32 s5, s4, 31
	s_add_u32 s4, s0, s4
	s_addc_u32 s5, s1, s5
	s_lshl_b64 s[4:5], s[4:5], 9
	s_add_u32 s26, s78, s4
	s_addc_u32 s27, s79, s5
	s_add_i32 s4, s9, -11
	s_max_i32 s4, s4, s7
	s_ashr_i32 s5, s4, 31
	s_add_u32 s4, s0, s4
	s_addc_u32 s5, s1, s5
	s_lshl_b64 s[4:5], s[4:5], 9
	s_add_u32 s28, s78, s4
	s_addc_u32 s29, s79, s5
	s_add_i32 s4, s9, -10
	s_max_i32 s4, s4, s7
	s_ashr_i32 s5, s4, 31
	s_add_u32 s4, s0, s4
	s_addc_u32 s5, s1, s5
	s_lshl_b64 s[4:5], s[4:5], 9
	s_add_u32 s30, s78, s4
	s_addc_u32 s31, s79, s5
	s_add_i32 s4, s9, -9
	s_max_i32 s4, s4, s7
	s_ashr_i32 s5, s4, 31
	s_add_u32 s4, s0, s4
	s_addc_u32 s5, s1, s5
	s_lshl_b64 s[4:5], s[4:5], 9
	s_add_u32 s34, s78, s4
	s_addc_u32 s35, s79, s5
	s_add_i32 s4, s9, -8
	s_max_i32 s4, s4, s7
	s_ashr_i32 s5, s4, 31
	s_add_u32 s4, s0, s4
	s_addc_u32 s5, s1, s5
	s_lshl_b64 s[4:5], s[4:5], 9
	s_add_u32 s36, s78, s4
	s_addc_u32 s37, s79, s5
	s_add_i32 s4, s9, -7
	s_max_i32 s4, s4, s7
	s_ashr_i32 s5, s4, 31
	s_add_u32 s4, s0, s4
	s_addc_u32 s5, s1, s5
	v_fmac_f32_e32 v109, v7, v120
	v_fmac_f32_e32 v110, v6, v120
	v_fmac_f32_e32 v111, v5, v120
	v_fmac_f32_e32 v112, v4, v120
	v_fmac_f32_e32 v113, v3, v120
	v_fmac_f32_e32 v114, v2, v120
	v_fmac_f32_e32 v115, v1, v120
	v_fma_f32 v116, v0, v120, v106
	v_fmac_f32_e32 v108, v8, v120
	s_lshl_b64 s[4:5], s[4:5], 9
	v_fmac_f32_e32 v109, v8, v121
	v_fmac_f32_e32 v110, v7, v121
	v_fmac_f32_e32 v111, v6, v121
	v_fmac_f32_e32 v112, v5, v121
	v_fmac_f32_e32 v113, v4, v121
	v_fmac_f32_e32 v114, v3, v121
	v_fmac_f32_e32 v115, v2, v121
	v_fmac_f32_e32 v116, v1, v121
	v_fma_f32 v117, v0, v121, v106
	v_fmac_f32_e32 v108, v9, v121
	s_add_u32 s38, s78, s4
	v_cndmask_b32_e32 v120, 0, v118, vcc
	v_fmac_f32_e32 v109, v9, v119
	v_fmac_f32_e32 v110, v8, v119
	v_fmac_f32_e32 v111, v7, v119
	v_fmac_f32_e32 v112, v6, v119
	v_fmac_f32_e32 v113, v5, v119
	v_fmac_f32_e32 v114, v4, v119
	v_fmac_f32_e32 v115, v3, v119
	v_fmac_f32_e32 v116, v2, v119
	v_fmac_f32_e32 v117, v1, v119
	v_fma_f32 v118, v0, v119, v106
	v_fmac_f32_e32 v108, v10, v119
	s_addc_u32 s39, s79, s5
	s_or_b32 s4, s10, 12
	v_fmac_f32_e32 v109, v10, v120
	v_fmac_f32_e32 v110, v9, v120
	v_fmac_f32_e32 v111, v8, v120
	v_fmac_f32_e32 v112, v7, v120
	v_fmac_f32_e32 v113, v6, v120
	v_fmac_f32_e32 v114, v5, v120
	v_fmac_f32_e32 v115, v4, v120
	v_fmac_f32_e32 v116, v3, v120
	v_fmac_f32_e32 v117, v2, v120
	v_fmac_f32_e32 v118, v1, v120
	v_fma_f32 v119, v0, v120, v106
	v_fmac_f32_e32 v108, v11, v120
	s_add_u32 s98, s98, 0x200
	s_addc_u32 s99, s99, 0
	global_load_ushort v231, v33, s[98:99]
	s_add_u32 s98, s98, 0x200
	s_addc_u32 s99, s99, 0
	global_load_ushort v232, v33, s[98:99]
	s_add_u32 s98, s98, 0x200
	s_addc_u32 s99, s99, 0
	global_load_ushort v233, v33, s[98:99]
	s_add_u32 s98, s98, 0x200
	s_addc_u32 s99, s99, 0
	global_load_ushort v236, v33, s[98:99]
	s_add_u32 s98, s98, 0x200
	s_addc_u32 s99, s99, 0
	global_load_ushort v237, v33, s[98:99]
	s_add_u32 s98, s98, 0x200
	s_addc_u32 s99, s99, 0
	global_load_ushort v238, v33, s[98:99]
	s_add_u32 s98, s98, 0x200
	s_addc_u32 s99, s99, 0
	global_load_ushort v239, v33, s[98:99]
	s_add_u32 s98, s98, 0x200
	s_addc_u32 s99, s99, 0
	global_load_ushort v240, v33, s[98:99]
	s_add_u32 s98, s98, 0x200
	s_addc_u32 s99, s99, 0
	global_load_ushort v245, v33, s[98:99]
	s_add_u32 s98, s98, 0x200
	s_addc_u32 s99, s99, 0
	global_load_ushort v246, v33, s[98:99]
	s_add_u32 s98, s98, 0x200
	s_addc_u32 s99, s99, 0
	global_load_ushort v247, v33, s[98:99]
	s_add_u32 s98, s98, 0x200
	s_addc_u32 s99, s99, 0
	global_load_ushort v248, v33, s[98:99]
	s_waitcnt vmcnt(12)
; __device__ __forceinline__ void conv_item(int l, int it, LAS unsigned char* lds, const bf16_t* CGB, bf16_t* YC, const float* conv_w, const float* conv_b,
;                                           const float* conv_ln_g, const float* conv_ln_b, int tid, int lane, int wave) {
;     ...
;                 for (int j = 0; j < 12; ++j) if (ib + j < 46) x[ib + j] = (pos0 + tp - 30 + ib + j >= 0) ? __uint_as_float(raw[j] << 16) : 0.f;
;             }
; #pragma unroll
;             for (int t = 0; t < 16; ++t) {
;                 float acc = bias;
; #pragma unroll
;                 for (int j = 0; j < 31; ++j) acc += wd[j] * x[t + j];
	v_mov_b32_e32 v120, v219
	v_mov_b32_e32 v121, v220
	v_mov_b32_e32 v122, v221
	v_mov_b32_e32 v123, v222
	v_mov_b32_e32 v124, v223
	v_mov_b32_e32 v125, v224
	v_mov_b32_e32 v126, v225
	v_mov_b32_e32 v127, v226
	v_mov_b32_e32 v128, v227
	v_mov_b32_e32 v129, v228
	v_mov_b32_e32 v130, v229
	v_mov_b32_e32 v131, v230
	s_cmp_gt_i32 s4, 29
	v_lshlrev_b32_e32 v120, 16, v120
	s_cselect_b64 vcc, -1, 0
	s_cmp_gt_i32 s4, 28
	v_lshlrev_b32_e32 v121, 16, v121
	v_cndmask_b32_e32 v120, 0, v120, vcc
	s_cselect_b64 vcc, -1, 0
	s_cmp_gt_i32 s4, 27
	v_lshlrev_b32_e32 v122, 16, v122
	v_lshlrev_b32_e32 v150, 16, v127
	v_lshlrev_b32_e32 v127, 16, v128
	v_cndmask_b32_e32 v128, 0, v121, vcc
	s_cselect_b64 vcc, -1, 0
	s_cmp_gt_i32 s4, 26
	v_lshlrev_b32_e32 v123, 16, v123
	v_lshlrev_b32_e32 v149, 16, v126
	v_lshlrev_b32_e32 v126, 16, v129
	v_cndmask_b32_e32 v129, 0, v122, vcc
	s_cselect_b64 vcc, -1, 0
	s_cmp_gt_i32 s4, 25
	v_lshlrev_b32_e32 v132, 16, v124
	v_lshlrev_b32_e32 v133, 16, v125
	v_lshlrev_b32_e32 v125, 16, v130
	v_fmac_f32_e32 v108, v35, v120
	v_fmac_f32_e32 v109, v11, v120
	v_fmac_f32_e32 v110, v10, v120
	v_fmac_f32_e32 v111, v9, v120
	v_fmac_f32_e32 v112, v8, v120
	v_fmac_f32_e32 v113, v7, v120
	v_fmac_f32_e32 v114, v6, v120
	v_fmac_f32_e32 v115, v5, v120
	v_fmac_f32_e32 v116, v4, v120
	v_fmac_f32_e32 v117, v3, v120
	v_fmac_f32_e32 v118, v2, v120
	v_fmac_f32_e32 v119, v1, v120
	v_fma_f32 v121, v0, v120, v106
	v_cndmask_b32_e32 v130, 0, v123, vcc
	s_cselect_b64 vcc, -1, 0
	s_cmp_gt_i32 s4, 24
	v_fma_f32 v120, v0, v128, v106
	v_fmac_f32_e32 v108, v86, v128
	v_fmac_f32_e32 v109, v35, v128
	v_fmac_f32_e32 v110, v11, v128
	v_fmac_f32_e32 v111, v10, v128
	v_fmac_f32_e32 v112, v9, v128
	v_fmac_f32_e32 v113, v8, v128
	v_fmac_f32_e32 v114, v7, v128
	v_fmac_f32_e32 v115, v6, v128
	v_fmac_f32_e32 v116, v5, v128
	v_fmac_f32_e32 v117, v4, v128
	v_fmac_f32_e32 v118, v3, v128
	v_fmac_f32_e32 v119, v2, v128
	v_fmac_f32_e32 v121, v1, v128
	v_cndmask_b32_e32 v128, 0, v132, vcc
	s_cselect_b64 vcc, -1, 0
	s_cmp_gt_i32 s4, 23
	v_fmac_f32_e32 v120, v1, v129
	v_fma_f32 v122, v0, v129, v106
	v_fmac_f32_e32 v108, v87, v129
	v_fmac_f32_e32 v109, v86, v129
	v_fmac_f32_e32 v110, v35, v129
	v_fmac_f32_e32 v111, v11, v129
	v_fmac_f32_e32 v112, v10, v129
	v_fmac_f32_e32 v113, v9, v129
	v_fmac_f32_e32 v114, v8, v129
	v_fmac_f32_e32 v115, v7, v129
	v_fmac_f32_e32 v116, v6, v129
	v_fmac_f32_e32 v117, v5, v129
	v_fmac_f32_e32 v118, v4, v129
	v_fmac_f32_e32 v119, v3, v129
	v_fmac_f32_e32 v121, v2, v129
	v_cndmask_b32_e32 v129, 0, v133, vcc
	s_cselect_b64 vcc, -1, 0
	s_cmp_gt_i32 s4, 22
	v_fmac_f32_e32 v120, v2, v130
	v_fmac_f32_e32 v122, v1, v130
	v_fma_f32 v123, v0, v130, v106
	v_fmac_f32_e32 v108, v90, v130
	v_fmac_f32_e32 v109, v87, v130
	v_fmac_f32_e32 v110, v86, v130
	v_fmac_f32_e32 v111, v35, v130
	v_fmac_f32_e32 v112, v11, v130
	v_fmac_f32_e32 v113, v10, v130
	v_fmac_f32_e32 v114, v9, v130
	v_fmac_f32_e32 v115, v8, v130
	v_fmac_f32_e32 v116, v7, v130
	v_fmac_f32_e32 v117, v6, v130
	v_fmac_f32_e32 v118, v5, v130
	v_fmac_f32_e32 v119, v4, v130
	v_fmac_f32_e32 v121, v3, v130
	v_cndmask_b32_e32 v130, 0, v149, vcc
	s_cselect_b64 vcc, -1, 0
	s_cmp_gt_i32 s4, 21
	v_fmac_f32_e32 v120, v3, v128
	v_fmac_f32_e32 v122, v2, v128
	v_fmac_f32_e32 v123, v1, v128
	v_fmac_f32_e32 v108, v91, v128
	v_fmac_f32_e32 v109, v90, v128
	v_fmac_f32_e32 v110, v87, v128
	v_fmac_f32_e32 v111, v86, v128
	v_fmac_f32_e32 v112, v35, v128
	v_fmac_f32_e32 v113, v11, v128
	v_fmac_f32_e32 v114, v10, v128
	v_fmac_f32_e32 v115, v9, v128
	v_fmac_f32_e32 v116, v8, v128
	v_fmac_f32_e32 v117, v7, v128
	v_fmac_f32_e32 v118, v6, v128
	v_fmac_f32_e32 v119, v5, v128
	v_fmac_f32_e32 v121, v4, v128
	v_cndmask_b32_e32 v128, 0, v150, vcc
	s_cselect_b64 vcc, -1, 0
	s_cmp_gt_i32 s4, 20
	v_cndmask_b32_e32 v127, 0, v127, vcc
	s_cselect_b64 vcc, -1, 0
	s_cmp_gt_i32 s4, 19
	v_cndmask_b32_e32 v126, 0, v126, vcc
	s_cselect_b64 vcc, -1, 0
	s_cmp_gt_i32 s4, 18
	v_cndmask_b32_e32 v125, 0, v125, vcc
	s_cselect_b64 vcc, -1, 0
	s_add_i32 s4, s9, -6
	s_max_i32 s4, s4, s7
	s_ashr_i32 s5, s4, 31
	s_add_u32 s4, s0, s4
	s_addc_u32 s5, s1, s5
	s_lshl_b64 s[4:5], s[4:5], 9
	s_add_u32 s4, s78, s4
	s_addc_u32 s5, s79, s5
	s_add_i32 s11, s9, -5
	s_max_i32 s11, s11, s7
	s_ashr_i32 s13, s11, 31
	s_add_u32 s12, s0, s11
	s_addc_u32 s13, s1, s13
	s_lshl_b64 s[12:13], s[12:13], 9
	s_add_u32 s12, s78, s12
	s_addc_u32 s13, s79, s13
	s_add_i32 s11, s9, -4
	s_max_i32 s11, s11, s7
	s_ashr_i32 s14, s11, 31
	s_add_u32 s16, s0, s11
	s_addc_u32 s17, s1, s14
	s_lshl_b64 s[16:17], s[16:17], 9
	s_add_u32 s16, s78, s16
	s_addc_u32 s17, s79, s17
	s_add_i32 s11, s9, -3
	s_max_i32 s11, s11, s7
	s_ashr_i32 s14, s11, 31
	s_add_u32 s18, s0, s11
	s_addc_u32 s19, s1, s14
	s_lshl_b64 s[18:19], s[18:19], 9
	s_add_u32 s18, s78, s18
	s_addc_u32 s19, s79, s19
	s_add_i32 s11, s9, -2
	s_max_i32 s11, s11, s7
	s_ashr_i32 s14, s11, 31
	s_add_u32 s20, s0, s11
	s_addc_u32 s21, s1, s14
	s_lshl_b64 s[20:21], s[20:21], 9
	s_add_u32 s20, s78, s20
	s_addc_u32 s21, s79, s21
	s_add_i32 s11, s9, -1
	s_max_i32 s11, s11, s7
	s_ashr_i32 s14, s11, 31
	s_add_u32 s22, s0, s11
	s_addc_u32 s23, s1, s14
	s_lshl_b64 s[22:23], s[22:23], 9
	s_add_u32 s22, s78, s22
	s_addc_u32 s23, s79, s23
	s_max_i32 s11, s9, s7
	s_ashr_i32 s14, s11, 31
	v_fmac_f32_e32 v120, v4, v129
	v_fmac_f32_e32 v122, v3, v129
	v_fmac_f32_e32 v123, v2, v129
	v_fmac_f32_e32 v108, v92, v129
	v_fmac_f32_e32 v109, v91, v129
	v_fmac_f32_e32 v110, v90, v129
	v_fmac_f32_e32 v111, v87, v129
	v_fmac_f32_e32 v112, v86, v129
	v_fmac_f32_e32 v113, v35, v129
	v_fmac_f32_e32 v114, v11, v129
	v_fmac_f32_e32 v115, v10, v129
	v_fmac_f32_e32 v116, v9, v129
; __device__ __forceinline__ void conv_item(int l, int it, LAS unsigned char* lds, const bf16_t* CGB, bf16_t* YC, const float* conv_w, const float* conv_b,
;                                           const float* conv_ln_g, const float* conv_ln_b, int tid, int lane, int wave) {
;     ...
;                 for (int j = 0; j < 12; ++j) { const int off = tp - 30 + (ib + j < 46 ? ib + j : 45); pp[j] = CGB + (r0 + (pos0 + off >= 0 ? off : -pos0)) * BW; }
;                 ld_u16_s12(raw, (unsigned)c * 2u, pp);
; #pragma unroll
;                 for (int j = 0; j < 12; ++j) if (ib + j < 46) x[ib + j] = (pos0 + tp - 30 + ib + j >= 0) ? __uint_as_float(raw[j] << 16) : 0.f;
;             }
; #pragma unroll
;             for (int t = 0; t < 16; ++t) {
;                 float acc = bias;
; #pragma unroll
;                 for (int j = 0; j < 31; ++j) acc += wd[j] * x[t + j];
	v_fmac_f32_e32 v117, v8, v129
	v_fmac_f32_e32 v118, v7, v129
	v_fmac_f32_e32 v119, v6, v129
	v_fmac_f32_e32 v121, v5, v129
	s_add_u32 s24, s0, s11
	v_fmac_f32_e32 v120, v5, v130
	v_fmac_f32_e32 v122, v4, v130
	v_fmac_f32_e32 v123, v3, v130
	v_fmac_f32_e32 v108, v93, v130
	v_fmac_f32_e32 v109, v92, v130
	v_fmac_f32_e32 v110, v91, v130
	v_fmac_f32_e32 v111, v90, v130
	v_fmac_f32_e32 v112, v87, v130
	v_fmac_f32_e32 v113, v86, v130
	v_fmac_f32_e32 v114, v35, v130
	v_fmac_f32_e32 v115, v11, v130
	v_fmac_f32_e32 v116, v10, v130
	v_fmac_f32_e32 v117, v9, v130
	v_fmac_f32_e32 v118, v8, v130
	v_fmac_f32_e32 v119, v7, v130
	v_fmac_f32_e32 v121, v6, v130
	s_addc_u32 s25, s1, s14
	v_fmac_f32_e32 v120, v6, v128
	v_fmac_f32_e32 v122, v5, v128
	v_fmac_f32_e32 v123, v4, v128
	v_fmac_f32_e32 v108, v94, v128
	v_fmac_f32_e32 v109, v93, v128
	v_fmac_f32_e32 v110, v92, v128
	v_fmac_f32_e32 v111, v91, v128
	v_fmac_f32_e32 v112, v90, v128
	v_fmac_f32_e32 v113, v87, v128
	v_fmac_f32_e32 v114, v86, v128
	v_fmac_f32_e32 v115, v35, v128
	v_fmac_f32_e32 v116, v11, v128
	v_fmac_f32_e32 v117, v10, v128
	v_fmac_f32_e32 v118, v9, v128
	v_fmac_f32_e32 v119, v8, v128
	v_fmac_f32_e32 v121, v7, v128
	s_lshl_b64 s[24:25], s[24:25], 9
	v_fmac_f32_e32 v120, v7, v127
	v_fmac_f32_e32 v122, v6, v127
	v_fmac_f32_e32 v123, v5, v127
	v_fmac_f32_e32 v108, v95, v127
	v_fmac_f32_e32 v109, v94, v127
	v_fmac_f32_e32 v110, v93, v127
	v_fmac_f32_e32 v111, v92, v127
	v_fmac_f32_e32 v112, v91, v127
	v_fmac_f32_e32 v113, v90, v127
	v_fmac_f32_e32 v114, v87, v127
	v_fmac_f32_e32 v115, v86, v127
	v_fmac_f32_e32 v116, v35, v127
	v_fmac_f32_e32 v117, v11, v127
	v_fmac_f32_e32 v118, v10, v127
	v_fmac_f32_e32 v119, v9, v127
	v_fmac_f32_e32 v121, v8, v127
	s_add_u32 s24, s78, s24
	v_lshlrev_b32_e32 v124, 16, v131
	v_fmac_f32_e32 v120, v8, v126
	v_fmac_f32_e32 v122, v7, v126
	v_fmac_f32_e32 v123, v6, v126
	v_fmac_f32_e32 v108, v96, v126
	v_fmac_f32_e32 v109, v95, v126
	v_fmac_f32_e32 v110, v94, v126
	v_fmac_f32_e32 v111, v93, v126
	v_fmac_f32_e32 v112, v92, v126
	v_fmac_f32_e32 v113, v91, v126
	v_fmac_f32_e32 v114, v90, v126
	v_fmac_f32_e32 v115, v87, v126
	v_fmac_f32_e32 v116, v86, v126
	v_fmac_f32_e32 v117, v35, v126
	v_fmac_f32_e32 v118, v11, v126
	v_fmac_f32_e32 v119, v10, v126
	v_fmac_f32_e32 v121, v9, v126
	s_addc_u32 s25, s79, s25
	s_or_b32 s11, s9, 1
	v_cndmask_b32_e32 v124, 0, v124, vcc
	v_fmac_f32_e32 v120, v9, v125
	v_fmac_f32_e32 v122, v8, v125
	v_fmac_f32_e32 v123, v7, v125
	v_fmac_f32_e32 v108, v97, v125
	v_fmac_f32_e32 v109, v96, v125
	v_fmac_f32_e32 v110, v95, v125
	v_fmac_f32_e32 v111, v94, v125
	v_fmac_f32_e32 v112, v93, v125
	v_fmac_f32_e32 v113, v92, v125
	v_fmac_f32_e32 v114, v91, v125
	v_fmac_f32_e32 v115, v90, v125
	v_fmac_f32_e32 v116, v87, v125
	v_fmac_f32_e32 v117, v86, v125
	v_fmac_f32_e32 v118, v35, v125
	v_fmac_f32_e32 v119, v11, v125
	v_fmac_f32_e32 v121, v10, v125
	s_max_i32 s14, s11, s7
	v_fmac_f32_e32 v120, v10, v124
	v_fmac_f32_e32 v122, v9, v124
	v_fmac_f32_e32 v123, v8, v124
	v_fmac_f32_e32 v108, v98, v124
	v_fmac_f32_e32 v109, v97, v124
	v_fmac_f32_e32 v110, v96, v124
	v_fmac_f32_e32 v111, v95, v124
	v_fmac_f32_e32 v112, v94, v124
	v_fmac_f32_e32 v113, v93, v124
	v_fmac_f32_e32 v114, v92, v124
	v_fmac_f32_e32 v115, v91, v124
	v_fmac_f32_e32 v116, v90, v124
	v_fmac_f32_e32 v117, v87, v124
	v_fmac_f32_e32 v118, v86, v124
	v_fmac_f32_e32 v119, v35, v124
	v_fmac_f32_e32 v121, v11, v124
	v_lshl_add_u32 v124, s11, 10, v88
	s_ashr_i32 s11, s14, 31
	s_add_u32 s26, s0, s14
	s_addc_u32 s27, s1, s11
	s_lshl_b64 s[26:27], s[26:27], 9
	s_add_u32 s26, s78, s26
	s_addc_u32 s27, s79, s27
	s_or_b32 s11, s9, 2
	s_max_i32 s14, s11, s7
	v_lshl_add_u32 v125, s11, 10, v88
	s_ashr_i32 s11, s14, 31
	s_add_u32 s28, s0, s14
	s_addc_u32 s29, s1, s11
	s_lshl_b64 s[28:29], s[28:29], 9
	s_add_u32 s28, s78, s28
	s_addc_u32 s29, s79, s29
	s_or_b32 s11, s9, 3
	s_max_i32 s14, s11, s7
	v_lshl_add_u32 v126, s11, 10, v88
	s_ashr_i32 s11, s14, 31
	s_add_u32 s30, s0, s14
	s_addc_u32 s31, s1, s11
	s_lshl_b64 s[30:31], s[30:31], 9
	s_add_u32 s30, s78, s30
	s_addc_u32 s31, s79, s31
	s_or_b32 s11, s9, 4
	s_max_i32 s14, s11, s7
	v_lshl_add_u32 v127, s11, 10, v88
	s_ashr_i32 s11, s14, 31
	s_add_u32 s34, s0, s14
	s_addc_u32 s35, s1, s11
	s_lshl_b64 s[34:35], s[34:35], 9
	s_add_u32 s34, s78, s34
	s_addc_u32 s35, s79, s35
	s_or_b32 s11, s9, 5
	s_max_i32 s14, s11, s7
	v_lshl_add_u32 v128, s11, 10, v88
	s_ashr_i32 s11, s14, 31
	s_add_u32 s36, s0, s14
	s_addc_u32 s37, s1, s11
	s_lshl_b64 s[36:37], s[36:37], 9
	s_add_u32 s36, s78, s36
	s_addc_u32 s37, s79, s37
	s_add_u32 s98, s98, 0x200
	s_addc_u32 s99, s99, 0
	global_load_ushort v219, v33, s[98:99]
	s_add_u32 s98, s98, 0x200
	s_addc_u32 s99, s99, 0
	global_load_ushort v220, v33, s[98:99]
	s_add_u32 s98, s98, 0x200
	s_addc_u32 s99, s99, 0
	global_load_ushort v221, v33, s[98:99]
	s_add_u32 s98, s98, 0x200
	s_addc_u32 s99, s99, 0
	global_load_ushort v222, v33, s[98:99]
	s_add_u32 s98, s98, 0x200
	s_addc_u32 s99, s99, 0
	global_load_ushort v223, v33, s[98:99]
	s_add_u32 s98, s98, 0x200
	s_addc_u32 s99, s99, 0
	global_load_ushort v224, v33, s[98:99]
	s_add_u32 s98, s98, 0x200
	s_addc_u32 s99, s99, 0
	global_load_ushort v225, v33, s[98:99]
	s_add_u32 s98, s98, 0x200
	s_addc_u32 s99, s99, 0
	global_load_ushort v226, v33, s[98:99]
	s_add_u32 s98, s98, 0x200
	s_addc_u32 s99, s99, 0
	global_load_ushort v227, v33, s[98:99]
	s_add_u32 s98, s98, 0x200
	s_addc_u32 s99, s99, 0
	global_load_ushort v228, v33, s[98:99]
	global_load_ushort v229, v33, s[98:99]
	global_load_ushort v230, v33, s[98:99]
	s_waitcnt vmcnt(12)
; __device__ __forceinline__ void conv_item(int l, int it, LAS unsigned char* lds, const bf16_t* CGB, bf16_t* YC, const float* conv_w, const float* conv_b,
;                                           const float* conv_ln_g, const float* conv_ln_b, int tid, int lane, int wave) {
;     ...
;                 for (int j = 0; j < 12; ++j) if (ib + j < 46) x[ib + j] = (pos0 + tp - 30 + ib + j >= 0) ? __uint_as_float(raw[j] << 16) : 0.f;
;             }
; #pragma unroll
;             for (int t = 0; t < 16; ++t) {
;                 float acc = bias;
; #pragma unroll
;                 for (int j = 0; j < 31; ++j) acc += wd[j] * x[t + j];
	v_mov_b32_e32 v129, v231
	v_mov_b32_e32 v130, v232
	v_mov_b32_e32 v131, v233
	v_mov_b32_e32 v132, v236
	v_mov_b32_e32 v133, v237
	v_mov_b32_e32 v149, v238
	v_mov_b32_e32 v150, v239
	v_mov_b32_e32 v151, v240
	v_mov_b32_e32 v152, v245
	v_mov_b32_e32 v153, v246
	v_mov_b32_e32 v154, v247
	v_mov_b32_e32 v155, v248
	s_cmp_gt_i32 s10, 5
	v_lshlrev_b32_e32 v129, 16, v129
	s_cselect_b64 vcc, -1, 0
	s_cmp_gt_i32 s10, 4
	v_lshlrev_b32_e32 v130, 16, v130
	v_cndmask_b32_e32 v129, 0, v129, vcc
	s_cselect_b64 vcc, -1, 0
	s_cmp_gt_i32 s10, 3
	v_lshlrev_b32_e32 v131, 16, v131
	v_cndmask_b32_e32 v130, 0, v130, vcc
	s_cselect_b64 vcc, -1, 0
	s_cmp_gt_i32 s10, 2
	v_lshlrev_b32_e32 v132, 16, v132
	v_cndmask_b32_e32 v131, 0, v131, vcc
	s_cselect_b64 vcc, -1, 0
	s_cmp_gt_i32 s10, 1
	v_lshlrev_b32_e32 v133, 16, v133
	v_fmac_f32_e32 v108, v99, v129
	v_fmac_f32_e32 v109, v98, v129
	v_fmac_f32_e32 v110, v97, v129
	v_fmac_f32_e32 v111, v96, v129
	v_fmac_f32_e32 v112, v95, v129
	v_fmac_f32_e32 v113, v94, v129
	v_fmac_f32_e32 v114, v93, v129
	v_fmac_f32_e32 v115, v92, v129
	v_fmac_f32_e32 v116, v91, v129
	v_fmac_f32_e32 v117, v90, v129
	v_fmac_f32_e32 v118, v87, v129
	v_fmac_f32_e32 v119, v86, v129
	v_fmac_f32_e32 v121, v35, v129
	v_fmac_f32_e32 v120, v11, v129
	v_fmac_f32_e32 v122, v10, v129
	v_fmac_f32_e32 v123, v9, v129
	v_cndmask_b32_e32 v129, 0, v132, vcc
	s_cselect_b64 vcc, -1, 0
	s_cmp_gt_i32 s10, 0
	v_lshlrev_b32_e32 v149, 16, v149
	v_fmac_f32_e32 v108, v100, v130
	v_fmac_f32_e32 v109, v99, v130
	v_fmac_f32_e32 v110, v98, v130
	v_fmac_f32_e32 v111, v97, v130
	v_fmac_f32_e32 v112, v96, v130
	v_fmac_f32_e32 v113, v95, v130
	v_fmac_f32_e32 v114, v94, v130
	v_fmac_f32_e32 v115, v93, v130
	v_fmac_f32_e32 v116, v92, v130
	v_fmac_f32_e32 v117, v91, v130
	v_fmac_f32_e32 v118, v90, v130
	v_fmac_f32_e32 v119, v87, v130
	v_fmac_f32_e32 v121, v86, v130
	v_fmac_f32_e32 v120, v35, v130
	v_fmac_f32_e32 v122, v11, v130
	v_fmac_f32_e32 v123, v10, v130
	v_cndmask_b32_e32 v130, 0, v133, vcc
	s_cselect_b64 vcc, -1, 0
	s_cmp_gt_i32 s10, -1
	v_lshlrev_b32_e32 v150, 16, v150
	v_fmac_f32_e32 v108, v101, v131
	v_fmac_f32_e32 v109, v100, v131
	v_fmac_f32_e32 v110, v99, v131
	v_fmac_f32_e32 v111, v98, v131
	v_fmac_f32_e32 v112, v97, v131
	v_fmac_f32_e32 v113, v96, v131
	v_fmac_f32_e32 v114, v95, v131
	v_fmac_f32_e32 v115, v94, v131
	v_fmac_f32_e32 v116, v93, v131
	v_fmac_f32_e32 v117, v92, v131
	v_fmac_f32_e32 v118, v91, v131
	v_fmac_f32_e32 v119, v90, v131
	v_fmac_f32_e32 v121, v87, v131
	v_fmac_f32_e32 v120, v86, v131
	v_fmac_f32_e32 v122, v35, v131
	v_fmac_f32_e32 v123, v11, v131
	v_cndmask_b32_e32 v131, 0, v149, vcc
	s_cselect_b64 vcc, -1, 0
	s_cmp_gt_i32 s10, -2
	v_lshlrev_b32_e32 v151, 16, v151
	v_fmac_f32_e32 v108, v102, v129
	v_fmac_f32_e32 v109, v101, v129
	v_fmac_f32_e32 v110, v100, v129
	v_fmac_f32_e32 v111, v99, v129
	v_fmac_f32_e32 v112, v98, v129
	v_fmac_f32_e32 v113, v97, v129
	v_fmac_f32_e32 v114, v96, v129
	v_fmac_f32_e32 v115, v95, v129
	v_fmac_f32_e32 v116, v94, v129
	v_fmac_f32_e32 v117, v93, v129
	v_fmac_f32_e32 v118, v92, v129
	v_fmac_f32_e32 v119, v91, v129
	v_fmac_f32_e32 v121, v90, v129
	v_fmac_f32_e32 v120, v87, v129
	v_fmac_f32_e32 v122, v86, v129
	v_fmac_f32_e32 v123, v35, v129
	v_cndmask_b32_e32 v129, 0, v150, vcc
	s_cselect_b64 vcc, -1, 0
	s_cmp_gt_i32 s10, -3
	v_lshlrev_b32_e32 v152, 16, v152
	v_fmac_f32_e32 v108, v103, v130
	v_fmac_f32_e32 v109, v102, v130
	v_fmac_f32_e32 v110, v101, v130
	v_fmac_f32_e32 v111, v100, v130
	v_fmac_f32_e32 v112, v99, v130
	v_fmac_f32_e32 v113, v98, v130
	v_fmac_f32_e32 v114, v97, v130
	v_fmac_f32_e32 v115, v96, v130
	v_fmac_f32_e32 v116, v95, v130
	v_fmac_f32_e32 v117, v94, v130
	v_fmac_f32_e32 v118, v93, v130
	v_fmac_f32_e32 v119, v92, v130
	v_fmac_f32_e32 v121, v91, v130
	v_fmac_f32_e32 v120, v90, v130
	v_fmac_f32_e32 v122, v87, v130
	v_fmac_f32_e32 v123, v86, v130
	v_cndmask_b32_e32 v130, 0, v151, vcc
	s_cselect_b64 vcc, -1, 0
	s_cmp_gt_i32 s10, -4
	v_lshlrev_b32_e32 v153, 16, v153
	v_fmac_f32_e32 v108, v104, v131
	v_fmac_f32_e32 v109, v103, v131
	v_fmac_f32_e32 v110, v102, v131
	v_fmac_f32_e32 v111, v101, v131
	v_fmac_f32_e32 v112, v100, v131
	v_fmac_f32_e32 v113, v99, v131
	v_fmac_f32_e32 v114, v98, v131
	v_fmac_f32_e32 v115, v97, v131
	v_fmac_f32_e32 v116, v96, v131
	v_fmac_f32_e32 v117, v95, v131
	v_fmac_f32_e32 v118, v94, v131
	v_fmac_f32_e32 v119, v93, v131
	v_fmac_f32_e32 v121, v92, v131
	v_fmac_f32_e32 v120, v91, v131
	v_fmac_f32_e32 v122, v90, v131
	v_fmac_f32_e32 v123, v87, v131
	v_cndmask_b32_e32 v131, 0, v152, vcc
	s_cselect_b64 vcc, -1, 0
	s_cmp_gt_i32 s10, -5
	v_lshlrev_b32_e32 v154, 16, v154
	v_fmac_f32_e32 v108, v105, v129
	v_fmac_f32_e32 v109, v104, v129
	v_fmac_f32_e32 v110, v103, v129
	v_fmac_f32_e32 v111, v102, v129
	v_fmac_f32_e32 v112, v101, v129
	v_fmac_f32_e32 v113, v100, v129
	v_fmac_f32_e32 v114, v99, v129
	v_fmac_f32_e32 v115, v98, v129
	v_fmac_f32_e32 v116, v97, v129
	v_fmac_f32_e32 v117, v96, v129
	v_fmac_f32_e32 v118, v95, v129
	v_fmac_f32_e32 v119, v94, v129
	v_fmac_f32_e32 v121, v93, v129
	v_fmac_f32_e32 v120, v92, v129
	v_fmac_f32_e32 v122, v91, v129
	v_fmac_f32_e32 v123, v90, v129
	v_cndmask_b32_e32 v129, 0, v153, vcc
	s_cselect_b64 vcc, -1, 0
	s_cmp_gt_i32 s10, -6
	v_fmac_f32_e32 v109, v105, v130
	v_fmac_f32_e32 v110, v104, v130
	v_fmac_f32_e32 v111, v103, v130
	v_fmac_f32_e32 v112, v102, v130
	v_fmac_f32_e32 v113, v101, v130
	v_fmac_f32_e32 v114, v100, v130
	v_fmac_f32_e32 v115, v99, v130
	v_fmac_f32_e32 v116, v98, v130
	v_fmac_f32_e32 v117, v97, v130
	v_fmac_f32_e32 v118, v96, v130
	v_fmac_f32_e32 v119, v95, v130
	v_fmac_f32_e32 v121, v94, v130
	v_fmac_f32_e32 v120, v93, v130
; __device__ __forceinline__ void conv_item(int l, int it, LAS unsigned char* lds, const bf16_t* CGB, bf16_t* YC, const float* conv_w, const float* conv_b,
;                                           const float* conv_ln_g, const float* conv_ln_b, int tid, int lane, int wave) {
;     ...
;                 for (int j = 0; j < 12; ++j) { const int off = tp - 30 + (ib + j < 46 ? ib + j : 45); pp[j] = CGB + (r0 + (pos0 + off >= 0 ? off : -pos0)) * BW; }
;                 ld_u16_s12(raw, (unsigned)c * 2u, pp);
; #pragma unroll
;                 for (int j = 0; j < 12; ++j) if (ib + j < 46) x[ib + j] = (pos0 + tp - 30 + ib + j >= 0) ? __uint_as_float(raw[j] << 16) : 0.f;
;             }
; #pragma unroll
;             for (int t = 0; t < 16; ++t) {
;                 float acc = bias;
; #pragma unroll
;                 for (int j = 0; j < 31; ++j) acc += wd[j] * x[t + j];
	v_fmac_f32_e32 v122, v92, v130
	v_fmac_f32_e32 v123, v91, v130
	v_cndmask_b32_e32 v130, 0, v154, vcc
	s_cselect_b64 vcc, -1, 0
	s_or_b32 s4, s9, 6
	s_max_i32 s5, s4, s7
	v_fmac_f32_e32 v111, v104, v131
	v_fmac_f32_e32 v112, v103, v131
	v_fmac_f32_e32 v113, v102, v131
	v_fmac_f32_e32 v114, v101, v131
	v_fmac_f32_e32 v115, v100, v131
	v_fmac_f32_e32 v116, v99, v131
	v_fmac_f32_e32 v117, v98, v131
	v_fmac_f32_e32 v118, v97, v131
	v_fmac_f32_e32 v119, v96, v131
	v_fmac_f32_e32 v121, v95, v131
	v_fmac_f32_e32 v120, v94, v131
	v_fmac_f32_e32 v122, v93, v131
	v_fmac_f32_e32 v123, v92, v131
	s_ashr_i32 s11, s5, 31
	v_fmac_f32_e32 v111, v105, v129
	v_fmac_f32_e32 v112, v104, v129
	v_fmac_f32_e32 v113, v103, v129
	v_fmac_f32_e32 v114, v102, v129
	v_fmac_f32_e32 v115, v101, v129
	v_fmac_f32_e32 v116, v100, v129
	v_fmac_f32_e32 v117, v99, v129
	v_fmac_f32_e32 v118, v98, v129
	v_fmac_f32_e32 v119, v97, v129
	v_fmac_f32_e32 v121, v96, v129
	v_fmac_f32_e32 v120, v95, v129
	v_fmac_f32_e32 v122, v94, v129
	v_fmac_f32_e32 v123, v93, v129
	v_lshl_add_u32 v129, s4, 10, v88
	s_add_u32 s4, s0, s5
	s_addc_u32 s5, s1, s11
	s_lshl_b64 s[4:5], s[4:5], 9
	s_add_u32 s4, s78, s4
	s_addc_u32 s5, s79, s5
	s_or_b32 s11, s9, 7
	s_max_i32 s12, s11, s7
	v_fmac_f32_e32 v112, v105, v130
	v_fmac_f32_e32 v113, v104, v130
	v_fmac_f32_e32 v114, v103, v130
	v_fmac_f32_e32 v115, v102, v130
	v_fmac_f32_e32 v116, v101, v130
	v_fmac_f32_e32 v117, v100, v130
	v_fmac_f32_e32 v118, v99, v130
	v_fmac_f32_e32 v119, v98, v130
	v_fmac_f32_e32 v121, v97, v130
	v_fmac_f32_e32 v120, v96, v130
	v_fmac_f32_e32 v122, v95, v130
	v_fmac_f32_e32 v123, v94, v130
	v_lshl_add_u32 v130, s11, 10, v88
	s_ashr_i32 s11, s12, 31
	s_add_u32 s12, s0, s12
	s_addc_u32 s13, s1, s11
	s_lshl_b64 s[12:13], s[12:13], 9
	s_add_u32 s12, s78, s12
	v_lshlrev_b32_e32 v155, 16, v155
	s_addc_u32 s13, s79, s13
	s_or_b32 s11, s9, 8
	v_fmac_f32_e32 v110, v105, v131
	v_cndmask_b32_e32 v131, 0, v155, vcc
	s_max_i32 s14, s11, s7
	v_fmac_f32_e32 v113, v105, v131
	v_fmac_f32_e32 v114, v104, v131
	v_fmac_f32_e32 v115, v103, v131
	v_fmac_f32_e32 v116, v102, v131
	v_fmac_f32_e32 v117, v101, v131
	v_fmac_f32_e32 v118, v100, v131
	v_fmac_f32_e32 v119, v99, v131
	v_fmac_f32_e32 v121, v98, v131
	v_fmac_f32_e32 v120, v97, v131
	v_fmac_f32_e32 v122, v96, v131
	v_fmac_f32_e32 v123, v95, v131
	v_lshl_add_u32 v131, s11, 10, v88
	s_ashr_i32 s11, s14, 31
	s_add_u32 s16, s0, s14
	s_addc_u32 s17, s1, s11
	s_lshl_b64 s[16:17], s[16:17], 9
	s_add_u32 s16, s78, s16
	s_addc_u32 s17, s79, s17
	s_or_b32 s11, s9, 9
	s_max_i32 s14, s11, s7
	v_lshl_add_u32 v132, s11, 10, v88
	s_ashr_i32 s11, s14, 31
	s_add_u32 s18, s0, s14
	s_addc_u32 s19, s1, s11
	s_lshl_b64 s[18:19], s[18:19], 9
	s_add_u32 s18, s78, s18
	s_addc_u32 s19, s79, s19
	s_or_b32 s11, s9, 10
	s_max_i32 s14, s11, s7
	v_lshl_add_u32 v133, s11, 10, v88
	s_ashr_i32 s11, s14, 31
	s_add_u32 s20, s0, s14
	s_addc_u32 s21, s1, s11
	s_lshl_b64 s[20:21], s[20:21], 9
	s_add_u32 s20, s78, s20
	s_addc_u32 s21, s79, s21
	s_or_b32 s11, s9, 11
	s_max_i32 s14, s11, s7
	v_lshl_add_u32 v149, s11, 10, v88
	s_ashr_i32 s11, s14, 31
	s_add_u32 s22, s0, s14
	s_addc_u32 s23, s1, s11
	s_lshl_b64 s[22:23], s[22:23], 9
	s_add_u32 s22, s78, s22
	s_addc_u32 s23, s79, s23
	s_or_b32 s11, s9, 12
	s_max_i32 s14, s11, s7
	v_lshl_add_u32 v150, s11, 10, v88
	s_ashr_i32 s11, s14, 31
	s_add_u32 s24, s0, s14
	s_addc_u32 s25, s1, s11
	s_lshl_b64 s[24:25], s[24:25], 9
	s_add_u32 s24, s78, s24
	s_addc_u32 s25, s79, s25
	s_or_b32 s11, s9, 13
	s_max_i32 s14, s11, s7
	v_lshl_add_u32 v151, s11, 10, v88
	s_ashr_i32 s11, s14, 31
	s_add_u32 s26, s0, s14
	s_addc_u32 s27, s1, s11
	s_lshl_b64 s[26:27], s[26:27], 9
	s_add_u32 s26, s78, s26
	s_addc_u32 s27, s79, s27
	s_or_b32 s11, s9, 14
	s_max_i32 s14, s11, s7
	v_lshl_add_u32 v152, s11, 10, v88
	s_ashr_i32 s11, s14, 31
	s_add_u32 s28, s0, s14
	s_addc_u32 s29, s1, s11
	s_lshl_b64 s[28:29], s[28:29], 9
	s_add_u32 s28, s78, s28
	v_lshl_add_u32 v107, s9, 10, v88
	s_addc_u32 s29, s79, s29
	s_or_b32 s9, s9, 15
	s_max_i32 s11, s9, s7
	v_lshl_add_u32 v153, s9, 10, v88
	s_ashr_i32 s9, s11, 31
	s_add_u32 s30, s0, s11
	s_addc_u32 s31, s1, s9
	s_lshl_b64 s[30:31], s[30:31], 9
	s_add_u32 s30, s78, s30
	s_addc_u32 s31, s79, s31
	s_cmp_gt_i32 s10, -7
	s_waitcnt vmcnt(0)
; #define LAS __attribute__((address_space(3)))
; __device__ __forceinline__ unsigned cvt_pk_bf16(float lo, float hi) { unsigned r; asm volatile("v_cvt_pk_bf16_f32 %0, %1, %2" : "=v"(r) : "v"(lo), "v"(hi)); return r; }
; __device__ __forceinline__ float silu_f(float x) { return x * sigmoid_f(x); }
; __device__ __forceinline__ float ln_eps_s() { float e = LN_EPS; asm volatile("" : "+s"(e)); return e; }
; __device__ __forceinline__ void conv_item(int l, int it, LAS unsigned char* lds, const bf16_t* CGB, bf16_t* YC, const float* conv_w, const float* conv_b,
;                                           const float* conv_ln_g, const float* conv_ln_b, int tid, int lane, int wave) {
;     ...
;             for (int t = 0; t < 16; ++t) {
;                 float acc = bias;
; #pragma unroll
;                 for (int j = 0; j < 31; ++j) acc += wd[j] * x[t + j];
;                 cv[(tp + t) * BW + c] = acc;
;     ...
;     {
;         const f32x4 gg = *(const f32x4*)(conv_ln_g + l * BW + lane * 4), bb = *(const f32x4*)(conv_ln_b + l * BW + lane * 4);
;         for (int i = 0; i < 8; ++i) {
;             const int row = wave * 8 + i;
;             f32x4 v = *(const LAS f32x4*)(cv + row * BW + lane * 4);
;             const float mean = wave_sum((v.x + v.y) + (v.z + v.w)) * (1.f / BW);
;             v = v - mean;
;             const float rstd = __builtin_amdgcn_rsqf(wave_sum((v.x * v.x + v.y * v.y) + (v.z * v.z + v.w * v.w)) * (1.f / BW) + ln_eps_s());
;             const f32x4 y = v * rstd * gg + bb;
;             u32x2 w; w.x = cvt_pk_bf16(silu_f(y.x), silu_f(y.y)); w.y = cvt_pk_bf16(silu_f(y.z), silu_f(y.w));
;             *(u32x2*)(YC + (size_t)3 * MTOK * BW + (r0 + row) * BW + lane * 4) = w;
	v_mov_b32_e32 v154, v219
	v_mov_b32_e32 v155, v220
	v_mov_b32_e32 v157, v221
	v_mov_b32_e32 v161, v222
	v_mov_b32_e32 v162, v223
	v_mov_b32_e32 v163, v224
	v_mov_b32_e32 v164, v225
	v_mov_b32_e32 v165, v226
	v_mov_b32_e32 v166, v227
	v_mov_b32_e32 v167, v228
	v_mov_b32_e32 v168, v229
	v_mov_b32_e32 v169, v230
	ds_write_b32 v107, v108
	ds_write_b32 v124, v109
	ds_write_b32 v125, v110
	ds_write_b32 v126, v111
	ds_write_b32 v127, v112
	ds_write_b32 v128, v113
	v_lshlrev_b32_e32 v107, 16, v154
	s_cselect_b64 vcc, -1, 0
	s_cmp_gt_i32 s10, -8
	v_lshlrev_b32_e32 v108, 16, v155
	v_cndmask_b32_e32 v107, 0, v107, vcc
	s_cselect_b64 vcc, -1, 0
	s_cmp_gt_i32 s10, -9
	v_lshlrev_b32_e32 v109, 16, v157
	v_cndmask_b32_e32 v108, 0, v108, vcc
	s_cselect_b64 vcc, -1, 0
	s_cmp_gt_i32 s10, -10
	v_fmac_f32_e32 v123, v96, v107
	v_lshlrev_b32_e32 v110, 16, v161
	v_cndmask_b32_e32 v109, 0, v109, vcc
	v_fmac_f32_e32 v122, v97, v107
	s_cselect_b64 vcc, -1, 0
	s_cmp_gt_i32 s10, -11
	v_fmac_f32_e32 v123, v97, v108
	v_lshlrev_b32_e32 v111, 16, v162
	v_fmac_f32_e32 v114, v105, v107
	v_fmac_f32_e32 v115, v104, v107
	v_fmac_f32_e32 v116, v103, v107
	v_fmac_f32_e32 v117, v102, v107
	v_fmac_f32_e32 v118, v101, v107
	v_fmac_f32_e32 v119, v100, v107
	v_fmac_f32_e32 v121, v99, v107
	v_fmac_f32_e32 v120, v98, v107
	v_cndmask_b32_e32 v107, 0, v110, vcc
	v_fmac_f32_e32 v122, v98, v108
	s_cselect_b64 vcc, -1, 0
	s_cmp_gt_i32 s10, -12
	v_fmac_f32_e32 v123, v98, v109
	v_lshlrev_b32_e32 v112, 16, v163
	v_fmac_f32_e32 v115, v105, v108
	v_fmac_f32_e32 v116, v104, v108
	v_fmac_f32_e32 v117, v103, v108
	v_fmac_f32_e32 v118, v102, v108
	v_fmac_f32_e32 v119, v101, v108
	v_fmac_f32_e32 v121, v100, v108
	v_fmac_f32_e32 v120, v99, v108
	v_cndmask_b32_e32 v108, 0, v111, vcc
	v_fmac_f32_e32 v122, v99, v109
	s_cselect_b64 vcc, -1, 0
	s_cmp_gt_i32 s10, -13
	v_fmac_f32_e32 v123, v99, v107
	v_lshlrev_b32_e32 v113, 16, v164
	v_fmac_f32_e32 v116, v105, v109
	v_fmac_f32_e32 v117, v104, v109
	v_fmac_f32_e32 v118, v103, v109
	v_fmac_f32_e32 v119, v102, v109
	v_fmac_f32_e32 v121, v101, v109
	v_fmac_f32_e32 v120, v100, v109
	v_cndmask_b32_e32 v109, 0, v112, vcc
	v_fmac_f32_e32 v122, v100, v107
	s_cselect_b64 vcc, -1, 0
	s_cmp_gt_i32 s10, -14
	v_fmac_f32_e32 v123, v100, v108
	v_lshlrev_b32_e32 v124, 16, v165
	v_fmac_f32_e32 v117, v105, v107
	v_fmac_f32_e32 v118, v104, v107
	v_fmac_f32_e32 v119, v103, v107
	v_fmac_f32_e32 v121, v102, v107
	v_fmac_f32_e32 v120, v101, v107
	v_cndmask_b32_e32 v107, 0, v113, vcc
	v_fmac_f32_e32 v122, v101, v108
	s_cselect_b64 vcc, -1, 0
	s_cmp_gt_i32 s10, -15
	v_fmac_f32_e32 v123, v101, v109
	v_lshlrev_b32_e32 v125, 16, v166
	v_fmac_f32_e32 v118, v105, v108
	v_fmac_f32_e32 v119, v104, v108
	v_fmac_f32_e32 v121, v103, v108
	v_fmac_f32_e32 v120, v102, v108
	v_cndmask_b32_e32 v108, 0, v124, vcc
	v_fmac_f32_e32 v122, v102, v109
	s_cselect_b64 vcc, -1, 0
	s_cmp_gt_i32 s10, -16
	v_fmac_f32_e32 v123, v102, v107
	v_lshlrev_b32_e32 v126, 16, v167
	v_fmac_f32_e32 v119, v105, v109
	v_fmac_f32_e32 v121, v104, v109
	v_fmac_f32_e32 v120, v103, v109
	v_cndmask_b32_e32 v109, 0, v125, vcc
	v_fmac_f32_e32 v122, v103, v107
	s_cselect_b64 vcc, -1, 0
	v_fmac_f32_e32 v123, v103, v108
	v_fmac_f32_e32 v121, v105, v107
	v_fmac_f32_e32 v120, v104, v107
	v_cndmask_b32_e32 v107, 0, v126, vcc
	v_fmac_f32_e32 v122, v104, v108
	v_fmac_f32_e32 v123, v104, v109
	s_mov_b32 s8, 16
	v_fmac_f32_e32 v120, v105, v108
	s_and_b64 vcc, exec, s[2:3]
	s_mov_b64 s[2:3], 0
	v_fmac_f32_e32 v122, v105, v109
	v_fmac_f32_e32 v123, v105, v107
	ds_write_b32 v129, v114
	ds_write_b32 v130, v115
	ds_write_b32 v131, v116
	ds_write_b32 v132, v117
	ds_write_b32 v133, v118
	ds_write_b32 v149, v119
	ds_write_b32 v150, v121
	ds_write_b32 v151, v120
	ds_write_b32 v152, v122
	ds_write_b32 v153, v123
	s_cbranch_vccnz .LBB0_102
	v_add_u32_e32 v0, s15, v89
	s_waitcnt lgkmcnt(0)
	s_barrier
	ds_read_b128 v[8:11], v0
	s_mov_b32 s2, 0x3727c5ac
	s_mov_b32 s4, 0x3727c5ac
	s_waitcnt lgkmcnt(0)
	v_mov_b32_e32 v0, v9
	v_mov_b32_e32 v1, v10
	v_mov_b32_e32 v2, v8
	v_mov_b32_e32 v3, v11
	v_pk_add_f32 v[0:1], v[0:1], v[2:3]
	s_nop 0
	v_add_f32_e32 v0, v0, v1
	ds_swizzle_b32 v1, v0 offset:swizzle(SWAP,1)
	s_waitcnt lgkmcnt(0)
	v_add_f32_e32 v35, v0, v1
	global_load_dwordx4 v[0:3], v[82:83], off
	global_load_dwordx4 v[4:7], v[84:85], off
	ds_swizzle_b32 v86, v35 offset:swizzle(SWAP,2)
	s_waitcnt lgkmcnt(0)
	v_add_f32_e32 v35, v35, v86
	ds_swizzle_b32 v86, v35 offset:swizzle(SWAP,4)
	s_waitcnt lgkmcnt(0)
	v_add_f32_e32 v35, v35, v86
	ds_swizzle_b32 v86, v35 offset:swizzle(SWAP,8)
	s_waitcnt lgkmcnt(0)
	v_add_f32_e32 v35, v35, v86
	ds_swizzle_b32 v86, v35 offset:swizzle(SWAP,16)
	s_waitcnt lgkmcnt(0)
	v_add_f32_e32 v35, v35, v86
	v_mov_b32_e32 v86, v35
	v_mov_b32_e32 v87, v35
	s_nop 1
	v_permlane32_swap_b32_e32 v86, v87
	v_add_u32_e32 v86, v86, v87
	v_sub_u32_e32 v86, v86, v35
	v_add_f32_e32 v35, v35, v86
	v_fmamk_f32 v9, v35, 0xbb800000, v9
	v_fmamk_f32 v8, v35, 0xbb800000, v8
	v_fmamk_f32 v11, v35, 0xbb800000, v11
	v_fmac_f32_e32 v10, 0xbb800000, v35
	v_pk_mul_f32 v[86:87], v[10:11], v[10:11]
	v_pk_mul_f32 v[90:91], v[8:9], v[8:9]
	s_nop 0
	v_pk_mov_b32 v[92:93], v[90:91], v[86:87] op_sel:[1,0]
	v_mov_b32_e32 v91, v87
	v_pk_add_f32 v[86:87], v[92:93], v[90:91]
	s_nop 0
	v_add_f32_e32 v35, v86, v87
	ds_swizzle_b32 v86, v35 offset:swizzle(SWAP,1)
	v_mov_b32_e32 v87, s2
	v_readlane_b32 s2, v253, 33
	s_add_u32 s2, s0, s2
	s_addc_u32 s3, s1, s56
	s_waitcnt lgkmcnt(0)
	v_add_f32_e32 v35, v35, v86
	ds_swizzle_b32 v86, v35 offset:swizzle(SWAP,2)
	s_lshl_b64 s[2:3], s[2:3], 9
	s_waitcnt lgkmcnt(0)
	v_add_f32_e32 v35, v35, v86
	ds_swizzle_b32 v86, v35 offset:swizzle(SWAP,4)
	s_waitcnt lgkmcnt(0)
; #define LAS __attribute__((address_space(3)))
; __device__ __forceinline__ unsigned cvt_pk_bf16(float lo, float hi) { unsigned r; asm volatile("v_cvt_pk_bf16_f32 %0, %1, %2" : "=v"(r) : "v"(lo), "v"(hi)); return r; }
; __device__ __forceinline__ float silu_f(float x) { return x * sigmoid_f(x); }
; __device__ __forceinline__ float ln_eps_s() { float e = LN_EPS; asm volatile("" : "+s"(e)); return e; }
; __device__ __forceinline__ void conv_item(int l, int it, LAS unsigned char* lds, const bf16_t* CGB, bf16_t* YC, const float* conv_w, const float* conv_b,
;                                           const float* conv_ln_g, const float* conv_ln_b, int tid, int lane, int wave) {
;     ...
;         for (int i = 0; i < 8; ++i) {
;             const int row = wave * 8 + i;
;             f32x4 v = *(const LAS f32x4*)(cv + row * BW + lane * 4);
;             const float mean = wave_sum((v.x + v.y) + (v.z + v.w)) * (1.f / BW);
;             v = v - mean;
;             const float rstd = __builtin_amdgcn_rsqf(wave_sum((v.x * v.x + v.y * v.y) + (v.z * v.z + v.w * v.w)) * (1.f / BW) + ln_eps_s());
;             const f32x4 y = v * rstd * gg + bb;
;             u32x2 w; w.x = cvt_pk_bf16(silu_f(y.x), silu_f(y.y)); w.y = cvt_pk_bf16(silu_f(y.z), silu_f(y.w));
;             *(u32x2*)(YC + (size_t)3 * MTOK * BW + (r0 + row) * BW + lane * 4) = w;
	v_add_f32_e32 v35, v35, v86
	ds_swizzle_b32 v86, v35 offset:swizzle(SWAP,8)
	s_waitcnt lgkmcnt(0)
	v_add_f32_e32 v35, v35, v86
	ds_swizzle_b32 v86, v35 offset:swizzle(SWAP,16)
	s_waitcnt lgkmcnt(0)
	v_add_f32_e32 v35, v35, v86
	v_mov_b32_e32 v86, v35
	v_mov_b32_e32 v90, v35
	s_nop 1
	v_permlane32_swap_b32_e32 v86, v90
	v_add_u32_e32 v86, v86, v90
	v_sub_u32_e32 v86, v86, v35
	v_add_f32_e32 v35, v35, v86
	v_fmac_f32_e32 v87, 0x3b800000, v35
	v_rsq_f32_e32 v86, v87
	v_add_u32_e32 v35, s58, v89
	v_pk_mul_f32 v[8:9], v[8:9], v[86:87] op_sel_hi:[1,0]
	v_pk_mul_f32 v[10:11], v[10:11], v[86:87] op_sel_hi:[1,0]
	s_waitcnt vmcnt(0)
	v_pk_fma_f32 v[8:9], v[0:1], v[8:9], v[4:5]
	v_pk_fma_f32 v[10:11], v[2:3], v[10:11], v[6:7]
	v_mul_f32_e32 v86, 0xbfb8aa3b, v8
	v_mul_f32_e32 v87, 0xbfb8aa3b, v9
	v_mul_f32_e32 v90, 0xbfb8aa3b, v10
	v_mul_f32_e32 v91, 0xbfb8aa3b, v11
	v_exp_f32_e32 v86, v86
	v_exp_f32_e32 v87, v87
	v_exp_f32_e32 v90, v90
	v_exp_f32_e32 v91, v91
	v_add_f32_e32 v86, 1.0, v86
	v_add_f32_e32 v87, 1.0, v87
	v_add_f32_e32 v90, 1.0, v90
	v_add_f32_e32 v91, 1.0, v91
	v_rcp_f32_e32 v86, v86
	v_rcp_f32_e32 v87, v87
	v_rcp_f32_e32 v90, v90
	v_rcp_f32_e32 v91, v91
	v_mul_f32_e32 v8, v8, v86
	v_mul_f32_e32 v9, v9, v87
	v_mul_f32_e32 v10, v10, v90
	v_mul_f32_e32 v11, v11, v91
	v_cvt_pk_bf16_f32 v86, v8, v9
	v_cvt_pk_bf16_f32 v87, v10, v11
	ds_read_b128 v[8:11], v35
	s_waitcnt lgkmcnt(0)
	v_mov_b32_e32 v90, v9
	v_mov_b32_e32 v91, v10
	v_mov_b32_e32 v92, v8
	v_mov_b32_e32 v93, v11
	v_pk_add_f32 v[90:91], v[90:91], v[92:93]
	s_nop 0
	v_add_f32_e32 v35, v90, v91
	ds_swizzle_b32 v90, v35 offset:swizzle(SWAP,1)
	s_waitcnt lgkmcnt(0)
	v_add_f32_e32 v35, v35, v90
	ds_swizzle_b32 v90, v35 offset:swizzle(SWAP,2)
	s_waitcnt lgkmcnt(0)
	v_add_f32_e32 v35, v35, v90
	ds_swizzle_b32 v90, v35 offset:swizzle(SWAP,4)
	s_waitcnt lgkmcnt(0)
	v_add_f32_e32 v35, v35, v90
	ds_swizzle_b32 v90, v35 offset:swizzle(SWAP,8)
	s_waitcnt lgkmcnt(0)
	v_add_f32_e32 v35, v35, v90
	ds_swizzle_b32 v90, v35 offset:swizzle(SWAP,16)
	s_waitcnt lgkmcnt(0)
	v_add_f32_e32 v35, v35, v90
	v_mov_b32_e32 v90, v35
	v_mov_b32_e32 v91, v35
	s_nop 1
	v_permlane32_swap_b32_e32 v90, v91
	v_add_u32_e32 v90, v90, v91
	v_sub_u32_e32 v90, v90, v35
	v_add_f32_e32 v35, v35, v90
	v_fmamk_f32 v9, v35, 0xbb800000, v9
	v_fmamk_f32 v8, v35, 0xbb800000, v8
	v_fmamk_f32 v11, v35, 0xbb800000, v11
	v_fmac_f32_e32 v10, 0xbb800000, v35
	v_pk_mul_f32 v[90:91], v[10:11], v[10:11]
	v_pk_mul_f32 v[92:93], v[8:9], v[8:9]
	s_nop 0
	v_pk_mov_b32 v[94:95], v[92:93], v[90:91] op_sel:[1,0]
	v_mov_b32_e32 v93, v91
	v_pk_add_f32 v[90:91], v[94:95], v[92:93]
	s_nop 0
	v_add_f32_e32 v35, v90, v91
	ds_swizzle_b32 v90, v35 offset:swizzle(SWAP,1)
	s_waitcnt lgkmcnt(0)
	v_add_f32_e32 v35, v35, v90
	ds_swizzle_b32 v90, v35 offset:swizzle(SWAP,2)
	s_waitcnt lgkmcnt(0)
	v_add_f32_e32 v35, v35, v90
	ds_swizzle_b32 v90, v35 offset:swizzle(SWAP,4)
	s_waitcnt lgkmcnt(0)
	v_add_f32_e32 v35, v35, v90
	ds_swizzle_b32 v90, v35 offset:swizzle(SWAP,8)
	s_waitcnt lgkmcnt(0)
	v_add_f32_e32 v35, v35, v90
	ds_swizzle_b32 v92, v35 offset:swizzle(SWAP,16)
	v_lshl_add_u64 v[90:91], v[12:13], 0, s[2:3]
	global_store_dwordx2 v[90:91], v[86:87], off
	s_add_u32 s2, s0, s57
	s_waitcnt lgkmcnt(0)
	v_add_f32_e32 v35, v35, v92
	v_mov_b32_e32 v87, v35
	v_mov_b32_e32 v90, v35
	s_nop 1
	v_permlane32_swap_b32_e32 v87, v90
	v_add_u32_e32 v87, v87, v90
	v_sub_u32_e32 v87, v87, v35
	v_mov_b32_e32 v86, s4
	v_add_f32_e32 v35, v35, v87
	v_fmac_f32_e32 v86, 0x3b800000, v35
	v_rsq_f32_e32 v86, v86
	v_add_u32_e32 v35, s61, v89
	s_addc_u32 s3, s1, s59
	s_lshl_b64 s[2:3], s[2:3], 9
	v_pk_mul_f32 v[8:9], v[8:9], v[86:87] op_sel_hi:[1,0]
	v_pk_mul_f32 v[10:11], v[10:11], v[86:87] op_sel_hi:[1,0]
	v_pk_fma_f32 v[8:9], v[0:1], v[8:9], v[4:5]
	v_pk_fma_f32 v[10:11], v[2:3], v[10:11], v[6:7]
	v_mul_f32_e32 v86, 0xbfb8aa3b, v8
	v_mul_f32_e32 v87, 0xbfb8aa3b, v9
	v_mul_f32_e32 v90, 0xbfb8aa3b, v10
	v_mul_f32_e32 v91, 0xbfb8aa3b, v11
	v_exp_f32_e32 v86, v86
	v_exp_f32_e32 v87, v87
	v_exp_f32_e32 v90, v90
	v_exp_f32_e32 v91, v91
	v_add_f32_e32 v86, 1.0, v86
	v_add_f32_e32 v87, 1.0, v87
	v_add_f32_e32 v90, 1.0, v90
	v_add_f32_e32 v91, 1.0, v91
	v_rcp_f32_e32 v86, v86
	v_rcp_f32_e32 v87, v87
	v_rcp_f32_e32 v90, v90
	v_rcp_f32_e32 v91, v91
	v_mul_f32_e32 v8, v8, v86
	v_mul_f32_e32 v9, v9, v87
	v_mul_f32_e32 v10, v10, v90
	v_mul_f32_e32 v11, v11, v91
	v_cvt_pk_bf16_f32 v86, v8, v9
	v_cvt_pk_bf16_f32 v87, v10, v11
	ds_read_b128 v[8:11], v35
	s_mov_b32 s4, 0x3727c5ac
	s_waitcnt lgkmcnt(0)
	v_mov_b32_e32 v90, v9
	v_mov_b32_e32 v91, v10
	v_mov_b32_e32 v92, v8
	v_mov_b32_e32 v93, v11
	v_pk_add_f32 v[90:91], v[90:91], v[92:93]
	s_nop 0
	v_add_f32_e32 v35, v90, v91
	ds_swizzle_b32 v90, v35 offset:swizzle(SWAP,1)
	s_waitcnt lgkmcnt(0)
	v_add_f32_e32 v35, v35, v90
	ds_swizzle_b32 v90, v35 offset:swizzle(SWAP,2)
	s_waitcnt lgkmcnt(0)
	v_add_f32_e32 v35, v35, v90
	ds_swizzle_b32 v90, v35 offset:swizzle(SWAP,4)
	s_waitcnt lgkmcnt(0)
	v_add_f32_e32 v35, v35, v90
	ds_swizzle_b32 v90, v35 offset:swizzle(SWAP,8)
	s_waitcnt lgkmcnt(0)
	v_add_f32_e32 v35, v35, v90
	ds_swizzle_b32 v90, v35 offset:swizzle(SWAP,16)
	s_waitcnt lgkmcnt(0)
	v_add_f32_e32 v35, v35, v90
	v_mov_b32_e32 v90, v35
	v_mov_b32_e32 v91, v35
	s_nop 1
	v_permlane32_swap_b32_e32 v90, v91
	v_add_u32_e32 v90, v90, v91
	v_sub_u32_e32 v90, v90, v35
	v_add_f32_e32 v35, v35, v90
	v_fmamk_f32 v9, v35, 0xbb800000, v9
	v_fmamk_f32 v8, v35, 0xbb800000, v8
	v_fmamk_f32 v11, v35, 0xbb800000, v11
	v_fmac_f32_e32 v10, 0xbb800000, v35
	v_pk_mul_f32 v[90:91], v[10:11], v[10:11]
	v_pk_mul_f32 v[92:93], v[8:9], v[8:9]
	s_nop 0
	v_pk_mov_b32 v[94:95], v[92:93], v[90:91] op_sel:[1,0]
	v_mov_b32_e32 v93, v91
	v_pk_add_f32 v[90:91], v[94:95], v[92:93]
	s_nop 0
	v_add_f32_e32 v35, v90, v91
	ds_swizzle_b32 v90, v35 offset:swizzle(SWAP,1)
	s_waitcnt lgkmcnt(0)
; #define LAS __attribute__((address_space(3)))
; __device__ __forceinline__ unsigned cvt_pk_bf16(float lo, float hi) { unsigned r; asm volatile("v_cvt_pk_bf16_f32 %0, %1, %2" : "=v"(r) : "v"(lo), "v"(hi)); return r; }
; __device__ __forceinline__ float silu_f(float x) { return x * sigmoid_f(x); }
; __device__ __forceinline__ float ln_eps_s() { float e = LN_EPS; asm volatile("" : "+s"(e)); return e; }
; __device__ __forceinline__ void conv_item(int l, int it, LAS unsigned char* lds, const bf16_t* CGB, bf16_t* YC, const float* conv_w, const float* conv_b,
;                                           const float* conv_ln_g, const float* conv_ln_b, int tid, int lane, int wave) {
;     ...
;         for (int i = 0; i < 8; ++i) {
;             const int row = wave * 8 + i;
;             f32x4 v = *(const LAS f32x4*)(cv + row * BW + lane * 4);
;             const float mean = wave_sum((v.x + v.y) + (v.z + v.w)) * (1.f / BW);
;             v = v - mean;
;             const float rstd = __builtin_amdgcn_rsqf(wave_sum((v.x * v.x + v.y * v.y) + (v.z * v.z + v.w * v.w)) * (1.f / BW) + ln_eps_s());
;             const f32x4 y = v * rstd * gg + bb;
;             u32x2 w; w.x = cvt_pk_bf16(silu_f(y.x), silu_f(y.y)); w.y = cvt_pk_bf16(silu_f(y.z), silu_f(y.w));
;             *(u32x2*)(YC + (size_t)3 * MTOK * BW + (r0 + row) * BW + lane * 4) = w;
	v_add_f32_e32 v35, v35, v90
	ds_swizzle_b32 v90, v35 offset:swizzle(SWAP,2)
	s_waitcnt lgkmcnt(0)
	v_add_f32_e32 v35, v35, v90
	ds_swizzle_b32 v90, v35 offset:swizzle(SWAP,4)
	s_waitcnt lgkmcnt(0)
	v_add_f32_e32 v35, v35, v90
	ds_swizzle_b32 v90, v35 offset:swizzle(SWAP,8)
	s_waitcnt lgkmcnt(0)
	v_add_f32_e32 v35, v35, v90
	ds_swizzle_b32 v92, v35 offset:swizzle(SWAP,16)
	v_lshl_add_u64 v[90:91], v[12:13], 0, s[2:3]
	global_store_dwordx2 v[90:91], v[86:87], off
	s_add_u32 s2, s0, s60
	s_waitcnt lgkmcnt(0)
	v_add_f32_e32 v35, v35, v92
	v_mov_b32_e32 v87, v35
	v_mov_b32_e32 v90, v35
	s_nop 1
	v_permlane32_swap_b32_e32 v87, v90
	v_add_u32_e32 v87, v87, v90
	v_sub_u32_e32 v87, v87, v35
	v_mov_b32_e32 v86, s4
	v_add_f32_e32 v35, v35, v87
	v_fmac_f32_e32 v86, 0x3b800000, v35
	v_rsq_f32_e32 v86, v86
	v_add_u32_e32 v35, s64, v89
	s_addc_u32 s3, s1, s62
	s_lshl_b64 s[2:3], s[2:3], 9
	v_pk_mul_f32 v[8:9], v[8:9], v[86:87] op_sel_hi:[1,0]
	v_pk_mul_f32 v[10:11], v[10:11], v[86:87] op_sel_hi:[1,0]
	v_pk_fma_f32 v[8:9], v[0:1], v[8:9], v[4:5]
	v_pk_fma_f32 v[10:11], v[2:3], v[10:11], v[6:7]
	v_mul_f32_e32 v86, 0xbfb8aa3b, v8
	v_mul_f32_e32 v87, 0xbfb8aa3b, v9
	v_mul_f32_e32 v90, 0xbfb8aa3b, v10
	v_mul_f32_e32 v91, 0xbfb8aa3b, v11
	v_exp_f32_e32 v86, v86
	v_exp_f32_e32 v87, v87
	v_exp_f32_e32 v90, v90
	v_exp_f32_e32 v91, v91
	v_add_f32_e32 v86, 1.0, v86
	v_add_f32_e32 v87, 1.0, v87
	v_add_f32_e32 v90, 1.0, v90
	v_add_f32_e32 v91, 1.0, v91
	v_rcp_f32_e32 v86, v86
	v_rcp_f32_e32 v87, v87
	v_rcp_f32_e32 v90, v90
	v_rcp_f32_e32 v91, v91
	v_mul_f32_e32 v8, v8, v86
	v_mul_f32_e32 v9, v9, v87
	v_mul_f32_e32 v10, v10, v90
	v_mul_f32_e32 v11, v11, v91
	v_cvt_pk_bf16_f32 v86, v8, v9
	v_cvt_pk_bf16_f32 v87, v10, v11
	ds_read_b128 v[8:11], v35
	s_mov_b32 s4, 0x3727c5ac
	s_waitcnt lgkmcnt(0)
	v_mov_b32_e32 v90, v9
	v_mov_b32_e32 v91, v10
	v_mov_b32_e32 v92, v8
	v_mov_b32_e32 v93, v11
	v_pk_add_f32 v[90:91], v[90:91], v[92:93]
	s_nop 0
	v_add_f32_e32 v35, v90, v91
	ds_swizzle_b32 v90, v35 offset:swizzle(SWAP,1)
	s_waitcnt lgkmcnt(0)
	v_add_f32_e32 v35, v35, v90
	ds_swizzle_b32 v90, v35 offset:swizzle(SWAP,2)
	s_waitcnt lgkmcnt(0)
	v_add_f32_e32 v35, v35, v90
	ds_swizzle_b32 v90, v35 offset:swizzle(SWAP,4)
	s_waitcnt lgkmcnt(0)
	v_add_f32_e32 v35, v35, v90
	ds_swizzle_b32 v90, v35 offset:swizzle(SWAP,8)
	s_waitcnt lgkmcnt(0)
	v_add_f32_e32 v35, v35, v90
	ds_swizzle_b32 v90, v35 offset:swizzle(SWAP,16)
	s_waitcnt lgkmcnt(0)
	v_add_f32_e32 v35, v35, v90
	v_mov_b32_e32 v90, v35
	v_mov_b32_e32 v91, v35
	s_nop 1
	v_permlane32_swap_b32_e32 v90, v91
	v_add_u32_e32 v90, v90, v91
	v_sub_u32_e32 v90, v90, v35
	v_add_f32_e32 v35, v35, v90
	v_fmamk_f32 v9, v35, 0xbb800000, v9
	v_fmamk_f32 v8, v35, 0xbb800000, v8
	v_fmamk_f32 v11, v35, 0xbb800000, v11
	v_fmac_f32_e32 v10, 0xbb800000, v35
	v_pk_mul_f32 v[90:91], v[10:11], v[10:11]
	v_pk_mul_f32 v[92:93], v[8:9], v[8:9]
	s_nop 0
	v_pk_mov_b32 v[94:95], v[92:93], v[90:91] op_sel:[1,0]
	v_mov_b32_e32 v93, v91
	v_pk_add_f32 v[90:91], v[94:95], v[92:93]
	s_nop 0
	v_add_f32_e32 v35, v90, v91
	ds_swizzle_b32 v90, v35 offset:swizzle(SWAP,1)
	s_waitcnt lgkmcnt(0)
	v_add_f32_e32 v35, v35, v90
	ds_swizzle_b32 v90, v35 offset:swizzle(SWAP,2)
	s_waitcnt lgkmcnt(0)
	v_add_f32_e32 v35, v35, v90
	ds_swizzle_b32 v90, v35 offset:swizzle(SWAP,4)
	s_waitcnt lgkmcnt(0)
	v_add_f32_e32 v35, v35, v90
	ds_swizzle_b32 v90, v35 offset:swizzle(SWAP,8)
	s_waitcnt lgkmcnt(0)
	v_add_f32_e32 v35, v35, v90
	ds_swizzle_b32 v92, v35 offset:swizzle(SWAP,16)
	v_lshl_add_u64 v[90:91], v[12:13], 0, s[2:3]
	global_store_dwordx2 v[90:91], v[86:87], off
	s_add_u32 s2, s0, s63
	s_waitcnt lgkmcnt(0)
	v_add_f32_e32 v35, v35, v92
	v_mov_b32_e32 v87, v35
	v_mov_b32_e32 v90, v35
	s_nop 1
	v_permlane32_swap_b32_e32 v87, v90
	v_add_u32_e32 v87, v87, v90
	v_sub_u32_e32 v87, v87, v35
	v_mov_b32_e32 v86, s4
	v_add_f32_e32 v35, v35, v87
	v_fmac_f32_e32 v86, 0x3b800000, v35
	v_rsq_f32_e32 v86, v86
	v_add_u32_e32 v35, s67, v89
	s_addc_u32 s3, s1, s65
	s_lshl_b64 s[2:3], s[2:3], 9
	v_pk_mul_f32 v[8:9], v[8:9], v[86:87] op_sel_hi:[1,0]
	v_pk_mul_f32 v[10:11], v[10:11], v[86:87] op_sel_hi:[1,0]
	v_pk_fma_f32 v[8:9], v[0:1], v[8:9], v[4:5]
	v_pk_fma_f32 v[10:11], v[2:3], v[10:11], v[6:7]
	v_mul_f32_e32 v86, 0xbfb8aa3b, v8
	v_mul_f32_e32 v87, 0xbfb8aa3b, v9
	v_mul_f32_e32 v90, 0xbfb8aa3b, v10
	v_mul_f32_e32 v91, 0xbfb8aa3b, v11
	v_exp_f32_e32 v86, v86
	v_exp_f32_e32 v87, v87
	v_exp_f32_e32 v90, v90
	v_exp_f32_e32 v91, v91
	v_add_f32_e32 v86, 1.0, v86
	v_add_f32_e32 v87, 1.0, v87
	v_add_f32_e32 v90, 1.0, v90
	v_add_f32_e32 v91, 1.0, v91
	v_rcp_f32_e32 v86, v86
	v_rcp_f32_e32 v87, v87
	v_rcp_f32_e32 v90, v90
	v_rcp_f32_e32 v91, v91
	v_mul_f32_e32 v8, v8, v86
	v_mul_f32_e32 v9, v9, v87
	v_mul_f32_e32 v10, v10, v90
	v_mul_f32_e32 v11, v11, v91
	v_cvt_pk_bf16_f32 v86, v8, v9
	v_cvt_pk_bf16_f32 v87, v10, v11
	ds_read_b128 v[8:11], v35
	s_mov_b32 s4, 0x3727c5ac
	s_waitcnt lgkmcnt(0)
	v_mov_b32_e32 v90, v9
	v_mov_b32_e32 v91, v10
	v_mov_b32_e32 v92, v8
	v_mov_b32_e32 v93, v11
	v_pk_add_f32 v[90:91], v[90:91], v[92:93]
	s_nop 0
	v_add_f32_e32 v35, v90, v91
	ds_swizzle_b32 v90, v35 offset:swizzle(SWAP,1)
	s_waitcnt lgkmcnt(0)
	v_add_f32_e32 v35, v35, v90
	ds_swizzle_b32 v90, v35 offset:swizzle(SWAP,2)
	s_waitcnt lgkmcnt(0)
	v_add_f32_e32 v35, v35, v90
	ds_swizzle_b32 v90, v35 offset:swizzle(SWAP,4)
	s_waitcnt lgkmcnt(0)
	v_add_f32_e32 v35, v35, v90
	ds_swizzle_b32 v90, v35 offset:swizzle(SWAP,8)
	s_waitcnt lgkmcnt(0)
	v_add_f32_e32 v35, v35, v90
	ds_swizzle_b32 v90, v35 offset:swizzle(SWAP,16)
	s_waitcnt lgkmcnt(0)
; #define LAS __attribute__((address_space(3)))
; __device__ __forceinline__ unsigned cvt_pk_bf16(float lo, float hi) { unsigned r; asm volatile("v_cvt_pk_bf16_f32 %0, %1, %2" : "=v"(r) : "v"(lo), "v"(hi)); return r; }
; __device__ __forceinline__ float silu_f(float x) { return x * sigmoid_f(x); }
; __device__ __forceinline__ float ln_eps_s() { float e = LN_EPS; asm volatile("" : "+s"(e)); return e; }
; __device__ __forceinline__ void conv_item(int l, int it, LAS unsigned char* lds, const bf16_t* CGB, bf16_t* YC, const float* conv_w, const float* conv_b,
;                                           const float* conv_ln_g, const float* conv_ln_b, int tid, int lane, int wave) {
;     ...
;         for (int i = 0; i < 8; ++i) {
;             const int row = wave * 8 + i;
;             f32x4 v = *(const LAS f32x4*)(cv + row * BW + lane * 4);
;             const float mean = wave_sum((v.x + v.y) + (v.z + v.w)) * (1.f / BW);
;             v = v - mean;
;             const float rstd = __builtin_amdgcn_rsqf(wave_sum((v.x * v.x + v.y * v.y) + (v.z * v.z + v.w * v.w)) * (1.f / BW) + ln_eps_s());
;             const f32x4 y = v * rstd * gg + bb;
;             u32x2 w; w.x = cvt_pk_bf16(silu_f(y.x), silu_f(y.y)); w.y = cvt_pk_bf16(silu_f(y.z), silu_f(y.w));
;             *(u32x2*)(YC + (size_t)3 * MTOK * BW + (r0 + row) * BW + lane * 4) = w;
	v_add_f32_e32 v35, v35, v90
	v_mov_b32_e32 v90, v35
	v_mov_b32_e32 v91, v35
	s_nop 1
	v_permlane32_swap_b32_e32 v90, v91
	v_add_u32_e32 v90, v90, v91
	v_sub_u32_e32 v90, v90, v35
	v_add_f32_e32 v35, v35, v90
	v_fmamk_f32 v9, v35, 0xbb800000, v9
	v_fmamk_f32 v8, v35, 0xbb800000, v8
	v_fmamk_f32 v11, v35, 0xbb800000, v11
	v_fmac_f32_e32 v10, 0xbb800000, v35
	v_pk_mul_f32 v[90:91], v[10:11], v[10:11]
	v_pk_mul_f32 v[92:93], v[8:9], v[8:9]
	s_nop 0
	v_pk_mov_b32 v[94:95], v[92:93], v[90:91] op_sel:[1,0]
	v_mov_b32_e32 v93, v91
	v_pk_add_f32 v[90:91], v[94:95], v[92:93]
	s_nop 0
	v_add_f32_e32 v35, v90, v91
	ds_swizzle_b32 v90, v35 offset:swizzle(SWAP,1)
	s_waitcnt lgkmcnt(0)
	v_add_f32_e32 v35, v35, v90
	ds_swizzle_b32 v90, v35 offset:swizzle(SWAP,2)
	s_waitcnt lgkmcnt(0)
	v_add_f32_e32 v35, v35, v90
	ds_swizzle_b32 v90, v35 offset:swizzle(SWAP,4)
	s_waitcnt lgkmcnt(0)
	v_add_f32_e32 v35, v35, v90
	ds_swizzle_b32 v90, v35 offset:swizzle(SWAP,8)
	s_waitcnt lgkmcnt(0)
	v_add_f32_e32 v35, v35, v90
	ds_swizzle_b32 v92, v35 offset:swizzle(SWAP,16)
	v_lshl_add_u64 v[90:91], v[12:13], 0, s[2:3]
	global_store_dwordx2 v[90:91], v[86:87], off
	s_add_u32 s2, s0, s66
	s_waitcnt lgkmcnt(0)
	v_add_f32_e32 v35, v35, v92
	v_mov_b32_e32 v87, v35
	v_mov_b32_e32 v90, v35
	s_nop 1
	v_permlane32_swap_b32_e32 v87, v90
	v_add_u32_e32 v87, v87, v90
	v_sub_u32_e32 v87, v87, v35
	v_mov_b32_e32 v86, s4
	v_add_f32_e32 v35, v35, v87
	v_fmac_f32_e32 v86, 0x3b800000, v35
	v_rsq_f32_e32 v86, v86
	v_add_u32_e32 v35, s70, v89
	s_addc_u32 s3, s1, s68
	s_lshl_b64 s[2:3], s[2:3], 9
	v_pk_mul_f32 v[8:9], v[8:9], v[86:87] op_sel_hi:[1,0]
	v_pk_mul_f32 v[10:11], v[10:11], v[86:87] op_sel_hi:[1,0]
	v_pk_fma_f32 v[8:9], v[0:1], v[8:9], v[4:5]
	v_pk_fma_f32 v[10:11], v[2:3], v[10:11], v[6:7]
	v_mul_f32_e32 v86, 0xbfb8aa3b, v8
	v_mul_f32_e32 v87, 0xbfb8aa3b, v9
	v_mul_f32_e32 v90, 0xbfb8aa3b, v10
	v_mul_f32_e32 v91, 0xbfb8aa3b, v11
	v_exp_f32_e32 v86, v86
	v_exp_f32_e32 v87, v87
	v_exp_f32_e32 v90, v90
	v_exp_f32_e32 v91, v91
	v_add_f32_e32 v86, 1.0, v86
	v_add_f32_e32 v87, 1.0, v87
	v_add_f32_e32 v90, 1.0, v90
	v_add_f32_e32 v91, 1.0, v91
	v_rcp_f32_e32 v86, v86
	v_rcp_f32_e32 v87, v87
	v_rcp_f32_e32 v90, v90
	v_rcp_f32_e32 v91, v91
	v_mul_f32_e32 v8, v8, v86
	v_mul_f32_e32 v9, v9, v87
	v_mul_f32_e32 v10, v10, v90
	v_mul_f32_e32 v11, v11, v91
	v_cvt_pk_bf16_f32 v86, v8, v9
	v_cvt_pk_bf16_f32 v87, v10, v11
	ds_read_b128 v[8:11], v35
	s_mov_b32 s4, 0x3727c5ac
	s_waitcnt lgkmcnt(0)
	v_mov_b32_e32 v90, v9
	v_mov_b32_e32 v91, v10
	v_mov_b32_e32 v92, v8
	v_mov_b32_e32 v93, v11
	v_pk_add_f32 v[90:91], v[90:91], v[92:93]
	s_nop 0
	v_add_f32_e32 v35, v90, v91
	ds_swizzle_b32 v90, v35 offset:swizzle(SWAP,1)
	s_waitcnt lgkmcnt(0)
	v_add_f32_e32 v35, v35, v90
	ds_swizzle_b32 v90, v35 offset:swizzle(SWAP,2)
	s_waitcnt lgkmcnt(0)
	v_add_f32_e32 v35, v35, v90
	ds_swizzle_b32 v90, v35 offset:swizzle(SWAP,4)
	s_waitcnt lgkmcnt(0)
	v_add_f32_e32 v35, v35, v90
	ds_swizzle_b32 v90, v35 offset:swizzle(SWAP,8)
	s_waitcnt lgkmcnt(0)
	v_add_f32_e32 v35, v35, v90
	ds_swizzle_b32 v90, v35 offset:swizzle(SWAP,16)
	s_waitcnt lgkmcnt(0)
	v_add_f32_e32 v35, v35, v90
	v_mov_b32_e32 v90, v35
	v_mov_b32_e32 v91, v35
	s_nop 1
	v_permlane32_swap_b32_e32 v90, v91
	v_add_u32_e32 v90, v90, v91
	v_sub_u32_e32 v90, v90, v35
	v_add_f32_e32 v35, v35, v90
	v_fmamk_f32 v9, v35, 0xbb800000, v9
	v_fmamk_f32 v8, v35, 0xbb800000, v8
	v_fmamk_f32 v11, v35, 0xbb800000, v11
	v_fmac_f32_e32 v10, 0xbb800000, v35
	v_pk_mul_f32 v[90:91], v[10:11], v[10:11]
	v_pk_mul_f32 v[92:93], v[8:9], v[8:9]
	s_nop 0
	v_pk_mov_b32 v[94:95], v[92:93], v[90:91] op_sel:[1,0]
	v_mov_b32_e32 v93, v91
	v_pk_add_f32 v[90:91], v[94:95], v[92:93]
	s_nop 0
	v_add_f32_e32 v35, v90, v91
	ds_swizzle_b32 v90, v35 offset:swizzle(SWAP,1)
	s_waitcnt lgkmcnt(0)
	v_add_f32_e32 v35, v35, v90
	ds_swizzle_b32 v90, v35 offset:swizzle(SWAP,2)
	s_waitcnt lgkmcnt(0)
	v_add_f32_e32 v35, v35, v90
	ds_swizzle_b32 v90, v35 offset:swizzle(SWAP,4)
	s_waitcnt lgkmcnt(0)
	v_add_f32_e32 v35, v35, v90
	ds_swizzle_b32 v90, v35 offset:swizzle(SWAP,8)
	s_waitcnt lgkmcnt(0)
	v_add_f32_e32 v35, v35, v90
	ds_swizzle_b32 v92, v35 offset:swizzle(SWAP,16)
	v_lshl_add_u64 v[90:91], v[12:13], 0, s[2:3]
	global_store_dwordx2 v[90:91], v[86:87], off
	s_add_u32 s2, s0, s69
	s_waitcnt lgkmcnt(0)
	v_add_f32_e32 v35, v35, v92
	v_mov_b32_e32 v87, v35
	v_mov_b32_e32 v90, v35
	s_nop 1
	v_permlane32_swap_b32_e32 v87, v90
	v_add_u32_e32 v87, v87, v90
	v_sub_u32_e32 v87, v87, v35
	v_mov_b32_e32 v86, s4
	v_add_f32_e32 v35, v35, v87
	v_fmac_f32_e32 v86, 0x3b800000, v35
	v_rsq_f32_e32 v86, v86
	v_add_u32_e32 v35, s73, v89
	s_addc_u32 s3, s1, s71
	s_lshl_b64 s[2:3], s[2:3], 9
	v_pk_mul_f32 v[8:9], v[8:9], v[86:87] op_sel_hi:[1,0]
	v_pk_mul_f32 v[10:11], v[10:11], v[86:87] op_sel_hi:[1,0]
	v_pk_fma_f32 v[8:9], v[0:1], v[8:9], v[4:5]
	v_pk_fma_f32 v[10:11], v[2:3], v[10:11], v[6:7]
	v_mul_f32_e32 v86, 0xbfb8aa3b, v8
	v_mul_f32_e32 v87, 0xbfb8aa3b, v9
	v_mul_f32_e32 v90, 0xbfb8aa3b, v10
	v_mul_f32_e32 v91, 0xbfb8aa3b, v11
	v_exp_f32_e32 v86, v86
	v_exp_f32_e32 v87, v87
	v_exp_f32_e32 v90, v90
	v_exp_f32_e32 v91, v91
	v_add_f32_e32 v86, 1.0, v86
	v_add_f32_e32 v87, 1.0, v87
	v_add_f32_e32 v90, 1.0, v90
	v_add_f32_e32 v91, 1.0, v91
	v_rcp_f32_e32 v86, v86
	v_rcp_f32_e32 v87, v87
	v_rcp_f32_e32 v90, v90
	v_rcp_f32_e32 v91, v91
	v_mul_f32_e32 v8, v8, v86
	v_mul_f32_e32 v9, v9, v87
	v_mul_f32_e32 v10, v10, v90
	v_mul_f32_e32 v11, v11, v91
	v_cvt_pk_bf16_f32 v86, v8, v9
	v_cvt_pk_bf16_f32 v87, v10, v11
	ds_read_b128 v[8:11], v35
	s_mov_b32 s4, 0x3727c5ac
	s_waitcnt lgkmcnt(0)
; #define LAS __attribute__((address_space(3)))
; __device__ __forceinline__ unsigned cvt_pk_bf16(float lo, float hi) { unsigned r; asm volatile("v_cvt_pk_bf16_f32 %0, %1, %2" : "=v"(r) : "v"(lo), "v"(hi)); return r; }
; __device__ __forceinline__ float silu_f(float x) { return x * sigmoid_f(x); }
; __device__ __forceinline__ float ln_eps_s() { float e = LN_EPS; asm volatile("" : "+s"(e)); return e; }
; __device__ __forceinline__ void conv_item(int l, int it, LAS unsigned char* lds, const bf16_t* CGB, bf16_t* YC, const float* conv_w, const float* conv_b,
;                                           const float* conv_ln_g, const float* conv_ln_b, int tid, int lane, int wave) {
;     ...
;         for (int i = 0; i < 8; ++i) {
;             const int row = wave * 8 + i;
;             f32x4 v = *(const LAS f32x4*)(cv + row * BW + lane * 4);
;             const float mean = wave_sum((v.x + v.y) + (v.z + v.w)) * (1.f / BW);
;             v = v - mean;
;             const float rstd = __builtin_amdgcn_rsqf(wave_sum((v.x * v.x + v.y * v.y) + (v.z * v.z + v.w * v.w)) * (1.f / BW) + ln_eps_s());
;             const f32x4 y = v * rstd * gg + bb;
;             u32x2 w; w.x = cvt_pk_bf16(silu_f(y.x), silu_f(y.y)); w.y = cvt_pk_bf16(silu_f(y.z), silu_f(y.w));
;             *(u32x2*)(YC + (size_t)3 * MTOK * BW + (r0 + row) * BW + lane * 4) = w;
;         }
;     }
;     __syncthreads();
	v_mov_b32_e32 v90, v9
	v_mov_b32_e32 v91, v10
	v_mov_b32_e32 v92, v8
	v_mov_b32_e32 v93, v11
	v_pk_add_f32 v[90:91], v[90:91], v[92:93]
	s_nop 0
	v_add_f32_e32 v35, v90, v91
	ds_swizzle_b32 v90, v35 offset:swizzle(SWAP,1)
	s_waitcnt lgkmcnt(0)
	v_add_f32_e32 v35, v35, v90
	ds_swizzle_b32 v90, v35 offset:swizzle(SWAP,2)
	s_waitcnt lgkmcnt(0)
	v_add_f32_e32 v35, v35, v90
	ds_swizzle_b32 v90, v35 offset:swizzle(SWAP,4)
	s_waitcnt lgkmcnt(0)
	v_add_f32_e32 v35, v35, v90
	ds_swizzle_b32 v90, v35 offset:swizzle(SWAP,8)
	s_waitcnt lgkmcnt(0)
	v_add_f32_e32 v35, v35, v90
	ds_swizzle_b32 v90, v35 offset:swizzle(SWAP,16)
	s_waitcnt lgkmcnt(0)
	v_add_f32_e32 v35, v35, v90
	v_mov_b32_e32 v90, v35
	v_mov_b32_e32 v91, v35
	s_nop 1
	v_permlane32_swap_b32_e32 v90, v91
	v_add_u32_e32 v90, v90, v91
	v_sub_u32_e32 v90, v90, v35
	v_add_f32_e32 v35, v35, v90
	v_fmamk_f32 v9, v35, 0xbb800000, v9
	v_fmamk_f32 v8, v35, 0xbb800000, v8
	v_fmamk_f32 v11, v35, 0xbb800000, v11
	v_fmac_f32_e32 v10, 0xbb800000, v35
	v_pk_mul_f32 v[90:91], v[10:11], v[10:11]
	v_pk_mul_f32 v[92:93], v[8:9], v[8:9]
	s_nop 0
	v_pk_mov_b32 v[94:95], v[92:93], v[90:91] op_sel:[1,0]
	v_mov_b32_e32 v93, v91
	v_pk_add_f32 v[90:91], v[94:95], v[92:93]
	s_nop 0
	v_add_f32_e32 v35, v90, v91
	ds_swizzle_b32 v90, v35 offset:swizzle(SWAP,1)
	s_waitcnt lgkmcnt(0)
	v_add_f32_e32 v35, v35, v90
	ds_swizzle_b32 v90, v35 offset:swizzle(SWAP,2)
	s_waitcnt lgkmcnt(0)
	v_add_f32_e32 v35, v35, v90
	ds_swizzle_b32 v90, v35 offset:swizzle(SWAP,4)
	s_waitcnt lgkmcnt(0)
	v_add_f32_e32 v35, v35, v90
	ds_swizzle_b32 v90, v35 offset:swizzle(SWAP,8)
	s_waitcnt lgkmcnt(0)
	v_add_f32_e32 v35, v35, v90
	ds_swizzle_b32 v92, v35 offset:swizzle(SWAP,16)
	v_lshl_add_u64 v[90:91], v[12:13], 0, s[2:3]
	global_store_dwordx2 v[90:91], v[86:87], off
	s_add_u32 s2, s0, s72
	s_waitcnt lgkmcnt(0)
	v_add_f32_e32 v35, v35, v92
	v_mov_b32_e32 v87, v35
	v_mov_b32_e32 v90, v35
	s_nop 1
	v_permlane32_swap_b32_e32 v87, v90
	v_add_u32_e32 v87, v87, v90
	v_sub_u32_e32 v87, v87, v35
	v_mov_b32_e32 v86, s4
	v_add_f32_e32 v35, v35, v87
	v_fmac_f32_e32 v86, 0x3b800000, v35
	v_rsq_f32_e32 v86, v86
	v_add_u32_e32 v35, s76, v89
	s_addc_u32 s3, s1, s74
	s_lshl_b64 s[2:3], s[2:3], 9
	v_pk_mul_f32 v[8:9], v[8:9], v[86:87] op_sel_hi:[1,0]
	v_pk_mul_f32 v[10:11], v[10:11], v[86:87] op_sel_hi:[1,0]
	v_pk_fma_f32 v[8:9], v[0:1], v[8:9], v[4:5]
	v_pk_fma_f32 v[10:11], v[2:3], v[10:11], v[6:7]
	v_mul_f32_e32 v86, 0xbfb8aa3b, v8
	v_mul_f32_e32 v87, 0xbfb8aa3b, v9
	v_mul_f32_e32 v90, 0xbfb8aa3b, v10
	v_mul_f32_e32 v91, 0xbfb8aa3b, v11
	v_exp_f32_e32 v86, v86
	v_exp_f32_e32 v87, v87
	v_exp_f32_e32 v90, v90
	v_exp_f32_e32 v91, v91
	v_add_f32_e32 v86, 1.0, v86
	v_add_f32_e32 v87, 1.0, v87
	v_add_f32_e32 v90, 1.0, v90
	v_add_f32_e32 v91, 1.0, v91
	v_rcp_f32_e32 v86, v86
	v_rcp_f32_e32 v87, v87
	v_rcp_f32_e32 v90, v90
	v_rcp_f32_e32 v91, v91
	v_mul_f32_e32 v8, v8, v86
	v_mul_f32_e32 v9, v9, v87
	v_mul_f32_e32 v10, v10, v90
	v_mul_f32_e32 v11, v11, v91
	v_cvt_pk_bf16_f32 v86, v8, v9
	v_cvt_pk_bf16_f32 v87, v10, v11
	ds_read_b128 v[8:11], v35
	s_mov_b32 s4, 0x3727c5ac
	s_add_u32 s0, s0, s75
	s_addc_u32 s1, s1, s77
	s_add_i32 s40, s40, s96
	s_waitcnt lgkmcnt(0)
	v_mov_b32_e32 v90, v9
	v_mov_b32_e32 v91, v10
	v_mov_b32_e32 v92, v8
	v_mov_b32_e32 v93, v11
	v_pk_add_f32 v[90:91], v[90:91], v[92:93]
	s_lshl_b64 s[0:1], s[0:1], 9
	v_add_f32_e32 v35, v90, v91
	ds_swizzle_b32 v90, v35 offset:swizzle(SWAP,1)
	s_cmpk_gt_i32 s40, 0x1ff
	s_waitcnt lgkmcnt(0)
	v_add_f32_e32 v35, v35, v90
	ds_swizzle_b32 v90, v35 offset:swizzle(SWAP,2)
	s_waitcnt lgkmcnt(0)
	v_add_f32_e32 v35, v35, v90
	ds_swizzle_b32 v90, v35 offset:swizzle(SWAP,4)
	s_waitcnt lgkmcnt(0)
	v_add_f32_e32 v35, v35, v90
	ds_swizzle_b32 v90, v35 offset:swizzle(SWAP,8)
	s_waitcnt lgkmcnt(0)
	v_add_f32_e32 v35, v35, v90
	ds_swizzle_b32 v90, v35 offset:swizzle(SWAP,16)
	s_waitcnt lgkmcnt(0)
	v_add_f32_e32 v35, v35, v90
	v_mov_b32_e32 v90, v35
	v_mov_b32_e32 v91, v35
	s_nop 1
	v_permlane32_swap_b32_e32 v90, v91
	v_add_u32_e32 v90, v90, v91
	v_sub_u32_e32 v90, v90, v35
	v_add_f32_e32 v35, v35, v90
	v_fmamk_f32 v9, v35, 0xbb800000, v9
	v_fmamk_f32 v8, v35, 0xbb800000, v8
	v_fmamk_f32 v11, v35, 0xbb800000, v11
	v_fmac_f32_e32 v10, 0xbb800000, v35
	v_pk_mul_f32 v[90:91], v[10:11], v[10:11]
	v_pk_mul_f32 v[92:93], v[8:9], v[8:9]
	s_nop 0
	v_pk_mov_b32 v[94:95], v[92:93], v[90:91] op_sel:[1,0]
	v_mov_b32_e32 v93, v91
	v_pk_add_f32 v[90:91], v[94:95], v[92:93]
	s_nop 0
	v_add_f32_e32 v35, v90, v91
	ds_swizzle_b32 v90, v35 offset:swizzle(SWAP,1)
	s_waitcnt lgkmcnt(0)
	v_add_f32_e32 v35, v35, v90
	ds_swizzle_b32 v90, v35 offset:swizzle(SWAP,2)
	s_waitcnt lgkmcnt(0)
	v_add_f32_e32 v35, v35, v90
	ds_swizzle_b32 v90, v35 offset:swizzle(SWAP,4)
	s_waitcnt lgkmcnt(0)
	v_add_f32_e32 v35, v35, v90
	ds_swizzle_b32 v92, v35 offset:swizzle(SWAP,8)
	v_lshl_add_u64 v[90:91], v[12:13], 0, s[2:3]
	global_store_dwordx2 v[90:91], v[86:87], off
	s_waitcnt lgkmcnt(0)
	v_add_f32_e32 v35, v35, v92
	ds_swizzle_b32 v92, v35 offset:swizzle(SWAP,16)
	v_mov_b32_e32 v86, s4
	s_waitcnt lgkmcnt(0)
	v_add_f32_e32 v35, v35, v92
	v_mov_b32_e32 v87, v35
	v_mov_b32_e32 v90, v35
	s_nop 1
	v_permlane32_swap_b32_e32 v87, v90
	v_add_u32_e32 v87, v87, v90
	v_sub_u32_e32 v87, v87, v35
	v_add_f32_e32 v35, v35, v87
	v_fmac_f32_e32 v86, 0x3b800000, v35
	v_rsq_f32_e32 v86, v86
	v_lshl_add_u64 v[90:91], v[12:13], 0, s[0:1]
	v_pk_mul_f32 v[8:9], v[8:9], v[86:87] op_sel_hi:[1,0]
	v_pk_mul_f32 v[10:11], v[10:11], v[86:87] op_sel_hi:[1,0]
	v_pk_fma_f32 v[0:1], v[0:1], v[8:9], v[4:5]
	v_pk_fma_f32 v[2:3], v[2:3], v[10:11], v[6:7]
	v_mul_f32_e32 v4, 0xbfb8aa3b, v0
	v_mul_f32_e32 v5, 0xbfb8aa3b, v1
	v_mul_f32_e32 v6, 0xbfb8aa3b, v2
	v_mul_f32_e32 v7, 0xbfb8aa3b, v3
	v_exp_f32_e32 v4, v4
	v_exp_f32_e32 v5, v5
	v_exp_f32_e32 v6, v6
	v_exp_f32_e32 v7, v7
	v_add_f32_e32 v4, 1.0, v4
	v_add_f32_e32 v5, 1.0, v5
	v_add_f32_e32 v6, 1.0, v6
	v_add_f32_e32 v7, 1.0, v7
	v_rcp_f32_e32 v4, v4
	v_rcp_f32_e32 v5, v5
	v_rcp_f32_e32 v6, v6
	v_rcp_f32_e32 v7, v7
	v_mul_f32_e32 v0, v0, v4
	v_mul_f32_e32 v1, v1, v5
	v_mul_f32_e32 v2, v2, v6
	v_mul_f32_e32 v3, v3, v7
	v_cvt_pk_bf16_f32 v0, v0, v1
	v_cvt_pk_bf16_f32 v1, v2, v3
	global_store_dwordx2 v[90:91], v[0:1], off
	s_barrier
	s_cbranch_scc0 .LBB0_101
